# gather_u: 4 lanes per pick fetching 48 B with three aligned dwordx4 (24 row loads per token-slice instead of 32), x slice staged through LDS, quad-level DPP reduction
# speedup vs baseline: 1.1684x; 1.0018x over previous
.Lgu0_start:
	s_mov_b64 exec, -1
	v_and_b32_e32 v0, 63, v205
	v_lshrrev_b32_e32 v1, 6, v205
	v_lshlrev_b32_e32 v193, 2, v0
	v_readfirstlane_b32 s68, v1
	v_and_b32_e32 v1, 3, v0
	v_lshlrev_b32_e32 v196, 4, v1
	v_mul_u32_u24_e32 v197, 48, v1
	s_nop 3
	s_lshl_b32 s17, s68, 14
	s_add_i32 s69, s93, s68
	v_and_b32_e32 v1, 3, v0
	v_lshlrev_b32_e32 v195, 4, v1
	v_lshrrev_b32_e32 v1, 2, v0
	v_add_u32_e32 v195, v195, v1
	v_lshl_add_u32 v195, v195, 2, s17
	v_lshrrev_b32_e32 v1, 2, v0
	v_lshl_add_u32 v194, v1, 2, s17
	v_add_u32_e32 v194, 0x2000, v194
	v_lshl_add_u32 v198, v0, 4, s17
	v_add_u32_e32 v200, s17, v193
	v_add_u32_e32 v199, 0x2000, v200
	v_lshrrev_b32_e32 v114, 3, v0
	v_lshlrev_b32_e32 v114, 8, v114
	v_and_b32_e32 v1, 7, v0
	v_lshl_add_u32 v114, v1, 3, v114
	s_lshl_b32 s18, s68, 9
	s_add_u32 s18, s18, 0x10000
	v_lshl_add_u32 v115, v0, 3, s18
	v_and_b32_e32 v1, 3, v0
	v_lshl_add_u32 v116, v1, 4, s18
.Lgu0_chunk:
	s_movk_i32 s64, 0xc0
	s_lshl_b32 s65, s92, 13
	s_mov_b32 s70, 0x11111111
	s_mov_b32 s71, 0x11111111
	s_mov_b32 s14, 0x22222222
	s_mov_b32 s15, 0x22222222
	s_mov_b32 s100, 0x44444444
	s_mov_b32 s101, 0x44444444
	s_mov_b32 s98, 0x88888888
	s_mov_b32 s99, 0x88888888
	s_add_u32 s10, s26, 0xd800000
	s_addc_u32 s11, s27, 0
	s_lshl_b32 s17, s69, 9
	s_add_u32 s10, s10, s17
	s_addc_u32 s11, s11, 0
	s_lshl_b32 s18, s92, 11
	global_load_dword v16, v193, s[10:11]
	global_load_dword v17, v193, s[10:11] offset:256
	s_add_u32 s10, s10, s18
	s_addc_u32 s11, s11, 0
	global_load_dword v18, v193, s[10:11]
	global_load_dword v19, v193, s[10:11] offset:256
	s_add_u32 s10, s10, s18
	s_addc_u32 s11, s11, 0
	global_load_dword v20, v193, s[10:11]
	global_load_dword v21, v193, s[10:11] offset:256
	s_add_u32 s10, s10, s18
	s_addc_u32 s11, s11, 0
	global_load_dword v22, v193, s[10:11]
	global_load_dword v23, v193, s[10:11] offset:256
	s_add_u32 s10, s10, s18
	s_addc_u32 s11, s11, 0
	global_load_dword v24, v193, s[10:11]
	global_load_dword v25, v193, s[10:11] offset:256
	s_add_u32 s10, s10, s18
	s_addc_u32 s11, s11, 0
	global_load_dword v26, v193, s[10:11]
	global_load_dword v27, v193, s[10:11] offset:256
	s_add_u32 s10, s10, s18
	s_addc_u32 s11, s11, 0
	global_load_dword v28, v193, s[10:11]
	global_load_dword v29, v193, s[10:11] offset:256
	s_add_u32 s10, s10, s18
	s_addc_u32 s11, s11, 0
	global_load_dword v30, v193, s[10:11]
	global_load_dword v31, v193, s[10:11] offset:256
	s_add_u32 s10, s10, s18
	s_addc_u32 s11, s11, 0
	global_load_dword v32, v193, s[10:11]
	global_load_dword v33, v193, s[10:11] offset:256
	s_add_u32 s10, s10, s18
	s_addc_u32 s11, s11, 0
	global_load_dword v34, v193, s[10:11]
	global_load_dword v35, v193, s[10:11] offset:256
	s_add_u32 s10, s10, s18
	s_addc_u32 s11, s11, 0
	global_load_dword v36, v193, s[10:11]
	global_load_dword v37, v193, s[10:11] offset:256
	s_add_u32 s10, s10, s18
	s_addc_u32 s11, s11, 0
	global_load_dword v38, v193, s[10:11]
	global_load_dword v39, v193, s[10:11] offset:256
	s_add_u32 s10, s10, s18
	s_addc_u32 s11, s11, 0
	global_load_dword v40, v193, s[10:11]
	global_load_dword v41, v193, s[10:11] offset:256
	s_add_u32 s10, s10, s18
	s_addc_u32 s11, s11, 0
	global_load_dword v42, v193, s[10:11]
	global_load_dword v43, v193, s[10:11] offset:256
	s_add_u32 s10, s10, s18
	s_addc_u32 s11, s11, 0
	global_load_dword v44, v193, s[10:11]
	global_load_dword v45, v193, s[10:11] offset:256
	s_add_u32 s10, s10, s18
	s_addc_u32 s11, s11, 0
	global_load_dword v46, v193, s[10:11]
	global_load_dword v47, v193, s[10:11] offset:256
	s_add_u32 s10, s10, s18
	s_addc_u32 s11, s11, 0
	v_mov_b32_e32 v0, 0
	v_mov_b32_e32 v1, 0
	v_mov_b32_e32 v2, 0
	v_mov_b32_e32 v3, 0
	ds_write_b128 v198, v[0:3] offset:0
	ds_write_b128 v198, v[0:3] offset:1024
	ds_write_b128 v198, v[0:3] offset:2048
	ds_write_b128 v198, v[0:3] offset:3072
	ds_write_b128 v198, v[0:3] offset:4096
	ds_write_b128 v198, v[0:3] offset:5120
	ds_write_b128 v198, v[0:3] offset:6144
	ds_write_b128 v198, v[0:3] offset:7168
	s_waitcnt vmcnt(0)
	ds_write2st64_b32 v199, v16, v17 offset0:0 offset1:1
	ds_write2st64_b32 v199, v18, v19 offset0:2 offset1:3
	ds_write2st64_b32 v199, v20, v21 offset0:4 offset1:5
	ds_write2st64_b32 v199, v22, v23 offset0:6 offset1:7
	ds_write2st64_b32 v199, v24, v25 offset0:8 offset1:9
	ds_write2st64_b32 v199, v26, v27 offset0:10 offset1:11
	ds_write2st64_b32 v199, v28, v29 offset0:12 offset1:13
	ds_write2st64_b32 v199, v30, v31 offset0:14 offset1:15
	ds_write2st64_b32 v199, v32, v33 offset0:16 offset1:17
	ds_write2st64_b32 v199, v34, v35 offset0:18 offset1:19
	ds_write2st64_b32 v199, v36, v37 offset0:20 offset1:21
	ds_write2st64_b32 v199, v38, v39 offset0:22 offset1:23
	ds_write2st64_b32 v199, v40, v41 offset0:24 offset1:25
	ds_write2st64_b32 v199, v42, v43 offset0:26 offset1:27
	ds_write2st64_b32 v199, v44, v45 offset0:28 offset1:29
	ds_write2st64_b32 v199, v46, v47 offset0:30 offset1:31
	s_waitcnt lgkmcnt(0)
	s_add_u32 s4, s26, 0x1800000
	s_addc_u32 s5, s27, 0
	s_add_u32 s8, s26, 0x5800000
	s_addc_u32 s9, s27, 0
	s_lshl_b32 s17, s69, 11
	s_add_u32 s8, s8, s17
	s_addc_u32 s9, s9, 0
	s_mov_b32 s16, 0
	s_and_b32 s19, s16, 15
	s_lshr_b32 s50, s16, 4
	s_lshl_b32 s51, s19, 9
	s_mul_i32 s17, s19, s65
	s_lshl_b32 s18, s50, 6
	s_add_u32 s17, s17, s18
	s_add_u32 s10, s8, s17
	s_addc_u32 s11, s9, 0
	s_mul_i32 s17, s50, 0x300000
	s_add_u32 s4, s26, 0x1800000
	s_addc_u32 s5, s27, 0
	s_add_u32 s4, s4, s17
	s_addc_u32 s5, s5, 0
	v_add_u32_e32 v201, s51, v194
	ds_read2_b32 v[184:185], v201 offset0:0 offset1:16
	ds_read2_b32 v[186:187], v201 offset0:32 offset1:48
	ds_read2_b32 v[188:189], v201 offset0:64 offset1:80
	ds_read2_b32 v[190:191], v201 offset0:96 offset1:112
	global_load_dwordx2 v[112:113], v114, s[10:11]
	s_waitcnt lgkmcnt(0)
	v_mad_u32_u24 v184, v184, s64, v197
	v_mad_u32_u24 v185, v185, s64, v197
	global_load_dwordx4 v[16:19], v184, s[4:5]
	global_load_dwordx4 v[20:23], v184, s[4:5] offset:16
	global_load_dwordx4 v[24:27], v184, s[4:5] offset:32
	global_load_dwordx4 v[28:31], v185, s[4:5]
	global_load_dwordx4 v[32:35], v185, s[4:5] offset:16
	global_load_dwordx4 v[36:39], v185, s[4:5] offset:32
	v_mad_u32_u24 v186, v186, s64, v197
	v_mad_u32_u24 v187, v187, s64, v197
	global_load_dwordx4 v[40:43], v186, s[4:5]
	global_load_dwordx4 v[44:47], v186, s[4:5] offset:16
	global_load_dwordx4 v[48:51], v186, s[4:5] offset:32
	global_load_dwordx4 v[52:55], v187, s[4:5]
	global_load_dwordx4 v[56:59], v187, s[4:5] offset:16
	global_load_dwordx4 v[60:63], v187, s[4:5] offset:32
	v_mad_u32_u24 v188, v188, s64, v197
	v_mad_u32_u24 v189, v189, s64, v197
	global_load_dwordx4 v[64:67], v188, s[4:5]
	global_load_dwordx4 v[68:71], v188, s[4:5] offset:16
	global_load_dwordx4 v[72:75], v188, s[4:5] offset:32
	global_load_dwordx4 v[76:79], v189, s[4:5]
	global_load_dwordx4 v[80:83], v189, s[4:5] offset:16
	global_load_dwordx4 v[84:87], v189, s[4:5] offset:32
	v_mad_u32_u24 v190, v190, s64, v197
	v_mad_u32_u24 v191, v191, s64, v197
	global_load_dwordx4 v[88:91], v190, s[4:5]
	global_load_dwordx4 v[92:95], v190, s[4:5] offset:16
	global_load_dwordx4 v[96:99], v190, s[4:5] offset:32
	global_load_dwordx4 v[100:103], v191, s[4:5]
	global_load_dwordx4 v[104:107], v191, s[4:5] offset:16
	global_load_dwordx4 v[108:111], v191, s[4:5] offset:32
	s_mov_b32 s18, 1
	s_and_b32 s19, s18, 15
	s_lshr_b32 s50, s18, 4
	s_lshl_b32 s51, s19, 9
	s_mul_i32 s17, s19, s65
	s_lshl_b32 s18, s50, 6
	s_add_u32 s17, s17, s18
	s_add_u32 s12, s8, s17
	s_addc_u32 s13, s9, 0
	s_mul_i32 s17, s50, 0x300000
	s_add_u32 s4, s26, 0x1800000
	s_addc_u32 s5, s27, 0
	s_add_u32 s4, s4, s17
	s_addc_u32 s5, s5, 0
	v_add_u32_e32 v202, s51, v194
	ds_read2_b32 v[184:185], v202 offset0:0 offset1:16
	ds_read2_b32 v[186:187], v202 offset0:32 offset1:48
	ds_read2_b32 v[188:189], v202 offset0:64 offset1:80
	ds_read2_b32 v[190:191], v202 offset0:96 offset1:112
.Lgu0_loop:
	s_and_b32 s19, s16, 15
	s_lshl_b32 s51, s19, 9
	v_add_u32_e32 v203, s51, v195
	s_waitcnt vmcnt(24)
	ds_write_b64 v115, v[112:113]
	ds_read_b128 v[144:147], v116 offset:0
	ds_read_b128 v[148:151], v116 offset:64
	ds_read_b128 v[152:155], v116 offset:128
	ds_read_b128 v[156:159], v116 offset:192
	ds_read_b128 v[160:163], v116 offset:256
	ds_read_b128 v[164:167], v116 offset:320
	ds_read_b128 v[168:171], v116 offset:384
	ds_read_b128 v[172:175], v116 offset:448
	s_waitcnt lgkmcnt(0)
	s_waitcnt vmcnt(21)
	v_cvt_scalef32_pk32_bf16_fp6 v[0:15], v[16:21], 1.0
	v_cvt_scalef32_pk32_bf16_fp6 v[128:143], v[22:27], 1.0
	v_dot2_f32_bf16 v176, v0, v144, 0
	v_dot2_f32_bf16 v177, v1, v145, 0
	v_dot2_f32_bf16 v178, v2, v148, 0
	v_dot2_f32_bf16 v179, v3, v149, 0
	v_dot2c_f32_bf16_e32 v176, v4, v152
	v_dot2c_f32_bf16_e32 v177, v5, v153
	v_dot2c_f32_bf16_e32 v178, v6, v156
	v_dot2c_f32_bf16_e32 v179, v7, v157
	v_dot2c_f32_bf16_e32 v176, v8, v160
	v_dot2c_f32_bf16_e32 v177, v9, v161
	v_dot2c_f32_bf16_e32 v178, v10, v164
	v_dot2c_f32_bf16_e32 v179, v11, v165
	v_dot2c_f32_bf16_e32 v176, v12, v168
	v_dot2c_f32_bf16_e32 v177, v13, v169
	v_dot2c_f32_bf16_e32 v178, v14, v172
	v_dot2c_f32_bf16_e32 v179, v15, v173
	v_dot2c_f32_bf16_e32 v176, v128, v146
	v_dot2c_f32_bf16_e32 v177, v129, v147
	v_dot2c_f32_bf16_e32 v178, v130, v150
	v_dot2c_f32_bf16_e32 v179, v131, v151
	v_dot2c_f32_bf16_e32 v176, v132, v154
	v_dot2c_f32_bf16_e32 v177, v133, v155
	v_dot2c_f32_bf16_e32 v178, v134, v158
	v_dot2c_f32_bf16_e32 v179, v135, v159
	v_dot2c_f32_bf16_e32 v176, v136, v162
	v_dot2c_f32_bf16_e32 v177, v137, v163
	v_dot2c_f32_bf16_e32 v178, v138, v166
	v_dot2c_f32_bf16_e32 v179, v139, v167
	v_dot2c_f32_bf16_e32 v176, v140, v170
	v_dot2c_f32_bf16_e32 v177, v141, v171
	v_dot2c_f32_bf16_e32 v178, v142, v174
	v_dot2c_f32_bf16_e32 v179, v143, v175
	s_waitcnt vmcnt(18)
	v_cvt_scalef32_pk32_bf16_fp6 v[0:15], v[28:33], 1.0
	v_cvt_scalef32_pk32_bf16_fp6 v[128:143], v[34:39], 1.0
	v_dot2_f32_bf16 v180, v0, v144, 0
	v_dot2_f32_bf16 v181, v1, v145, 0
	v_dot2_f32_bf16 v182, v2, v148, 0
	v_dot2_f32_bf16 v183, v3, v149, 0
	v_dot2c_f32_bf16_e32 v180, v4, v152
	v_dot2c_f32_bf16_e32 v181, v5, v153
	v_dot2c_f32_bf16_e32 v182, v6, v156
	v_dot2c_f32_bf16_e32 v183, v7, v157
	v_add_f32_e32 v192, v176, v177
	v_add_f32_e32 v206, v178, v179
	v_add_f32_e32 v192, v192, v206
	s_nop 1
	v_add_f32_dpp v192, v192, v192 quad_perm:[1,0,3,2] row_mask:0xf bank_mask:0xf
	s_nop 1
	v_add_f32_dpp v192, v192, v192 quad_perm:[2,3,0,1] row_mask:0xf bank_mask:0xf
	v_cndmask_b32_e64 v118, v118, v192, s[70:71]
	v_dot2c_f32_bf16_e32 v180, v8, v160
	v_dot2c_f32_bf16_e32 v181, v9, v161
	v_dot2c_f32_bf16_e32 v182, v10, v164
	v_dot2c_f32_bf16_e32 v183, v11, v165
	v_dot2c_f32_bf16_e32 v180, v12, v168
	v_dot2c_f32_bf16_e32 v181, v13, v169
	v_dot2c_f32_bf16_e32 v182, v14, v172
	v_dot2c_f32_bf16_e32 v183, v15, v173
	v_dot2c_f32_bf16_e32 v180, v128, v146
	v_dot2c_f32_bf16_e32 v181, v129, v147
	v_dot2c_f32_bf16_e32 v182, v130, v150
	v_dot2c_f32_bf16_e32 v183, v131, v151
	v_dot2c_f32_bf16_e32 v180, v132, v154
	v_dot2c_f32_bf16_e32 v181, v133, v155
	v_dot2c_f32_bf16_e32 v182, v134, v158
	v_dot2c_f32_bf16_e32 v183, v135, v159
	v_dot2c_f32_bf16_e32 v180, v136, v162
	v_dot2c_f32_bf16_e32 v181, v137, v163
	v_dot2c_f32_bf16_e32 v182, v138, v166
	v_dot2c_f32_bf16_e32 v183, v139, v167
	v_dot2c_f32_bf16_e32 v180, v140, v170
	v_dot2c_f32_bf16_e32 v181, v141, v171
	v_dot2c_f32_bf16_e32 v182, v142, v174
	v_dot2c_f32_bf16_e32 v183, v143, v175
	global_load_dwordx2 v[112:113], v114, s[12:13]
	s_waitcnt lgkmcnt(0)
	v_mad_u32_u24 v184, v184, s64, v197
	v_mad_u32_u24 v185, v185, s64, v197
	global_load_dwordx4 v[16:19], v184, s[4:5]
	global_load_dwordx4 v[20:23], v184, s[4:5] offset:16
	global_load_dwordx4 v[24:27], v184, s[4:5] offset:32
	global_load_dwordx4 v[28:31], v185, s[4:5]
	global_load_dwordx4 v[32:35], v185, s[4:5] offset:16
	global_load_dwordx4 v[36:39], v185, s[4:5] offset:32
	s_waitcnt vmcnt(22)
	v_cvt_scalef32_pk32_bf16_fp6 v[0:15], v[40:45], 1.0
	v_cvt_scalef32_pk32_bf16_fp6 v[128:143], v[46:51], 1.0
	v_dot2_f32_bf16 v176, v0, v144, 0
	v_dot2_f32_bf16 v177, v1, v145, 0
	v_dot2_f32_bf16 v178, v2, v148, 0
	v_dot2_f32_bf16 v179, v3, v149, 0
	v_dot2c_f32_bf16_e32 v176, v4, v152
	v_dot2c_f32_bf16_e32 v177, v5, v153
	v_dot2c_f32_bf16_e32 v178, v6, v156
	v_dot2c_f32_bf16_e32 v179, v7, v157
	v_add_f32_e32 v192, v180, v181
	v_add_f32_e32 v206, v182, v183
	v_add_f32_e32 v192, v192, v206
	s_nop 1
	v_add_f32_dpp v192, v192, v192 quad_perm:[1,0,3,2] row_mask:0xf bank_mask:0xf
	s_nop 1
	v_add_f32_dpp v192, v192, v192 quad_perm:[2,3,0,1] row_mask:0xf bank_mask:0xf
	v_cndmask_b32_e64 v118, v118, v192, s[14:15]
	v_dot2c_f32_bf16_e32 v176, v8, v160
	v_dot2c_f32_bf16_e32 v177, v9, v161
	v_dot2c_f32_bf16_e32 v178, v10, v164
	v_dot2c_f32_bf16_e32 v179, v11, v165
	v_dot2c_f32_bf16_e32 v176, v12, v168
	v_dot2c_f32_bf16_e32 v177, v13, v169
	v_dot2c_f32_bf16_e32 v178, v14, v172
	v_dot2c_f32_bf16_e32 v179, v15, v173
	v_dot2c_f32_bf16_e32 v176, v128, v146
	v_dot2c_f32_bf16_e32 v177, v129, v147
	v_dot2c_f32_bf16_e32 v178, v130, v150
	v_dot2c_f32_bf16_e32 v179, v131, v151
	v_dot2c_f32_bf16_e32 v176, v132, v154
	v_dot2c_f32_bf16_e32 v177, v133, v155
	v_dot2c_f32_bf16_e32 v178, v134, v158
	v_dot2c_f32_bf16_e32 v179, v135, v159
	v_dot2c_f32_bf16_e32 v176, v136, v162
	v_dot2c_f32_bf16_e32 v177, v137, v163
	v_dot2c_f32_bf16_e32 v178, v138, v166
	v_dot2c_f32_bf16_e32 v179, v139, v167
	v_dot2c_f32_bf16_e32 v176, v140, v170
	v_dot2c_f32_bf16_e32 v177, v141, v171
	v_dot2c_f32_bf16_e32 v178, v142, v174
	v_dot2c_f32_bf16_e32 v179, v143, v175
	s_waitcnt vmcnt(19)
	v_cvt_scalef32_pk32_bf16_fp6 v[0:15], v[52:57], 1.0
	v_cvt_scalef32_pk32_bf16_fp6 v[128:143], v[58:63], 1.0
	v_dot2_f32_bf16 v180, v0, v144, 0
	v_dot2_f32_bf16 v181, v1, v145, 0
	v_dot2_f32_bf16 v182, v2, v148, 0
	v_dot2_f32_bf16 v183, v3, v149, 0
	v_dot2c_f32_bf16_e32 v180, v4, v152
	v_dot2c_f32_bf16_e32 v181, v5, v153
	v_dot2c_f32_bf16_e32 v182, v6, v156
	v_dot2c_f32_bf16_e32 v183, v7, v157
	v_add_f32_e32 v192, v176, v177
	v_add_f32_e32 v206, v178, v179
	v_add_f32_e32 v192, v192, v206
	s_nop 1
	v_add_f32_dpp v192, v192, v192 quad_perm:[1,0,3,2] row_mask:0xf bank_mask:0xf
	s_nop 1
	v_add_f32_dpp v192, v192, v192 quad_perm:[2,3,0,1] row_mask:0xf bank_mask:0xf
	v_cndmask_b32_e64 v118, v118, v192, s[100:101]
	v_dot2c_f32_bf16_e32 v180, v8, v160
	v_dot2c_f32_bf16_e32 v181, v9, v161
	v_dot2c_f32_bf16_e32 v182, v10, v164
	v_dot2c_f32_bf16_e32 v183, v11, v165
	v_dot2c_f32_bf16_e32 v180, v12, v168
	v_dot2c_f32_bf16_e32 v181, v13, v169
	v_dot2c_f32_bf16_e32 v182, v14, v172
	v_dot2c_f32_bf16_e32 v183, v15, v173
	v_dot2c_f32_bf16_e32 v180, v128, v146
	v_dot2c_f32_bf16_e32 v181, v129, v147
	v_dot2c_f32_bf16_e32 v182, v130, v150
	v_dot2c_f32_bf16_e32 v183, v131, v151
	v_dot2c_f32_bf16_e32 v180, v132, v154
	v_dot2c_f32_bf16_e32 v181, v133, v155
	v_dot2c_f32_bf16_e32 v182, v134, v158
	v_dot2c_f32_bf16_e32 v183, v135, v159
	v_dot2c_f32_bf16_e32 v180, v136, v162
	v_dot2c_f32_bf16_e32 v181, v137, v163
	v_dot2c_f32_bf16_e32 v182, v138, v166
	v_dot2c_f32_bf16_e32 v183, v139, v167
	v_dot2c_f32_bf16_e32 v180, v140, v170
	v_dot2c_f32_bf16_e32 v181, v141, v171
	v_dot2c_f32_bf16_e32 v182, v142, v174
	v_dot2c_f32_bf16_e32 v183, v143, v175
	v_mad_u32_u24 v186, v186, s64, v197
	v_mad_u32_u24 v187, v187, s64, v197
	global_load_dwordx4 v[40:43], v186, s[4:5]
	global_load_dwordx4 v[44:47], v186, s[4:5] offset:16
	global_load_dwordx4 v[48:51], v186, s[4:5] offset:32
	global_load_dwordx4 v[52:55], v187, s[4:5]
	global_load_dwordx4 v[56:59], v187, s[4:5] offset:16
	global_load_dwordx4 v[60:63], v187, s[4:5] offset:32
	s_waitcnt vmcnt(22)
	v_cvt_scalef32_pk32_bf16_fp6 v[0:15], v[64:69], 1.0
	v_cvt_scalef32_pk32_bf16_fp6 v[128:143], v[70:75], 1.0
	v_dot2_f32_bf16 v176, v0, v144, 0
	v_dot2_f32_bf16 v177, v1, v145, 0
	v_dot2_f32_bf16 v178, v2, v148, 0
	v_dot2_f32_bf16 v179, v3, v149, 0
	v_dot2c_f32_bf16_e32 v176, v4, v152
	v_dot2c_f32_bf16_e32 v177, v5, v153
	v_dot2c_f32_bf16_e32 v178, v6, v156
	v_dot2c_f32_bf16_e32 v179, v7, v157
	v_add_f32_e32 v192, v180, v181
	v_add_f32_e32 v206, v182, v183
	v_add_f32_e32 v192, v192, v206
	s_nop 1
	v_add_f32_dpp v192, v192, v192 quad_perm:[1,0,3,2] row_mask:0xf bank_mask:0xf
	s_nop 1
	v_add_f32_dpp v192, v192, v192 quad_perm:[2,3,0,1] row_mask:0xf bank_mask:0xf
	v_cndmask_b32_e64 v118, v118, v192, s[98:99]
	ds_add_f32 v203, v118 offset:0
	v_dot2c_f32_bf16_e32 v176, v8, v160
	v_dot2c_f32_bf16_e32 v177, v9, v161
	v_dot2c_f32_bf16_e32 v178, v10, v164
	v_dot2c_f32_bf16_e32 v179, v11, v165
	v_dot2c_f32_bf16_e32 v176, v12, v168
	v_dot2c_f32_bf16_e32 v177, v13, v169
	v_dot2c_f32_bf16_e32 v178, v14, v172
	v_dot2c_f32_bf16_e32 v179, v15, v173
	v_dot2c_f32_bf16_e32 v176, v128, v146
	v_dot2c_f32_bf16_e32 v177, v129, v147
	v_dot2c_f32_bf16_e32 v178, v130, v150
	v_dot2c_f32_bf16_e32 v179, v131, v151
	v_dot2c_f32_bf16_e32 v176, v132, v154
	v_dot2c_f32_bf16_e32 v177, v133, v155
	v_dot2c_f32_bf16_e32 v178, v134, v158
	v_dot2c_f32_bf16_e32 v179, v135, v159
	v_dot2c_f32_bf16_e32 v176, v136, v162
	v_dot2c_f32_bf16_e32 v177, v137, v163
	v_dot2c_f32_bf16_e32 v178, v138, v166
	v_dot2c_f32_bf16_e32 v179, v139, v167
	v_dot2c_f32_bf16_e32 v176, v140, v170
	v_dot2c_f32_bf16_e32 v177, v141, v171
	v_dot2c_f32_bf16_e32 v178, v142, v174
	v_dot2c_f32_bf16_e32 v179, v143, v175
	s_waitcnt vmcnt(19)
	v_cvt_scalef32_pk32_bf16_fp6 v[0:15], v[76:81], 1.0
	v_cvt_scalef32_pk32_bf16_fp6 v[128:143], v[82:87], 1.0
	v_dot2_f32_bf16 v180, v0, v144, 0
	v_dot2_f32_bf16 v181, v1, v145, 0
	v_dot2_f32_bf16 v182, v2, v148, 0
	v_dot2_f32_bf16 v183, v3, v149, 0
	v_dot2c_f32_bf16_e32 v180, v4, v152
	v_dot2c_f32_bf16_e32 v181, v5, v153
	v_dot2c_f32_bf16_e32 v182, v6, v156
	v_dot2c_f32_bf16_e32 v183, v7, v157
	v_add_f32_e32 v192, v176, v177
	v_add_f32_e32 v206, v178, v179
	v_add_f32_e32 v192, v192, v206
	s_nop 1
	v_add_f32_dpp v192, v192, v192 quad_perm:[1,0,3,2] row_mask:0xf bank_mask:0xf
	s_nop 1
	v_add_f32_dpp v192, v192, v192 quad_perm:[2,3,0,1] row_mask:0xf bank_mask:0xf
	v_cndmask_b32_e64 v119, v119, v192, s[70:71]
	v_dot2c_f32_bf16_e32 v180, v8, v160
	v_dot2c_f32_bf16_e32 v181, v9, v161
	v_dot2c_f32_bf16_e32 v182, v10, v164
	v_dot2c_f32_bf16_e32 v183, v11, v165
	v_dot2c_f32_bf16_e32 v180, v12, v168
	v_dot2c_f32_bf16_e32 v181, v13, v169
	v_dot2c_f32_bf16_e32 v182, v14, v172
	v_dot2c_f32_bf16_e32 v183, v15, v173
	v_dot2c_f32_bf16_e32 v180, v128, v146
	v_dot2c_f32_bf16_e32 v181, v129, v147
	v_dot2c_f32_bf16_e32 v182, v130, v150
	v_dot2c_f32_bf16_e32 v183, v131, v151
	v_dot2c_f32_bf16_e32 v180, v132, v154
	v_dot2c_f32_bf16_e32 v181, v133, v155
	v_dot2c_f32_bf16_e32 v182, v134, v158
	v_dot2c_f32_bf16_e32 v183, v135, v159
	v_dot2c_f32_bf16_e32 v180, v136, v162
	v_dot2c_f32_bf16_e32 v181, v137, v163
	v_dot2c_f32_bf16_e32 v182, v138, v166
	v_dot2c_f32_bf16_e32 v183, v139, v167
	v_dot2c_f32_bf16_e32 v180, v140, v170
	v_dot2c_f32_bf16_e32 v181, v141, v171
	v_dot2c_f32_bf16_e32 v182, v142, v174
	v_dot2c_f32_bf16_e32 v183, v143, v175
	v_mad_u32_u24 v188, v188, s64, v197
	v_mad_u32_u24 v189, v189, s64, v197
	global_load_dwordx4 v[64:67], v188, s[4:5]
	global_load_dwordx4 v[68:71], v188, s[4:5] offset:16
	global_load_dwordx4 v[72:75], v188, s[4:5] offset:32
	global_load_dwordx4 v[76:79], v189, s[4:5]
	global_load_dwordx4 v[80:83], v189, s[4:5] offset:16
	global_load_dwordx4 v[84:87], v189, s[4:5] offset:32
	s_waitcnt vmcnt(22)
	v_cvt_scalef32_pk32_bf16_fp6 v[0:15], v[88:93], 1.0
	v_cvt_scalef32_pk32_bf16_fp6 v[128:143], v[94:99], 1.0
	v_dot2_f32_bf16 v176, v0, v144, 0
	v_dot2_f32_bf16 v177, v1, v145, 0
	v_dot2_f32_bf16 v178, v2, v148, 0
	v_dot2_f32_bf16 v179, v3, v149, 0
	v_dot2c_f32_bf16_e32 v176, v4, v152
	v_dot2c_f32_bf16_e32 v177, v5, v153
	v_dot2c_f32_bf16_e32 v178, v6, v156
	v_dot2c_f32_bf16_e32 v179, v7, v157
	v_add_f32_e32 v192, v180, v181
	v_add_f32_e32 v206, v182, v183
	v_add_f32_e32 v192, v192, v206
	s_nop 1
	v_add_f32_dpp v192, v192, v192 quad_perm:[1,0,3,2] row_mask:0xf bank_mask:0xf
	s_nop 1
	v_add_f32_dpp v192, v192, v192 quad_perm:[2,3,0,1] row_mask:0xf bank_mask:0xf
	v_cndmask_b32_e64 v119, v119, v192, s[14:15]
	v_dot2c_f32_bf16_e32 v176, v8, v160
	v_dot2c_f32_bf16_e32 v177, v9, v161
	v_dot2c_f32_bf16_e32 v178, v10, v164
	v_dot2c_f32_bf16_e32 v179, v11, v165
	v_dot2c_f32_bf16_e32 v176, v12, v168
	v_dot2c_f32_bf16_e32 v177, v13, v169
	v_dot2c_f32_bf16_e32 v178, v14, v172
	v_dot2c_f32_bf16_e32 v179, v15, v173
	v_dot2c_f32_bf16_e32 v176, v128, v146
	v_dot2c_f32_bf16_e32 v177, v129, v147
	v_dot2c_f32_bf16_e32 v178, v130, v150
	v_dot2c_f32_bf16_e32 v179, v131, v151
	v_dot2c_f32_bf16_e32 v176, v132, v154
	v_dot2c_f32_bf16_e32 v177, v133, v155
	v_dot2c_f32_bf16_e32 v178, v134, v158
	v_dot2c_f32_bf16_e32 v179, v135, v159
	v_dot2c_f32_bf16_e32 v176, v136, v162
	v_dot2c_f32_bf16_e32 v177, v137, v163
	v_dot2c_f32_bf16_e32 v178, v138, v166
	v_dot2c_f32_bf16_e32 v179, v139, v167
	v_dot2c_f32_bf16_e32 v176, v140, v170
	v_dot2c_f32_bf16_e32 v177, v141, v171
	v_dot2c_f32_bf16_e32 v178, v142, v174
	v_dot2c_f32_bf16_e32 v179, v143, v175
	s_waitcnt vmcnt(19)
	v_cvt_scalef32_pk32_bf16_fp6 v[0:15], v[100:105], 1.0
	v_cvt_scalef32_pk32_bf16_fp6 v[128:143], v[106:111], 1.0
	v_dot2_f32_bf16 v180, v0, v144, 0
	v_dot2_f32_bf16 v181, v1, v145, 0
	v_dot2_f32_bf16 v182, v2, v148, 0
	v_dot2_f32_bf16 v183, v3, v149, 0
	v_dot2c_f32_bf16_e32 v180, v4, v152
	v_dot2c_f32_bf16_e32 v181, v5, v153
	v_dot2c_f32_bf16_e32 v182, v6, v156
	v_dot2c_f32_bf16_e32 v183, v7, v157
	v_add_f32_e32 v192, v176, v177
	v_add_f32_e32 v206, v178, v179
	v_add_f32_e32 v192, v192, v206
	s_nop 1
	v_add_f32_dpp v192, v192, v192 quad_perm:[1,0,3,2] row_mask:0xf bank_mask:0xf
	s_nop 1
	v_add_f32_dpp v192, v192, v192 quad_perm:[2,3,0,1] row_mask:0xf bank_mask:0xf
	v_cndmask_b32_e64 v119, v119, v192, s[100:101]
	v_dot2c_f32_bf16_e32 v180, v8, v160
	v_dot2c_f32_bf16_e32 v181, v9, v161
	v_dot2c_f32_bf16_e32 v182, v10, v164
	v_dot2c_f32_bf16_e32 v183, v11, v165
	v_dot2c_f32_bf16_e32 v180, v12, v168
	v_dot2c_f32_bf16_e32 v181, v13, v169
	v_dot2c_f32_bf16_e32 v182, v14, v172
	v_dot2c_f32_bf16_e32 v183, v15, v173
	v_dot2c_f32_bf16_e32 v180, v128, v146
	v_dot2c_f32_bf16_e32 v181, v129, v147
	v_dot2c_f32_bf16_e32 v182, v130, v150
	v_dot2c_f32_bf16_e32 v183, v131, v151
	v_dot2c_f32_bf16_e32 v180, v132, v154
	v_dot2c_f32_bf16_e32 v181, v133, v155
	v_dot2c_f32_bf16_e32 v182, v134, v158
	v_dot2c_f32_bf16_e32 v183, v135, v159
	v_dot2c_f32_bf16_e32 v180, v136, v162
	v_dot2c_f32_bf16_e32 v181, v137, v163
	v_dot2c_f32_bf16_e32 v182, v138, v166
	v_dot2c_f32_bf16_e32 v183, v139, v167
	v_dot2c_f32_bf16_e32 v180, v140, v170
	v_dot2c_f32_bf16_e32 v181, v141, v171
	v_dot2c_f32_bf16_e32 v182, v142, v174
	v_dot2c_f32_bf16_e32 v183, v143, v175
	v_mad_u32_u24 v190, v190, s64, v197
	v_mad_u32_u24 v191, v191, s64, v197
	global_load_dwordx4 v[88:91], v190, s[4:5]
	global_load_dwordx4 v[92:95], v190, s[4:5] offset:16
	global_load_dwordx4 v[96:99], v190, s[4:5] offset:32
	global_load_dwordx4 v[100:103], v191, s[4:5]
	global_load_dwordx4 v[104:107], v191, s[4:5] offset:16
	global_load_dwordx4 v[108:111], v191, s[4:5] offset:32
	s_add_u32 s16, s16, 1
	s_and_b32 s16, s16, 63
	s_add_u32 s18, s16, 1
	s_and_b32 s18, s18, 63
	s_and_b32 s19, s18, 15
	s_lshr_b32 s50, s18, 4
	s_lshl_b32 s51, s19, 9
	s_mul_i32 s17, s19, s65
	s_lshl_b32 s18, s50, 6
	s_add_u32 s17, s17, s18
	s_add_u32 s10, s8, s17
	s_addc_u32 s11, s9, 0
	s_mul_i32 s17, s50, 0x300000
	s_add_u32 s4, s26, 0x1800000
	s_addc_u32 s5, s27, 0
	s_add_u32 s4, s4, s17
	s_addc_u32 s5, s5, 0
	v_add_u32_e32 v201, s51, v194
	ds_read2_b32 v[184:185], v201 offset0:0 offset1:16
	ds_read2_b32 v[186:187], v201 offset0:32 offset1:48
	ds_read2_b32 v[188:189], v201 offset0:64 offset1:80
	ds_read2_b32 v[190:191], v201 offset0:96 offset1:112
	v_add_f32_e32 v192, v180, v181
	v_add_f32_e32 v206, v182, v183
	v_add_f32_e32 v192, v192, v206
	s_nop 1
	v_add_f32_dpp v192, v192, v192 quad_perm:[1,0,3,2] row_mask:0xf bank_mask:0xf
	s_nop 1
	v_add_f32_dpp v192, v192, v192 quad_perm:[2,3,0,1] row_mask:0xf bank_mask:0xf
	v_cndmask_b32_e64 v119, v119, v192, s[98:99]
	ds_add_f32 v203, v119 offset:256
	s_and_b32 s19, s16, 15
	s_lshl_b32 s51, s19, 9
	v_add_u32_e32 v204, s51, v195
	s_waitcnt vmcnt(24)
	ds_write_b64 v115, v[112:113]
	ds_read_b128 v[144:147], v116 offset:0
	ds_read_b128 v[148:151], v116 offset:64
	ds_read_b128 v[152:155], v116 offset:128
	ds_read_b128 v[156:159], v116 offset:192
	ds_read_b128 v[160:163], v116 offset:256
	ds_read_b128 v[164:167], v116 offset:320
	ds_read_b128 v[168:171], v116 offset:384
	ds_read_b128 v[172:175], v116 offset:448
	s_waitcnt lgkmcnt(0)
	s_waitcnt vmcnt(21)
	v_cvt_scalef32_pk32_bf16_fp6 v[0:15], v[16:21], 1.0
	v_cvt_scalef32_pk32_bf16_fp6 v[128:143], v[22:27], 1.0
	v_dot2_f32_bf16 v176, v0, v144, 0
	v_dot2_f32_bf16 v177, v1, v145, 0
	v_dot2_f32_bf16 v178, v2, v148, 0
	v_dot2_f32_bf16 v179, v3, v149, 0
	v_dot2c_f32_bf16_e32 v176, v4, v152
	v_dot2c_f32_bf16_e32 v177, v5, v153
	v_dot2c_f32_bf16_e32 v178, v6, v156
	v_dot2c_f32_bf16_e32 v179, v7, v157
	v_dot2c_f32_bf16_e32 v176, v8, v160
	v_dot2c_f32_bf16_e32 v177, v9, v161
	v_dot2c_f32_bf16_e32 v178, v10, v164
	v_dot2c_f32_bf16_e32 v179, v11, v165
	v_dot2c_f32_bf16_e32 v176, v12, v168
	v_dot2c_f32_bf16_e32 v177, v13, v169
	v_dot2c_f32_bf16_e32 v178, v14, v172
	v_dot2c_f32_bf16_e32 v179, v15, v173
	v_dot2c_f32_bf16_e32 v176, v128, v146
	v_dot2c_f32_bf16_e32 v177, v129, v147
	v_dot2c_f32_bf16_e32 v178, v130, v150
	v_dot2c_f32_bf16_e32 v179, v131, v151
	v_dot2c_f32_bf16_e32 v176, v132, v154
	v_dot2c_f32_bf16_e32 v177, v133, v155
	v_dot2c_f32_bf16_e32 v178, v134, v158
	v_dot2c_f32_bf16_e32 v179, v135, v159
	v_dot2c_f32_bf16_e32 v176, v136, v162
	v_dot2c_f32_bf16_e32 v177, v137, v163
	v_dot2c_f32_bf16_e32 v178, v138, v166
	v_dot2c_f32_bf16_e32 v179, v139, v167
	v_dot2c_f32_bf16_e32 v176, v140, v170
	v_dot2c_f32_bf16_e32 v177, v141, v171
	v_dot2c_f32_bf16_e32 v178, v142, v174
	v_dot2c_f32_bf16_e32 v179, v143, v175
	s_waitcnt vmcnt(18)
	v_cvt_scalef32_pk32_bf16_fp6 v[0:15], v[28:33], 1.0
	v_cvt_scalef32_pk32_bf16_fp6 v[128:143], v[34:39], 1.0
	v_dot2_f32_bf16 v180, v0, v144, 0
	v_dot2_f32_bf16 v181, v1, v145, 0
	v_dot2_f32_bf16 v182, v2, v148, 0
	v_dot2_f32_bf16 v183, v3, v149, 0
	v_dot2c_f32_bf16_e32 v180, v4, v152
	v_dot2c_f32_bf16_e32 v181, v5, v153
	v_dot2c_f32_bf16_e32 v182, v6, v156
	v_dot2c_f32_bf16_e32 v183, v7, v157
	v_add_f32_e32 v192, v176, v177
	v_add_f32_e32 v206, v178, v179
	v_add_f32_e32 v192, v192, v206
	s_nop 1
	v_add_f32_dpp v192, v192, v192 quad_perm:[1,0,3,2] row_mask:0xf bank_mask:0xf
	s_nop 1
	v_add_f32_dpp v192, v192, v192 quad_perm:[2,3,0,1] row_mask:0xf bank_mask:0xf
	v_cndmask_b32_e64 v118, v118, v192, s[70:71]
	v_dot2c_f32_bf16_e32 v180, v8, v160
	v_dot2c_f32_bf16_e32 v181, v9, v161
	v_dot2c_f32_bf16_e32 v182, v10, v164
	v_dot2c_f32_bf16_e32 v183, v11, v165
	v_dot2c_f32_bf16_e32 v180, v12, v168
	v_dot2c_f32_bf16_e32 v181, v13, v169
	v_dot2c_f32_bf16_e32 v182, v14, v172
	v_dot2c_f32_bf16_e32 v183, v15, v173
	v_dot2c_f32_bf16_e32 v180, v128, v146
	v_dot2c_f32_bf16_e32 v181, v129, v147
	v_dot2c_f32_bf16_e32 v182, v130, v150
	v_dot2c_f32_bf16_e32 v183, v131, v151
	v_dot2c_f32_bf16_e32 v180, v132, v154
	v_dot2c_f32_bf16_e32 v181, v133, v155
	v_dot2c_f32_bf16_e32 v182, v134, v158
	v_dot2c_f32_bf16_e32 v183, v135, v159
	v_dot2c_f32_bf16_e32 v180, v136, v162
	v_dot2c_f32_bf16_e32 v181, v137, v163
	v_dot2c_f32_bf16_e32 v182, v138, v166
	v_dot2c_f32_bf16_e32 v183, v139, v167
	v_dot2c_f32_bf16_e32 v180, v140, v170
	v_dot2c_f32_bf16_e32 v181, v141, v171
	v_dot2c_f32_bf16_e32 v182, v142, v174
	v_dot2c_f32_bf16_e32 v183, v143, v175
	global_load_dwordx2 v[112:113], v114, s[10:11]
	s_waitcnt lgkmcnt(0)
	v_mad_u32_u24 v184, v184, s64, v197
	v_mad_u32_u24 v185, v185, s64, v197
	global_load_dwordx4 v[16:19], v184, s[4:5]
	global_load_dwordx4 v[20:23], v184, s[4:5] offset:16
	global_load_dwordx4 v[24:27], v184, s[4:5] offset:32
	global_load_dwordx4 v[28:31], v185, s[4:5]
	global_load_dwordx4 v[32:35], v185, s[4:5] offset:16
	global_load_dwordx4 v[36:39], v185, s[4:5] offset:32
	s_waitcnt vmcnt(22)
	v_cvt_scalef32_pk32_bf16_fp6 v[0:15], v[40:45], 1.0
	v_cvt_scalef32_pk32_bf16_fp6 v[128:143], v[46:51], 1.0
	v_dot2_f32_bf16 v176, v0, v144, 0
	v_dot2_f32_bf16 v177, v1, v145, 0
	v_dot2_f32_bf16 v178, v2, v148, 0
	v_dot2_f32_bf16 v179, v3, v149, 0
	v_dot2c_f32_bf16_e32 v176, v4, v152
	v_dot2c_f32_bf16_e32 v177, v5, v153
	v_dot2c_f32_bf16_e32 v178, v6, v156
	v_dot2c_f32_bf16_e32 v179, v7, v157
	v_add_f32_e32 v192, v180, v181
	v_add_f32_e32 v206, v182, v183
	v_add_f32_e32 v192, v192, v206
	s_nop 1
	v_add_f32_dpp v192, v192, v192 quad_perm:[1,0,3,2] row_mask:0xf bank_mask:0xf
	s_nop 1
	v_add_f32_dpp v192, v192, v192 quad_perm:[2,3,0,1] row_mask:0xf bank_mask:0xf
	v_cndmask_b32_e64 v118, v118, v192, s[14:15]
	v_dot2c_f32_bf16_e32 v176, v8, v160
	v_dot2c_f32_bf16_e32 v177, v9, v161
	v_dot2c_f32_bf16_e32 v178, v10, v164
	v_dot2c_f32_bf16_e32 v179, v11, v165
	v_dot2c_f32_bf16_e32 v176, v12, v168
	v_dot2c_f32_bf16_e32 v177, v13, v169
	v_dot2c_f32_bf16_e32 v178, v14, v172
	v_dot2c_f32_bf16_e32 v179, v15, v173
	v_dot2c_f32_bf16_e32 v176, v128, v146
	v_dot2c_f32_bf16_e32 v177, v129, v147
	v_dot2c_f32_bf16_e32 v178, v130, v150
	v_dot2c_f32_bf16_e32 v179, v131, v151
	v_dot2c_f32_bf16_e32 v176, v132, v154
	v_dot2c_f32_bf16_e32 v177, v133, v155
	v_dot2c_f32_bf16_e32 v178, v134, v158
	v_dot2c_f32_bf16_e32 v179, v135, v159
	v_dot2c_f32_bf16_e32 v176, v136, v162
	v_dot2c_f32_bf16_e32 v177, v137, v163
	v_dot2c_f32_bf16_e32 v178, v138, v166
	v_dot2c_f32_bf16_e32 v179, v139, v167
	v_dot2c_f32_bf16_e32 v176, v140, v170
	v_dot2c_f32_bf16_e32 v177, v141, v171
	v_dot2c_f32_bf16_e32 v178, v142, v174
	v_dot2c_f32_bf16_e32 v179, v143, v175
	s_waitcnt vmcnt(19)
	v_cvt_scalef32_pk32_bf16_fp6 v[0:15], v[52:57], 1.0
	v_cvt_scalef32_pk32_bf16_fp6 v[128:143], v[58:63], 1.0
	v_dot2_f32_bf16 v180, v0, v144, 0
	v_dot2_f32_bf16 v181, v1, v145, 0
	v_dot2_f32_bf16 v182, v2, v148, 0
	v_dot2_f32_bf16 v183, v3, v149, 0
	v_dot2c_f32_bf16_e32 v180, v4, v152
	v_dot2c_f32_bf16_e32 v181, v5, v153
	v_dot2c_f32_bf16_e32 v182, v6, v156
	v_dot2c_f32_bf16_e32 v183, v7, v157
	v_add_f32_e32 v192, v176, v177
	v_add_f32_e32 v206, v178, v179
	v_add_f32_e32 v192, v192, v206
	s_nop 1
	v_add_f32_dpp v192, v192, v192 quad_perm:[1,0,3,2] row_mask:0xf bank_mask:0xf
	s_nop 1
	v_add_f32_dpp v192, v192, v192 quad_perm:[2,3,0,1] row_mask:0xf bank_mask:0xf
	v_cndmask_b32_e64 v118, v118, v192, s[100:101]
	v_dot2c_f32_bf16_e32 v180, v8, v160
	v_dot2c_f32_bf16_e32 v181, v9, v161
	v_dot2c_f32_bf16_e32 v182, v10, v164
	v_dot2c_f32_bf16_e32 v183, v11, v165
	v_dot2c_f32_bf16_e32 v180, v12, v168
	v_dot2c_f32_bf16_e32 v181, v13, v169
	v_dot2c_f32_bf16_e32 v182, v14, v172
	v_dot2c_f32_bf16_e32 v183, v15, v173
	v_dot2c_f32_bf16_e32 v180, v128, v146
	v_dot2c_f32_bf16_e32 v181, v129, v147
	v_dot2c_f32_bf16_e32 v182, v130, v150
	v_dot2c_f32_bf16_e32 v183, v131, v151
	v_dot2c_f32_bf16_e32 v180, v132, v154
	v_dot2c_f32_bf16_e32 v181, v133, v155
	v_dot2c_f32_bf16_e32 v182, v134, v158
	v_dot2c_f32_bf16_e32 v183, v135, v159
	v_dot2c_f32_bf16_e32 v180, v136, v162
	v_dot2c_f32_bf16_e32 v181, v137, v163
	v_dot2c_f32_bf16_e32 v182, v138, v166
	v_dot2c_f32_bf16_e32 v183, v139, v167
	v_dot2c_f32_bf16_e32 v180, v140, v170
	v_dot2c_f32_bf16_e32 v181, v141, v171
	v_dot2c_f32_bf16_e32 v182, v142, v174
	v_dot2c_f32_bf16_e32 v183, v143, v175
	v_mad_u32_u24 v186, v186, s64, v197
	v_mad_u32_u24 v187, v187, s64, v197
	global_load_dwordx4 v[40:43], v186, s[4:5]
	global_load_dwordx4 v[44:47], v186, s[4:5] offset:16
	global_load_dwordx4 v[48:51], v186, s[4:5] offset:32
	global_load_dwordx4 v[52:55], v187, s[4:5]
	global_load_dwordx4 v[56:59], v187, s[4:5] offset:16
	global_load_dwordx4 v[60:63], v187, s[4:5] offset:32
	s_waitcnt vmcnt(22)
	v_cvt_scalef32_pk32_bf16_fp6 v[0:15], v[64:69], 1.0
	v_cvt_scalef32_pk32_bf16_fp6 v[128:143], v[70:75], 1.0
	v_dot2_f32_bf16 v176, v0, v144, 0
	v_dot2_f32_bf16 v177, v1, v145, 0
	v_dot2_f32_bf16 v178, v2, v148, 0
	v_dot2_f32_bf16 v179, v3, v149, 0
	v_dot2c_f32_bf16_e32 v176, v4, v152
	v_dot2c_f32_bf16_e32 v177, v5, v153
	v_dot2c_f32_bf16_e32 v178, v6, v156
	v_dot2c_f32_bf16_e32 v179, v7, v157
	v_add_f32_e32 v192, v180, v181
	v_add_f32_e32 v206, v182, v183
	v_add_f32_e32 v192, v192, v206
	s_nop 1
	v_add_f32_dpp v192, v192, v192 quad_perm:[1,0,3,2] row_mask:0xf bank_mask:0xf
	s_nop 1
	v_add_f32_dpp v192, v192, v192 quad_perm:[2,3,0,1] row_mask:0xf bank_mask:0xf
	v_cndmask_b32_e64 v118, v118, v192, s[98:99]
	ds_add_f32 v204, v118 offset:0
	v_dot2c_f32_bf16_e32 v176, v8, v160
	v_dot2c_f32_bf16_e32 v177, v9, v161
	v_dot2c_f32_bf16_e32 v178, v10, v164
	v_dot2c_f32_bf16_e32 v179, v11, v165
	v_dot2c_f32_bf16_e32 v176, v12, v168
	v_dot2c_f32_bf16_e32 v177, v13, v169
	v_dot2c_f32_bf16_e32 v178, v14, v172
	v_dot2c_f32_bf16_e32 v179, v15, v173
	v_dot2c_f32_bf16_e32 v176, v128, v146
	v_dot2c_f32_bf16_e32 v177, v129, v147
	v_dot2c_f32_bf16_e32 v178, v130, v150
	v_dot2c_f32_bf16_e32 v179, v131, v151
	v_dot2c_f32_bf16_e32 v176, v132, v154
	v_dot2c_f32_bf16_e32 v177, v133, v155
	v_dot2c_f32_bf16_e32 v178, v134, v158
	v_dot2c_f32_bf16_e32 v179, v135, v159
	v_dot2c_f32_bf16_e32 v176, v136, v162
	v_dot2c_f32_bf16_e32 v177, v137, v163
	v_dot2c_f32_bf16_e32 v178, v138, v166
	v_dot2c_f32_bf16_e32 v179, v139, v167
	v_dot2c_f32_bf16_e32 v176, v140, v170
	v_dot2c_f32_bf16_e32 v177, v141, v171
	v_dot2c_f32_bf16_e32 v178, v142, v174
	v_dot2c_f32_bf16_e32 v179, v143, v175
	s_waitcnt vmcnt(19)
	v_cvt_scalef32_pk32_bf16_fp6 v[0:15], v[76:81], 1.0
	v_cvt_scalef32_pk32_bf16_fp6 v[128:143], v[82:87], 1.0
	v_dot2_f32_bf16 v180, v0, v144, 0
	v_dot2_f32_bf16 v181, v1, v145, 0
	v_dot2_f32_bf16 v182, v2, v148, 0
	v_dot2_f32_bf16 v183, v3, v149, 0
	v_dot2c_f32_bf16_e32 v180, v4, v152
	v_dot2c_f32_bf16_e32 v181, v5, v153
	v_dot2c_f32_bf16_e32 v182, v6, v156
	v_dot2c_f32_bf16_e32 v183, v7, v157
	v_add_f32_e32 v192, v176, v177
	v_add_f32_e32 v206, v178, v179
	v_add_f32_e32 v192, v192, v206
	s_nop 1
	v_add_f32_dpp v192, v192, v192 quad_perm:[1,0,3,2] row_mask:0xf bank_mask:0xf
	s_nop 1
	v_add_f32_dpp v192, v192, v192 quad_perm:[2,3,0,1] row_mask:0xf bank_mask:0xf
	v_cndmask_b32_e64 v119, v119, v192, s[70:71]
	v_dot2c_f32_bf16_e32 v180, v8, v160
	v_dot2c_f32_bf16_e32 v181, v9, v161
	v_dot2c_f32_bf16_e32 v182, v10, v164
	v_dot2c_f32_bf16_e32 v183, v11, v165
	v_dot2c_f32_bf16_e32 v180, v12, v168
	v_dot2c_f32_bf16_e32 v181, v13, v169
	v_dot2c_f32_bf16_e32 v182, v14, v172
	v_dot2c_f32_bf16_e32 v183, v15, v173
	v_dot2c_f32_bf16_e32 v180, v128, v146
	v_dot2c_f32_bf16_e32 v181, v129, v147
	v_dot2c_f32_bf16_e32 v182, v130, v150
	v_dot2c_f32_bf16_e32 v183, v131, v151
	v_dot2c_f32_bf16_e32 v180, v132, v154
	v_dot2c_f32_bf16_e32 v181, v133, v155
	v_dot2c_f32_bf16_e32 v182, v134, v158
	v_dot2c_f32_bf16_e32 v183, v135, v159
	v_dot2c_f32_bf16_e32 v180, v136, v162
	v_dot2c_f32_bf16_e32 v181, v137, v163
	v_dot2c_f32_bf16_e32 v182, v138, v166
	v_dot2c_f32_bf16_e32 v183, v139, v167
	v_dot2c_f32_bf16_e32 v180, v140, v170
	v_dot2c_f32_bf16_e32 v181, v141, v171
	v_dot2c_f32_bf16_e32 v182, v142, v174
	v_dot2c_f32_bf16_e32 v183, v143, v175
	v_mad_u32_u24 v188, v188, s64, v197
	v_mad_u32_u24 v189, v189, s64, v197
	global_load_dwordx4 v[64:67], v188, s[4:5]
	global_load_dwordx4 v[68:71], v188, s[4:5] offset:16
	global_load_dwordx4 v[72:75], v188, s[4:5] offset:32
	global_load_dwordx4 v[76:79], v189, s[4:5]
	global_load_dwordx4 v[80:83], v189, s[4:5] offset:16
	global_load_dwordx4 v[84:87], v189, s[4:5] offset:32
	s_waitcnt vmcnt(22)
	v_cvt_scalef32_pk32_bf16_fp6 v[0:15], v[88:93], 1.0
	v_cvt_scalef32_pk32_bf16_fp6 v[128:143], v[94:99], 1.0
	v_dot2_f32_bf16 v176, v0, v144, 0
	v_dot2_f32_bf16 v177, v1, v145, 0
	v_dot2_f32_bf16 v178, v2, v148, 0
	v_dot2_f32_bf16 v179, v3, v149, 0
	v_dot2c_f32_bf16_e32 v176, v4, v152
	v_dot2c_f32_bf16_e32 v177, v5, v153
	v_dot2c_f32_bf16_e32 v178, v6, v156
	v_dot2c_f32_bf16_e32 v179, v7, v157
	v_add_f32_e32 v192, v180, v181
	v_add_f32_e32 v206, v182, v183
	v_add_f32_e32 v192, v192, v206
	s_nop 1
	v_add_f32_dpp v192, v192, v192 quad_perm:[1,0,3,2] row_mask:0xf bank_mask:0xf
	s_nop 1
	v_add_f32_dpp v192, v192, v192 quad_perm:[2,3,0,1] row_mask:0xf bank_mask:0xf
	v_cndmask_b32_e64 v119, v119, v192, s[14:15]
	v_dot2c_f32_bf16_e32 v176, v8, v160
	v_dot2c_f32_bf16_e32 v177, v9, v161
	v_dot2c_f32_bf16_e32 v178, v10, v164
	v_dot2c_f32_bf16_e32 v179, v11, v165
	v_dot2c_f32_bf16_e32 v176, v12, v168
	v_dot2c_f32_bf16_e32 v177, v13, v169
	v_dot2c_f32_bf16_e32 v178, v14, v172
	v_dot2c_f32_bf16_e32 v179, v15, v173
	v_dot2c_f32_bf16_e32 v176, v128, v146
	v_dot2c_f32_bf16_e32 v177, v129, v147
	v_dot2c_f32_bf16_e32 v178, v130, v150
	v_dot2c_f32_bf16_e32 v179, v131, v151
	v_dot2c_f32_bf16_e32 v176, v132, v154
	v_dot2c_f32_bf16_e32 v177, v133, v155
	v_dot2c_f32_bf16_e32 v178, v134, v158
	v_dot2c_f32_bf16_e32 v179, v135, v159
	v_dot2c_f32_bf16_e32 v176, v136, v162
	v_dot2c_f32_bf16_e32 v177, v137, v163
	v_dot2c_f32_bf16_e32 v178, v138, v166
	v_dot2c_f32_bf16_e32 v179, v139, v167
	v_dot2c_f32_bf16_e32 v176, v140, v170
	v_dot2c_f32_bf16_e32 v177, v141, v171
	v_dot2c_f32_bf16_e32 v178, v142, v174
	v_dot2c_f32_bf16_e32 v179, v143, v175
	s_waitcnt vmcnt(19)
	v_cvt_scalef32_pk32_bf16_fp6 v[0:15], v[100:105], 1.0
	v_cvt_scalef32_pk32_bf16_fp6 v[128:143], v[106:111], 1.0
	v_dot2_f32_bf16 v180, v0, v144, 0
	v_dot2_f32_bf16 v181, v1, v145, 0
	v_dot2_f32_bf16 v182, v2, v148, 0
	v_dot2_f32_bf16 v183, v3, v149, 0
	v_dot2c_f32_bf16_e32 v180, v4, v152
	v_dot2c_f32_bf16_e32 v181, v5, v153
	v_dot2c_f32_bf16_e32 v182, v6, v156
	v_dot2c_f32_bf16_e32 v183, v7, v157
	v_add_f32_e32 v192, v176, v177
	v_add_f32_e32 v206, v178, v179
	v_add_f32_e32 v192, v192, v206
	s_nop 1
	v_add_f32_dpp v192, v192, v192 quad_perm:[1,0,3,2] row_mask:0xf bank_mask:0xf
	s_nop 1
	v_add_f32_dpp v192, v192, v192 quad_perm:[2,3,0,1] row_mask:0xf bank_mask:0xf
	v_cndmask_b32_e64 v119, v119, v192, s[100:101]
	v_dot2c_f32_bf16_e32 v180, v8, v160
	v_dot2c_f32_bf16_e32 v181, v9, v161
	v_dot2c_f32_bf16_e32 v182, v10, v164
	v_dot2c_f32_bf16_e32 v183, v11, v165
	v_dot2c_f32_bf16_e32 v180, v12, v168
	v_dot2c_f32_bf16_e32 v181, v13, v169
	v_dot2c_f32_bf16_e32 v182, v14, v172
	v_dot2c_f32_bf16_e32 v183, v15, v173
	v_dot2c_f32_bf16_e32 v180, v128, v146
	v_dot2c_f32_bf16_e32 v181, v129, v147
	v_dot2c_f32_bf16_e32 v182, v130, v150
	v_dot2c_f32_bf16_e32 v183, v131, v151
	v_dot2c_f32_bf16_e32 v180, v132, v154
	v_dot2c_f32_bf16_e32 v181, v133, v155
	v_dot2c_f32_bf16_e32 v182, v134, v158
	v_dot2c_f32_bf16_e32 v183, v135, v159
	v_dot2c_f32_bf16_e32 v180, v136, v162
	v_dot2c_f32_bf16_e32 v181, v137, v163
	v_dot2c_f32_bf16_e32 v182, v138, v166
	v_dot2c_f32_bf16_e32 v183, v139, v167
	v_dot2c_f32_bf16_e32 v180, v140, v170
	v_dot2c_f32_bf16_e32 v181, v141, v171
	v_dot2c_f32_bf16_e32 v182, v142, v174
	v_dot2c_f32_bf16_e32 v183, v143, v175
	v_mad_u32_u24 v190, v190, s64, v197
	v_mad_u32_u24 v191, v191, s64, v197
	global_load_dwordx4 v[88:91], v190, s[4:5]
	global_load_dwordx4 v[92:95], v190, s[4:5] offset:16
	global_load_dwordx4 v[96:99], v190, s[4:5] offset:32
	global_load_dwordx4 v[100:103], v191, s[4:5]
	global_load_dwordx4 v[104:107], v191, s[4:5] offset:16
	global_load_dwordx4 v[108:111], v191, s[4:5] offset:32
	s_add_u32 s16, s16, 1
	s_and_b32 s16, s16, 63
	s_add_u32 s18, s16, 1
	s_and_b32 s18, s18, 63
	s_and_b32 s19, s18, 15
	s_lshr_b32 s50, s18, 4
	s_lshl_b32 s51, s19, 9
	s_mul_i32 s17, s19, s65
	s_lshl_b32 s18, s50, 6
	s_add_u32 s17, s17, s18
	s_add_u32 s12, s8, s17
	s_addc_u32 s13, s9, 0
	s_mul_i32 s17, s50, 0x300000
	s_add_u32 s4, s26, 0x1800000
	s_addc_u32 s5, s27, 0
	s_add_u32 s4, s4, s17
	s_addc_u32 s5, s5, 0
	v_add_u32_e32 v202, s51, v194
	ds_read2_b32 v[184:185], v202 offset0:0 offset1:16
	ds_read2_b32 v[186:187], v202 offset0:32 offset1:48
	ds_read2_b32 v[188:189], v202 offset0:64 offset1:80
	ds_read2_b32 v[190:191], v202 offset0:96 offset1:112
	v_add_f32_e32 v192, v180, v181
	v_add_f32_e32 v206, v182, v183
	v_add_f32_e32 v192, v192, v206
	s_nop 1
	v_add_f32_dpp v192, v192, v192 quad_perm:[1,0,3,2] row_mask:0xf bank_mask:0xf
	s_nop 1
	v_add_f32_dpp v192, v192, v192 quad_perm:[2,3,0,1] row_mask:0xf bank_mask:0xf
	v_cndmask_b32_e64 v119, v119, v192, s[98:99]
	ds_add_f32 v204, v119 offset:256
	s_cmp_lg_u32 s16, 0
	s_cbranch_scc1 .Lgu0_loop
	s_waitcnt vmcnt(0) lgkmcnt(0)
	s_add_u32 s4, s26, 0x1400000
	s_addc_u32 s5, s27, 0
	s_add_u32 s8, s26, 0x1410000
	s_addc_u32 s9, s27, 0
	s_lshl_b32 s17, s69, 9
	s_add_u32 s10, s26, 0xe800000
	s_addc_u32 s11, s27, 0
	s_add_u32 s10, s10, s17
	s_addc_u32 s11, s11, 0
	s_add_u32 s12, s26, 0xf800000
	s_addc_u32 s13, s27, 0
	s_add_u32 s12, s12, s17
	s_addc_u32 s13, s13, 0
	s_lshl_b32 s18, s92, 11
	s_mov_b32 s16, 0x378e98ab
	s_mov_b32 s19, 0x3b7cd369
	s_mov_b32 s50, 0xbcc618b2
	s_mov_b32 s51, 0x3dda74e4
	s_mov_b32 s64, 0x3f228afd
	s_mov_b32 s65, 0x3e03c728
	s_mov_b32 s98, 0xbfb8aa3b
	s_mov_b32 s70, 0x42ce8ed0
	s_mov_b32 s71, 0xc2b17218
	s_mov_b32 s14, 0x7fffffff
	v_mov_b32_e32 v176, 0x3ba10414
	v_mov_b32_e32 v177, 0xb9c68948
	v_mov_b32_e32 v178, 0x7f800000
	ds_read2st64_b32 v[16:17], v199 offset0:0 offset1:1
	ds_read2st64_b32 v[80:81], v200 offset0:0 offset1:1
	ds_read2st64_b32 v[18:19], v199 offset0:2 offset1:3
	ds_read2st64_b32 v[82:83], v200 offset0:2 offset1:3
	ds_read2st64_b32 v[20:21], v199 offset0:4 offset1:5
	ds_read2st64_b32 v[84:85], v200 offset0:4 offset1:5
	ds_read2st64_b32 v[22:23], v199 offset0:6 offset1:7
	ds_read2st64_b32 v[86:87], v200 offset0:6 offset1:7
	ds_read2st64_b32 v[24:25], v199 offset0:8 offset1:9
	ds_read2st64_b32 v[88:89], v200 offset0:8 offset1:9
	ds_read2st64_b32 v[26:27], v199 offset0:10 offset1:11
	ds_read2st64_b32 v[90:91], v200 offset0:10 offset1:11
	ds_read2st64_b32 v[28:29], v199 offset0:12 offset1:13
	ds_read2st64_b32 v[92:93], v200 offset0:12 offset1:13
	ds_read2st64_b32 v[30:31], v199 offset0:14 offset1:15
	ds_read2st64_b32 v[94:95], v200 offset0:14 offset1:15
	s_waitcnt lgkmcnt(0)
	v_lshlrev_b32_e32 v16, 2, v16
	v_lshlrev_b32_e32 v17, 2, v17
	v_lshlrev_b32_e32 v18, 2, v18
	v_lshlrev_b32_e32 v19, 2, v19
	v_lshlrev_b32_e32 v20, 2, v20
	v_lshlrev_b32_e32 v21, 2, v21
	v_lshlrev_b32_e32 v22, 2, v22
	v_lshlrev_b32_e32 v23, 2, v23
	v_lshlrev_b32_e32 v24, 2, v24
	v_lshlrev_b32_e32 v25, 2, v25
	v_lshlrev_b32_e32 v26, 2, v26
	v_lshlrev_b32_e32 v27, 2, v27
	v_lshlrev_b32_e32 v28, 2, v28
	v_lshlrev_b32_e32 v29, 2, v29
	v_lshlrev_b32_e32 v30, 2, v30
	v_lshlrev_b32_e32 v31, 2, v31
	global_load_dword v32, v193, s[10:11]
	global_load_dword v33, v193, s[10:11] offset:256
	global_load_dword v34, v16, s[4:5]
	global_load_dword v35, v17, s[4:5]
	global_load_dword v36, v16, s[8:9]
	global_load_dword v37, v17, s[8:9]
	s_add_u32 s10, s10, s18
	s_addc_u32 s11, s11, 0
	global_load_dword v38, v193, s[10:11]
	global_load_dword v39, v193, s[10:11] offset:256
	global_load_dword v40, v18, s[4:5]
	global_load_dword v41, v19, s[4:5]
	global_load_dword v42, v18, s[8:9]
	global_load_dword v43, v19, s[8:9]
	s_add_u32 s10, s10, s18
	s_addc_u32 s11, s11, 0
	global_load_dword v44, v193, s[10:11]
	global_load_dword v45, v193, s[10:11] offset:256
	global_load_dword v46, v20, s[4:5]
	global_load_dword v47, v21, s[4:5]
	global_load_dword v48, v20, s[8:9]
	global_load_dword v49, v21, s[8:9]
	s_add_u32 s10, s10, s18
	s_addc_u32 s11, s11, 0
	global_load_dword v50, v193, s[10:11]
	global_load_dword v51, v193, s[10:11] offset:256
	global_load_dword v52, v22, s[4:5]
	global_load_dword v53, v23, s[4:5]
	global_load_dword v54, v22, s[8:9]
	global_load_dword v55, v23, s[8:9]
	s_add_u32 s10, s10, s18
	s_addc_u32 s11, s11, 0
	global_load_dword v56, v193, s[10:11]
	global_load_dword v57, v193, s[10:11] offset:256
	global_load_dword v58, v24, s[4:5]
	global_load_dword v59, v25, s[4:5]
	global_load_dword v60, v24, s[8:9]
	global_load_dword v61, v25, s[8:9]
	s_add_u32 s10, s10, s18
	s_addc_u32 s11, s11, 0
	global_load_dword v62, v193, s[10:11]
	global_load_dword v63, v193, s[10:11] offset:256
	global_load_dword v64, v26, s[4:5]
	global_load_dword v65, v27, s[4:5]
	global_load_dword v66, v26, s[8:9]
	global_load_dword v67, v27, s[8:9]
	s_add_u32 s10, s10, s18
	s_addc_u32 s11, s11, 0
	global_load_dword v68, v193, s[10:11]
	global_load_dword v69, v193, s[10:11] offset:256
	global_load_dword v70, v28, s[4:5]
	global_load_dword v71, v29, s[4:5]
	global_load_dword v72, v28, s[8:9]
	global_load_dword v73, v29, s[8:9]
	s_add_u32 s10, s10, s18
	s_addc_u32 s11, s11, 0
	global_load_dword v74, v193, s[10:11]
	global_load_dword v75, v193, s[10:11] offset:256
	global_load_dword v76, v30, s[4:5]
	global_load_dword v77, v31, s[4:5]
	global_load_dword v78, v30, s[8:9]
	global_load_dword v79, v31, s[8:9]
	s_add_u32 s10, s10, s18
	s_addc_u32 s11, s11, 0
	s_waitcnt vmcnt(0)
	v_mul_f32_e32 v80, v34, v80
	v_mul_f32_e32 v180, 0x3f3504f3, v80
	v_fma_f32 v182, |v180|, s16, v177
	v_fma_f32 v182, |v180|, v182, s19
	v_fma_f32 v182, |v180|, v182, s50
	v_fma_f32 v182, |v180|, v182, s51
	v_fma_f32 v182, |v180|, v182, s64
	v_fma_f32 v182, |v180|, v182, s65
	v_fma_f32 v182, |v180|, v182, |v180|
	v_mul_f32_e32 v184, 0xbfb8aa3b, v182
	v_fma_f32 v185, v182, s98, -v184
	v_rndne_f32_e32 v186, v184
	v_fmac_f32_e32 v185, 0xb2a5705f, v182
	v_sub_f32_e32 v184, v184, v186
	v_add_f32_e32 v184, v184, v185
	v_cvt_i32_f32_e32 v185, v186
	v_exp_f32_e32 v184, v184
	v_cmp_nlt_f32_e32 vcc, s70, v182
	v_ldexp_f32 v184, v184, v185
	s_nop 0
	v_cndmask_b32_e32 v184, 0, v184, vcc
	v_cmp_ngt_f32_e32 vcc, s71, v182
	s_nop 1
	v_cndmask_b32_e32 v184, v178, v184, vcc
	v_sub_f32_e32 v184, 1.0, v184
	v_mul_f32_e32 v183, v180, v180
	v_fmamk_f32 v185, v183, 0xba1345e1, v176
	v_fmaak_f32 v185, v183, v185, 0xbcdac9b8
	v_fmaak_f32 v185, v183, v185, 0x3de703be
	v_fmaak_f32 v185, v183, v185, 0xbec09330
	v_fmaak_f32 v183, v183, v185, 0x3e0375d0
	v_fma_f32 v183, |v180|, v183, |v180|
	v_cmp_nlt_f32_e64 vcc, |v180|, 1.0
	s_nop 1
	v_cndmask_b32_e32 v184, v183, v184, vcc
	v_bfi_b32 v184, s14, v184, v180
	v_add_f32_e32 v184, 1.0, v184
	v_mul_f32_e32 v80, 0.5, v80
	v_mul_f32_e32 v32, v32, v36
	v_mul_f32_e32 v80, v80, v184
	v_mul_f32_e32 v80, v32, v80
	v_mul_f32_e32 v81, v35, v81
	v_mul_f32_e32 v180, 0x3f3504f3, v81
	v_fma_f32 v182, |v180|, s16, v177
	v_fma_f32 v182, |v180|, v182, s19
	v_fma_f32 v182, |v180|, v182, s50
	v_fma_f32 v182, |v180|, v182, s51
	v_fma_f32 v182, |v180|, v182, s64
	v_fma_f32 v182, |v180|, v182, s65
	v_fma_f32 v182, |v180|, v182, |v180|
	v_mul_f32_e32 v184, 0xbfb8aa3b, v182
	v_fma_f32 v185, v182, s98, -v184
	v_rndne_f32_e32 v186, v184
	v_fmac_f32_e32 v185, 0xb2a5705f, v182
	v_sub_f32_e32 v184, v184, v186
	v_add_f32_e32 v184, v184, v185
	v_cvt_i32_f32_e32 v185, v186
	v_exp_f32_e32 v184, v184
	v_cmp_nlt_f32_e32 vcc, s70, v182
	v_ldexp_f32 v184, v184, v185
	s_nop 0
	v_cndmask_b32_e32 v184, 0, v184, vcc
	v_cmp_ngt_f32_e32 vcc, s71, v182
	s_nop 1
	v_cndmask_b32_e32 v184, v178, v184, vcc
	v_sub_f32_e32 v184, 1.0, v184
	v_mul_f32_e32 v183, v180, v180
	v_fmamk_f32 v185, v183, 0xba1345e1, v176
	v_fmaak_f32 v185, v183, v185, 0xbcdac9b8
	v_fmaak_f32 v185, v183, v185, 0x3de703be
	v_fmaak_f32 v185, v183, v185, 0xbec09330
	v_fmaak_f32 v183, v183, v185, 0x3e0375d0
	v_fma_f32 v183, |v180|, v183, |v180|
	v_cmp_nlt_f32_e64 vcc, |v180|, 1.0
	s_nop 1
	v_cndmask_b32_e32 v184, v183, v184, vcc
	v_bfi_b32 v184, s14, v184, v180
	v_add_f32_e32 v184, 1.0, v184
	v_mul_f32_e32 v81, 0.5, v81
	v_mul_f32_e32 v33, v33, v37
	v_mul_f32_e32 v81, v81, v184
	v_mul_f32_e32 v81, v33, v81
	global_store_dword v193, v80, s[12:13]
	global_store_dword v193, v81, s[12:13] offset:256
	s_add_u32 s12, s12, s18
	s_addc_u32 s13, s13, 0
	v_mul_f32_e32 v82, v40, v82
	v_mul_f32_e32 v180, 0x3f3504f3, v82
	v_fma_f32 v182, |v180|, s16, v177
	v_fma_f32 v182, |v180|, v182, s19
	v_fma_f32 v182, |v180|, v182, s50
	v_fma_f32 v182, |v180|, v182, s51
	v_fma_f32 v182, |v180|, v182, s64
	v_fma_f32 v182, |v180|, v182, s65
	v_fma_f32 v182, |v180|, v182, |v180|
	v_mul_f32_e32 v184, 0xbfb8aa3b, v182
	v_fma_f32 v185, v182, s98, -v184
	v_rndne_f32_e32 v186, v184
	v_fmac_f32_e32 v185, 0xb2a5705f, v182
	v_sub_f32_e32 v184, v184, v186
	v_add_f32_e32 v184, v184, v185
	v_cvt_i32_f32_e32 v185, v186
	v_exp_f32_e32 v184, v184
	v_cmp_nlt_f32_e32 vcc, s70, v182
	v_ldexp_f32 v184, v184, v185
	s_nop 0
	v_cndmask_b32_e32 v184, 0, v184, vcc
	v_cmp_ngt_f32_e32 vcc, s71, v182
	s_nop 1
	v_cndmask_b32_e32 v184, v178, v184, vcc
	v_sub_f32_e32 v184, 1.0, v184
	v_mul_f32_e32 v183, v180, v180
	v_fmamk_f32 v185, v183, 0xba1345e1, v176
	v_fmaak_f32 v185, v183, v185, 0xbcdac9b8
	v_fmaak_f32 v185, v183, v185, 0x3de703be
	v_fmaak_f32 v185, v183, v185, 0xbec09330
	v_fmaak_f32 v183, v183, v185, 0x3e0375d0
	v_fma_f32 v183, |v180|, v183, |v180|
	v_cmp_nlt_f32_e64 vcc, |v180|, 1.0
	s_nop 1
	v_cndmask_b32_e32 v184, v183, v184, vcc
	v_bfi_b32 v184, s14, v184, v180
	v_add_f32_e32 v184, 1.0, v184
	v_mul_f32_e32 v82, 0.5, v82
	v_mul_f32_e32 v38, v38, v42
	v_mul_f32_e32 v82, v82, v184
	v_mul_f32_e32 v82, v38, v82
	v_mul_f32_e32 v83, v41, v83
	v_mul_f32_e32 v180, 0x3f3504f3, v83
	v_fma_f32 v182, |v180|, s16, v177
	v_fma_f32 v182, |v180|, v182, s19
	v_fma_f32 v182, |v180|, v182, s50
	v_fma_f32 v182, |v180|, v182, s51
	v_fma_f32 v182, |v180|, v182, s64
	v_fma_f32 v182, |v180|, v182, s65
	v_fma_f32 v182, |v180|, v182, |v180|
	v_mul_f32_e32 v184, 0xbfb8aa3b, v182
	v_fma_f32 v185, v182, s98, -v184
	v_rndne_f32_e32 v186, v184
	v_fmac_f32_e32 v185, 0xb2a5705f, v182
	v_sub_f32_e32 v184, v184, v186
	v_add_f32_e32 v184, v184, v185
	v_cvt_i32_f32_e32 v185, v186
	v_exp_f32_e32 v184, v184
	v_cmp_nlt_f32_e32 vcc, s70, v182
	v_ldexp_f32 v184, v184, v185
	s_nop 0
	v_cndmask_b32_e32 v184, 0, v184, vcc
	v_cmp_ngt_f32_e32 vcc, s71, v182
	s_nop 1
	v_cndmask_b32_e32 v184, v178, v184, vcc
	v_sub_f32_e32 v184, 1.0, v184
	v_mul_f32_e32 v183, v180, v180
	v_fmamk_f32 v185, v183, 0xba1345e1, v176
	v_fmaak_f32 v185, v183, v185, 0xbcdac9b8
	v_fmaak_f32 v185, v183, v185, 0x3de703be
	v_fmaak_f32 v185, v183, v185, 0xbec09330
	v_fmaak_f32 v183, v183, v185, 0x3e0375d0
	v_fma_f32 v183, |v180|, v183, |v180|
	v_cmp_nlt_f32_e64 vcc, |v180|, 1.0
	s_nop 1
	v_cndmask_b32_e32 v184, v183, v184, vcc
	v_bfi_b32 v184, s14, v184, v180
	v_add_f32_e32 v184, 1.0, v184
	v_mul_f32_e32 v83, 0.5, v83
	v_mul_f32_e32 v39, v39, v43
	v_mul_f32_e32 v83, v83, v184
	v_mul_f32_e32 v83, v39, v83
	global_store_dword v193, v82, s[12:13]
	global_store_dword v193, v83, s[12:13] offset:256
	s_add_u32 s12, s12, s18
	s_addc_u32 s13, s13, 0
	v_mul_f32_e32 v84, v46, v84
	v_mul_f32_e32 v180, 0x3f3504f3, v84
	v_fma_f32 v182, |v180|, s16, v177
	v_fma_f32 v182, |v180|, v182, s19
	v_fma_f32 v182, |v180|, v182, s50
	v_fma_f32 v182, |v180|, v182, s51
	v_fma_f32 v182, |v180|, v182, s64
	v_fma_f32 v182, |v180|, v182, s65
	v_fma_f32 v182, |v180|, v182, |v180|
	v_mul_f32_e32 v184, 0xbfb8aa3b, v182
	v_fma_f32 v185, v182, s98, -v184
	v_rndne_f32_e32 v186, v184
	v_fmac_f32_e32 v185, 0xb2a5705f, v182
	v_sub_f32_e32 v184, v184, v186
	v_add_f32_e32 v184, v184, v185
	v_cvt_i32_f32_e32 v185, v186
	v_exp_f32_e32 v184, v184
	v_cmp_nlt_f32_e32 vcc, s70, v182
	v_ldexp_f32 v184, v184, v185
	s_nop 0
	v_cndmask_b32_e32 v184, 0, v184, vcc
	v_cmp_ngt_f32_e32 vcc, s71, v182
	s_nop 1
	v_cndmask_b32_e32 v184, v178, v184, vcc
	v_sub_f32_e32 v184, 1.0, v184
	v_mul_f32_e32 v183, v180, v180
	v_fmamk_f32 v185, v183, 0xba1345e1, v176
	v_fmaak_f32 v185, v183, v185, 0xbcdac9b8
	v_fmaak_f32 v185, v183, v185, 0x3de703be
	v_fmaak_f32 v185, v183, v185, 0xbec09330
	v_fmaak_f32 v183, v183, v185, 0x3e0375d0
	v_fma_f32 v183, |v180|, v183, |v180|
	v_cmp_nlt_f32_e64 vcc, |v180|, 1.0
	s_nop 1
	v_cndmask_b32_e32 v184, v183, v184, vcc
	v_bfi_b32 v184, s14, v184, v180
	v_add_f32_e32 v184, 1.0, v184
	v_mul_f32_e32 v84, 0.5, v84
	v_mul_f32_e32 v44, v44, v48
	v_mul_f32_e32 v84, v84, v184
	v_mul_f32_e32 v84, v44, v84
	v_mul_f32_e32 v85, v47, v85
	v_mul_f32_e32 v180, 0x3f3504f3, v85
	v_fma_f32 v182, |v180|, s16, v177
	v_fma_f32 v182, |v180|, v182, s19
	v_fma_f32 v182, |v180|, v182, s50
	v_fma_f32 v182, |v180|, v182, s51
	v_fma_f32 v182, |v180|, v182, s64
	v_fma_f32 v182, |v180|, v182, s65
	v_fma_f32 v182, |v180|, v182, |v180|
	v_mul_f32_e32 v184, 0xbfb8aa3b, v182
	v_fma_f32 v185, v182, s98, -v184
	v_rndne_f32_e32 v186, v184
	v_fmac_f32_e32 v185, 0xb2a5705f, v182
	v_sub_f32_e32 v184, v184, v186
	v_add_f32_e32 v184, v184, v185
	v_cvt_i32_f32_e32 v185, v186
	v_exp_f32_e32 v184, v184
	v_cmp_nlt_f32_e32 vcc, s70, v182
	v_ldexp_f32 v184, v184, v185
	s_nop 0
	v_cndmask_b32_e32 v184, 0, v184, vcc
	v_cmp_ngt_f32_e32 vcc, s71, v182
	s_nop 1
	v_cndmask_b32_e32 v184, v178, v184, vcc
	v_sub_f32_e32 v184, 1.0, v184
	v_mul_f32_e32 v183, v180, v180
	v_fmamk_f32 v185, v183, 0xba1345e1, v176
	v_fmaak_f32 v185, v183, v185, 0xbcdac9b8
	v_fmaak_f32 v185, v183, v185, 0x3de703be
	v_fmaak_f32 v185, v183, v185, 0xbec09330
	v_fmaak_f32 v183, v183, v185, 0x3e0375d0
	v_fma_f32 v183, |v180|, v183, |v180|
	v_cmp_nlt_f32_e64 vcc, |v180|, 1.0
	s_nop 1
	v_cndmask_b32_e32 v184, v183, v184, vcc
	v_bfi_b32 v184, s14, v184, v180
	v_add_f32_e32 v184, 1.0, v184
	v_mul_f32_e32 v85, 0.5, v85
	v_mul_f32_e32 v45, v45, v49
	v_mul_f32_e32 v85, v85, v184
	v_mul_f32_e32 v85, v45, v85
	global_store_dword v193, v84, s[12:13]
	global_store_dword v193, v85, s[12:13] offset:256
	s_add_u32 s12, s12, s18
	s_addc_u32 s13, s13, 0
	v_mul_f32_e32 v86, v52, v86
	v_mul_f32_e32 v180, 0x3f3504f3, v86
	v_fma_f32 v182, |v180|, s16, v177
	v_fma_f32 v182, |v180|, v182, s19
	v_fma_f32 v182, |v180|, v182, s50
	v_fma_f32 v182, |v180|, v182, s51
	v_fma_f32 v182, |v180|, v182, s64
	v_fma_f32 v182, |v180|, v182, s65
	v_fma_f32 v182, |v180|, v182, |v180|
	v_mul_f32_e32 v184, 0xbfb8aa3b, v182
	v_fma_f32 v185, v182, s98, -v184
	v_rndne_f32_e32 v186, v184
	v_fmac_f32_e32 v185, 0xb2a5705f, v182
	v_sub_f32_e32 v184, v184, v186
	v_add_f32_e32 v184, v184, v185
	v_cvt_i32_f32_e32 v185, v186
	v_exp_f32_e32 v184, v184
	v_cmp_nlt_f32_e32 vcc, s70, v182
	v_ldexp_f32 v184, v184, v185
	s_nop 0
	v_cndmask_b32_e32 v184, 0, v184, vcc
	v_cmp_ngt_f32_e32 vcc, s71, v182
	s_nop 1
	v_cndmask_b32_e32 v184, v178, v184, vcc
	v_sub_f32_e32 v184, 1.0, v184
	v_mul_f32_e32 v183, v180, v180
	v_fmamk_f32 v185, v183, 0xba1345e1, v176
	v_fmaak_f32 v185, v183, v185, 0xbcdac9b8
	v_fmaak_f32 v185, v183, v185, 0x3de703be
	v_fmaak_f32 v185, v183, v185, 0xbec09330
	v_fmaak_f32 v183, v183, v185, 0x3e0375d0
	v_fma_f32 v183, |v180|, v183, |v180|
	v_cmp_nlt_f32_e64 vcc, |v180|, 1.0
	s_nop 1
	v_cndmask_b32_e32 v184, v183, v184, vcc
	v_bfi_b32 v184, s14, v184, v180
	v_add_f32_e32 v184, 1.0, v184
	v_mul_f32_e32 v86, 0.5, v86
	v_mul_f32_e32 v50, v50, v54
	v_mul_f32_e32 v86, v86, v184
	v_mul_f32_e32 v86, v50, v86
	v_mul_f32_e32 v87, v53, v87
	v_mul_f32_e32 v180, 0x3f3504f3, v87
	v_fma_f32 v182, |v180|, s16, v177
	v_fma_f32 v182, |v180|, v182, s19
	v_fma_f32 v182, |v180|, v182, s50
	v_fma_f32 v182, |v180|, v182, s51
	v_fma_f32 v182, |v180|, v182, s64
	v_fma_f32 v182, |v180|, v182, s65
	v_fma_f32 v182, |v180|, v182, |v180|
	v_mul_f32_e32 v184, 0xbfb8aa3b, v182
	v_fma_f32 v185, v182, s98, -v184
	v_rndne_f32_e32 v186, v184
	v_fmac_f32_e32 v185, 0xb2a5705f, v182
	v_sub_f32_e32 v184, v184, v186
	v_add_f32_e32 v184, v184, v185
	v_cvt_i32_f32_e32 v185, v186
	v_exp_f32_e32 v184, v184
	v_cmp_nlt_f32_e32 vcc, s70, v182
	v_ldexp_f32 v184, v184, v185
	s_nop 0
	v_cndmask_b32_e32 v184, 0, v184, vcc
	v_cmp_ngt_f32_e32 vcc, s71, v182
	s_nop 1
	v_cndmask_b32_e32 v184, v178, v184, vcc
	v_sub_f32_e32 v184, 1.0, v184
	v_mul_f32_e32 v183, v180, v180
	v_fmamk_f32 v185, v183, 0xba1345e1, v176
	v_fmaak_f32 v185, v183, v185, 0xbcdac9b8
	v_fmaak_f32 v185, v183, v185, 0x3de703be
	v_fmaak_f32 v185, v183, v185, 0xbec09330
	v_fmaak_f32 v183, v183, v185, 0x3e0375d0
	v_fma_f32 v183, |v180|, v183, |v180|
	v_cmp_nlt_f32_e64 vcc, |v180|, 1.0
	s_nop 1
	v_cndmask_b32_e32 v184, v183, v184, vcc
	v_bfi_b32 v184, s14, v184, v180
	v_add_f32_e32 v184, 1.0, v184
	v_mul_f32_e32 v87, 0.5, v87
	v_mul_f32_e32 v51, v51, v55
	v_mul_f32_e32 v87, v87, v184
	v_mul_f32_e32 v87, v51, v87
	global_store_dword v193, v86, s[12:13]
	global_store_dword v193, v87, s[12:13] offset:256
	s_add_u32 s12, s12, s18
	s_addc_u32 s13, s13, 0
	v_mul_f32_e32 v88, v58, v88
	v_mul_f32_e32 v180, 0x3f3504f3, v88
	v_fma_f32 v182, |v180|, s16, v177
	v_fma_f32 v182, |v180|, v182, s19
	v_fma_f32 v182, |v180|, v182, s50
	v_fma_f32 v182, |v180|, v182, s51
	v_fma_f32 v182, |v180|, v182, s64
	v_fma_f32 v182, |v180|, v182, s65
	v_fma_f32 v182, |v180|, v182, |v180|
	v_mul_f32_e32 v184, 0xbfb8aa3b, v182
	v_fma_f32 v185, v182, s98, -v184
	v_rndne_f32_e32 v186, v184
	v_fmac_f32_e32 v185, 0xb2a5705f, v182
	v_sub_f32_e32 v184, v184, v186
	v_add_f32_e32 v184, v184, v185
	v_cvt_i32_f32_e32 v185, v186
	v_exp_f32_e32 v184, v184
	v_cmp_nlt_f32_e32 vcc, s70, v182
	v_ldexp_f32 v184, v184, v185
	s_nop 0
	v_cndmask_b32_e32 v184, 0, v184, vcc
	v_cmp_ngt_f32_e32 vcc, s71, v182
	s_nop 1
	v_cndmask_b32_e32 v184, v178, v184, vcc
	v_sub_f32_e32 v184, 1.0, v184
	v_mul_f32_e32 v183, v180, v180
	v_fmamk_f32 v185, v183, 0xba1345e1, v176
	v_fmaak_f32 v185, v183, v185, 0xbcdac9b8
	v_fmaak_f32 v185, v183, v185, 0x3de703be
	v_fmaak_f32 v185, v183, v185, 0xbec09330
	v_fmaak_f32 v183, v183, v185, 0x3e0375d0
	v_fma_f32 v183, |v180|, v183, |v180|
	v_cmp_nlt_f32_e64 vcc, |v180|, 1.0
	s_nop 1
	v_cndmask_b32_e32 v184, v183, v184, vcc
	v_bfi_b32 v184, s14, v184, v180
	v_add_f32_e32 v184, 1.0, v184
	v_mul_f32_e32 v88, 0.5, v88
	v_mul_f32_e32 v56, v56, v60
	v_mul_f32_e32 v88, v88, v184
	v_mul_f32_e32 v88, v56, v88
	v_mul_f32_e32 v89, v59, v89
	v_mul_f32_e32 v180, 0x3f3504f3, v89
	v_fma_f32 v182, |v180|, s16, v177
	v_fma_f32 v182, |v180|, v182, s19
	v_fma_f32 v182, |v180|, v182, s50
	v_fma_f32 v182, |v180|, v182, s51
	v_fma_f32 v182, |v180|, v182, s64
	v_fma_f32 v182, |v180|, v182, s65
	v_fma_f32 v182, |v180|, v182, |v180|
	v_mul_f32_e32 v184, 0xbfb8aa3b, v182
	v_fma_f32 v185, v182, s98, -v184
	v_rndne_f32_e32 v186, v184
	v_fmac_f32_e32 v185, 0xb2a5705f, v182
	v_sub_f32_e32 v184, v184, v186
	v_add_f32_e32 v184, v184, v185
	v_cvt_i32_f32_e32 v185, v186
	v_exp_f32_e32 v184, v184
	v_cmp_nlt_f32_e32 vcc, s70, v182
	v_ldexp_f32 v184, v184, v185
	s_nop 0
	v_cndmask_b32_e32 v184, 0, v184, vcc
	v_cmp_ngt_f32_e32 vcc, s71, v182
	s_nop 1
	v_cndmask_b32_e32 v184, v178, v184, vcc
	v_sub_f32_e32 v184, 1.0, v184
	v_mul_f32_e32 v183, v180, v180
	v_fmamk_f32 v185, v183, 0xba1345e1, v176
	v_fmaak_f32 v185, v183, v185, 0xbcdac9b8
	v_fmaak_f32 v185, v183, v185, 0x3de703be
	v_fmaak_f32 v185, v183, v185, 0xbec09330
	v_fmaak_f32 v183, v183, v185, 0x3e0375d0
	v_fma_f32 v183, |v180|, v183, |v180|
	v_cmp_nlt_f32_e64 vcc, |v180|, 1.0
	s_nop 1
	v_cndmask_b32_e32 v184, v183, v184, vcc
	v_bfi_b32 v184, s14, v184, v180
	v_add_f32_e32 v184, 1.0, v184
	v_mul_f32_e32 v89, 0.5, v89
	v_mul_f32_e32 v57, v57, v61
	v_mul_f32_e32 v89, v89, v184
	v_mul_f32_e32 v89, v57, v89
	global_store_dword v193, v88, s[12:13]
	global_store_dword v193, v89, s[12:13] offset:256
	s_add_u32 s12, s12, s18
	s_addc_u32 s13, s13, 0
	v_mul_f32_e32 v90, v64, v90
	v_mul_f32_e32 v180, 0x3f3504f3, v90
	v_fma_f32 v182, |v180|, s16, v177
	v_fma_f32 v182, |v180|, v182, s19
	v_fma_f32 v182, |v180|, v182, s50
	v_fma_f32 v182, |v180|, v182, s51
	v_fma_f32 v182, |v180|, v182, s64
	v_fma_f32 v182, |v180|, v182, s65
	v_fma_f32 v182, |v180|, v182, |v180|
	v_mul_f32_e32 v184, 0xbfb8aa3b, v182
	v_fma_f32 v185, v182, s98, -v184
	v_rndne_f32_e32 v186, v184
	v_fmac_f32_e32 v185, 0xb2a5705f, v182
	v_sub_f32_e32 v184, v184, v186
	v_add_f32_e32 v184, v184, v185
	v_cvt_i32_f32_e32 v185, v186
	v_exp_f32_e32 v184, v184
	v_cmp_nlt_f32_e32 vcc, s70, v182
	v_ldexp_f32 v184, v184, v185
	s_nop 0
	v_cndmask_b32_e32 v184, 0, v184, vcc
	v_cmp_ngt_f32_e32 vcc, s71, v182
	s_nop 1
	v_cndmask_b32_e32 v184, v178, v184, vcc
	v_sub_f32_e32 v184, 1.0, v184
	v_mul_f32_e32 v183, v180, v180
	v_fmamk_f32 v185, v183, 0xba1345e1, v176
	v_fmaak_f32 v185, v183, v185, 0xbcdac9b8
	v_fmaak_f32 v185, v183, v185, 0x3de703be
	v_fmaak_f32 v185, v183, v185, 0xbec09330
	v_fmaak_f32 v183, v183, v185, 0x3e0375d0
	v_fma_f32 v183, |v180|, v183, |v180|
	v_cmp_nlt_f32_e64 vcc, |v180|, 1.0
	s_nop 1
	v_cndmask_b32_e32 v184, v183, v184, vcc
	v_bfi_b32 v184, s14, v184, v180
	v_add_f32_e32 v184, 1.0, v184
	v_mul_f32_e32 v90, 0.5, v90
	v_mul_f32_e32 v62, v62, v66
	v_mul_f32_e32 v90, v90, v184
	v_mul_f32_e32 v90, v62, v90
	v_mul_f32_e32 v91, v65, v91
	v_mul_f32_e32 v180, 0x3f3504f3, v91
	v_fma_f32 v182, |v180|, s16, v177
	v_fma_f32 v182, |v180|, v182, s19
	v_fma_f32 v182, |v180|, v182, s50
	v_fma_f32 v182, |v180|, v182, s51
	v_fma_f32 v182, |v180|, v182, s64
	v_fma_f32 v182, |v180|, v182, s65
	v_fma_f32 v182, |v180|, v182, |v180|
	v_mul_f32_e32 v184, 0xbfb8aa3b, v182
	v_fma_f32 v185, v182, s98, -v184
	v_rndne_f32_e32 v186, v184
	v_fmac_f32_e32 v185, 0xb2a5705f, v182
	v_sub_f32_e32 v184, v184, v186
	v_add_f32_e32 v184, v184, v185
	v_cvt_i32_f32_e32 v185, v186
	v_exp_f32_e32 v184, v184
	v_cmp_nlt_f32_e32 vcc, s70, v182
	v_ldexp_f32 v184, v184, v185
	s_nop 0
	v_cndmask_b32_e32 v184, 0, v184, vcc
	v_cmp_ngt_f32_e32 vcc, s71, v182
	s_nop 1
	v_cndmask_b32_e32 v184, v178, v184, vcc
	v_sub_f32_e32 v184, 1.0, v184
	v_mul_f32_e32 v183, v180, v180
	v_fmamk_f32 v185, v183, 0xba1345e1, v176
	v_fmaak_f32 v185, v183, v185, 0xbcdac9b8
	v_fmaak_f32 v185, v183, v185, 0x3de703be
	v_fmaak_f32 v185, v183, v185, 0xbec09330
	v_fmaak_f32 v183, v183, v185, 0x3e0375d0
	v_fma_f32 v183, |v180|, v183, |v180|
	v_cmp_nlt_f32_e64 vcc, |v180|, 1.0
	s_nop 1
	v_cndmask_b32_e32 v184, v183, v184, vcc
	v_bfi_b32 v184, s14, v184, v180
	v_add_f32_e32 v184, 1.0, v184
	v_mul_f32_e32 v91, 0.5, v91
	v_mul_f32_e32 v63, v63, v67
	v_mul_f32_e32 v91, v91, v184
	v_mul_f32_e32 v91, v63, v91
	global_store_dword v193, v90, s[12:13]
	global_store_dword v193, v91, s[12:13] offset:256
	s_add_u32 s12, s12, s18
	s_addc_u32 s13, s13, 0
	v_mul_f32_e32 v92, v70, v92
	v_mul_f32_e32 v180, 0x3f3504f3, v92
	v_fma_f32 v182, |v180|, s16, v177
	v_fma_f32 v182, |v180|, v182, s19
	v_fma_f32 v182, |v180|, v182, s50
	v_fma_f32 v182, |v180|, v182, s51
	v_fma_f32 v182, |v180|, v182, s64
	v_fma_f32 v182, |v180|, v182, s65
	v_fma_f32 v182, |v180|, v182, |v180|
	v_mul_f32_e32 v184, 0xbfb8aa3b, v182
	v_fma_f32 v185, v182, s98, -v184
	v_rndne_f32_e32 v186, v184
	v_fmac_f32_e32 v185, 0xb2a5705f, v182
	v_sub_f32_e32 v184, v184, v186
	v_add_f32_e32 v184, v184, v185
	v_cvt_i32_f32_e32 v185, v186
	v_exp_f32_e32 v184, v184
	v_cmp_nlt_f32_e32 vcc, s70, v182
	v_ldexp_f32 v184, v184, v185
	s_nop 0
	v_cndmask_b32_e32 v184, 0, v184, vcc
	v_cmp_ngt_f32_e32 vcc, s71, v182
	s_nop 1
	v_cndmask_b32_e32 v184, v178, v184, vcc
	v_sub_f32_e32 v184, 1.0, v184
	v_mul_f32_e32 v183, v180, v180
	v_fmamk_f32 v185, v183, 0xba1345e1, v176
	v_fmaak_f32 v185, v183, v185, 0xbcdac9b8
	v_fmaak_f32 v185, v183, v185, 0x3de703be
	v_fmaak_f32 v185, v183, v185, 0xbec09330
	v_fmaak_f32 v183, v183, v185, 0x3e0375d0
	v_fma_f32 v183, |v180|, v183, |v180|
	v_cmp_nlt_f32_e64 vcc, |v180|, 1.0
	s_nop 1
	v_cndmask_b32_e32 v184, v183, v184, vcc
	v_bfi_b32 v184, s14, v184, v180
	v_add_f32_e32 v184, 1.0, v184
	v_mul_f32_e32 v92, 0.5, v92
	v_mul_f32_e32 v68, v68, v72
	v_mul_f32_e32 v92, v92, v184
	v_mul_f32_e32 v92, v68, v92
	v_mul_f32_e32 v93, v71, v93
	v_mul_f32_e32 v180, 0x3f3504f3, v93
	v_fma_f32 v182, |v180|, s16, v177
	v_fma_f32 v182, |v180|, v182, s19
	v_fma_f32 v182, |v180|, v182, s50
	v_fma_f32 v182, |v180|, v182, s51
	v_fma_f32 v182, |v180|, v182, s64
	v_fma_f32 v182, |v180|, v182, s65
	v_fma_f32 v182, |v180|, v182, |v180|
	v_mul_f32_e32 v184, 0xbfb8aa3b, v182
	v_fma_f32 v185, v182, s98, -v184
	v_rndne_f32_e32 v186, v184
	v_fmac_f32_e32 v185, 0xb2a5705f, v182
	v_sub_f32_e32 v184, v184, v186
	v_add_f32_e32 v184, v184, v185
	v_cvt_i32_f32_e32 v185, v186
	v_exp_f32_e32 v184, v184
	v_cmp_nlt_f32_e32 vcc, s70, v182
	v_ldexp_f32 v184, v184, v185
	s_nop 0
	v_cndmask_b32_e32 v184, 0, v184, vcc
	v_cmp_ngt_f32_e32 vcc, s71, v182
	s_nop 1
	v_cndmask_b32_e32 v184, v178, v184, vcc
	v_sub_f32_e32 v184, 1.0, v184
	v_mul_f32_e32 v183, v180, v180
	v_fmamk_f32 v185, v183, 0xba1345e1, v176
	v_fmaak_f32 v185, v183, v185, 0xbcdac9b8
	v_fmaak_f32 v185, v183, v185, 0x3de703be
	v_fmaak_f32 v185, v183, v185, 0xbec09330
	v_fmaak_f32 v183, v183, v185, 0x3e0375d0
	v_fma_f32 v183, |v180|, v183, |v180|
	v_cmp_nlt_f32_e64 vcc, |v180|, 1.0
	s_nop 1
	v_cndmask_b32_e32 v184, v183, v184, vcc
	v_bfi_b32 v184, s14, v184, v180
	v_add_f32_e32 v184, 1.0, v184
	v_mul_f32_e32 v93, 0.5, v93
	v_mul_f32_e32 v69, v69, v73
	v_mul_f32_e32 v93, v93, v184
	v_mul_f32_e32 v93, v69, v93
	global_store_dword v193, v92, s[12:13]
	global_store_dword v193, v93, s[12:13] offset:256
	s_add_u32 s12, s12, s18
	s_addc_u32 s13, s13, 0
	v_mul_f32_e32 v94, v76, v94
	v_mul_f32_e32 v180, 0x3f3504f3, v94
	v_fma_f32 v182, |v180|, s16, v177
	v_fma_f32 v182, |v180|, v182, s19
	v_fma_f32 v182, |v180|, v182, s50
	v_fma_f32 v182, |v180|, v182, s51
	v_fma_f32 v182, |v180|, v182, s64
	v_fma_f32 v182, |v180|, v182, s65
	v_fma_f32 v182, |v180|, v182, |v180|
	v_mul_f32_e32 v184, 0xbfb8aa3b, v182
	v_fma_f32 v185, v182, s98, -v184
	v_rndne_f32_e32 v186, v184
	v_fmac_f32_e32 v185, 0xb2a5705f, v182
	v_sub_f32_e32 v184, v184, v186
	v_add_f32_e32 v184, v184, v185
	v_cvt_i32_f32_e32 v185, v186
	v_exp_f32_e32 v184, v184
	v_cmp_nlt_f32_e32 vcc, s70, v182
	v_ldexp_f32 v184, v184, v185
	s_nop 0
	v_cndmask_b32_e32 v184, 0, v184, vcc
	v_cmp_ngt_f32_e32 vcc, s71, v182
	s_nop 1
	v_cndmask_b32_e32 v184, v178, v184, vcc
	v_sub_f32_e32 v184, 1.0, v184
	v_mul_f32_e32 v183, v180, v180
	v_fmamk_f32 v185, v183, 0xba1345e1, v176
	v_fmaak_f32 v185, v183, v185, 0xbcdac9b8
	v_fmaak_f32 v185, v183, v185, 0x3de703be
	v_fmaak_f32 v185, v183, v185, 0xbec09330
	v_fmaak_f32 v183, v183, v185, 0x3e0375d0
	v_fma_f32 v183, |v180|, v183, |v180|
	v_cmp_nlt_f32_e64 vcc, |v180|, 1.0
	s_nop 1
	v_cndmask_b32_e32 v184, v183, v184, vcc
	v_bfi_b32 v184, s14, v184, v180
	v_add_f32_e32 v184, 1.0, v184
	v_mul_f32_e32 v94, 0.5, v94
	v_mul_f32_e32 v74, v74, v78
	v_mul_f32_e32 v94, v94, v184
	v_mul_f32_e32 v94, v74, v94
	v_mul_f32_e32 v95, v77, v95
	v_mul_f32_e32 v180, 0x3f3504f3, v95
	v_fma_f32 v182, |v180|, s16, v177
	v_fma_f32 v182, |v180|, v182, s19
	v_fma_f32 v182, |v180|, v182, s50
	v_fma_f32 v182, |v180|, v182, s51
	v_fma_f32 v182, |v180|, v182, s64
	v_fma_f32 v182, |v180|, v182, s65
	v_fma_f32 v182, |v180|, v182, |v180|
	v_mul_f32_e32 v184, 0xbfb8aa3b, v182
	v_fma_f32 v185, v182, s98, -v184
	v_rndne_f32_e32 v186, v184
	v_fmac_f32_e32 v185, 0xb2a5705f, v182
	v_sub_f32_e32 v184, v184, v186
	v_add_f32_e32 v184, v184, v185
	v_cvt_i32_f32_e32 v185, v186
	v_exp_f32_e32 v184, v184
	v_cmp_nlt_f32_e32 vcc, s70, v182
	v_ldexp_f32 v184, v184, v185
	s_nop 0
	v_cndmask_b32_e32 v184, 0, v184, vcc
	v_cmp_ngt_f32_e32 vcc, s71, v182
	s_nop 1
	v_cndmask_b32_e32 v184, v178, v184, vcc
	v_sub_f32_e32 v184, 1.0, v184
	v_mul_f32_e32 v183, v180, v180
	v_fmamk_f32 v185, v183, 0xba1345e1, v176
	v_fmaak_f32 v185, v183, v185, 0xbcdac9b8
	v_fmaak_f32 v185, v183, v185, 0x3de703be
	v_fmaak_f32 v185, v183, v185, 0xbec09330
	v_fmaak_f32 v183, v183, v185, 0x3e0375d0
	v_fma_f32 v183, |v180|, v183, |v180|
	v_cmp_nlt_f32_e64 vcc, |v180|, 1.0
	s_nop 1
	v_cndmask_b32_e32 v184, v183, v184, vcc
	v_bfi_b32 v184, s14, v184, v180
	v_add_f32_e32 v184, 1.0, v184
	v_mul_f32_e32 v95, 0.5, v95
	v_mul_f32_e32 v75, v75, v79
	v_mul_f32_e32 v95, v95, v184
	v_mul_f32_e32 v95, v75, v95
	global_store_dword v193, v94, s[12:13]
	global_store_dword v193, v95, s[12:13] offset:256
	s_add_u32 s12, s12, s18
	s_addc_u32 s13, s13, 0
	ds_read2st64_b32 v[16:17], v199 offset0:16 offset1:17
	ds_read2st64_b32 v[80:81], v200 offset0:16 offset1:17
	ds_read2st64_b32 v[18:19], v199 offset0:18 offset1:19
	ds_read2st64_b32 v[82:83], v200 offset0:18 offset1:19
	ds_read2st64_b32 v[20:21], v199 offset0:20 offset1:21
	ds_read2st64_b32 v[84:85], v200 offset0:20 offset1:21
	ds_read2st64_b32 v[22:23], v199 offset0:22 offset1:23
	ds_read2st64_b32 v[86:87], v200 offset0:22 offset1:23
	ds_read2st64_b32 v[24:25], v199 offset0:24 offset1:25
	ds_read2st64_b32 v[88:89], v200 offset0:24 offset1:25
	ds_read2st64_b32 v[26:27], v199 offset0:26 offset1:27
	ds_read2st64_b32 v[90:91], v200 offset0:26 offset1:27
	ds_read2st64_b32 v[28:29], v199 offset0:28 offset1:29
	ds_read2st64_b32 v[92:93], v200 offset0:28 offset1:29
	ds_read2st64_b32 v[30:31], v199 offset0:30 offset1:31
	ds_read2st64_b32 v[94:95], v200 offset0:30 offset1:31
	s_waitcnt lgkmcnt(0)
	v_lshlrev_b32_e32 v16, 2, v16
	v_lshlrev_b32_e32 v17, 2, v17
	v_lshlrev_b32_e32 v18, 2, v18
	v_lshlrev_b32_e32 v19, 2, v19
	v_lshlrev_b32_e32 v20, 2, v20
	v_lshlrev_b32_e32 v21, 2, v21
	v_lshlrev_b32_e32 v22, 2, v22
	v_lshlrev_b32_e32 v23, 2, v23
	v_lshlrev_b32_e32 v24, 2, v24
	v_lshlrev_b32_e32 v25, 2, v25
	v_lshlrev_b32_e32 v26, 2, v26
	v_lshlrev_b32_e32 v27, 2, v27
	v_lshlrev_b32_e32 v28, 2, v28
	v_lshlrev_b32_e32 v29, 2, v29
	v_lshlrev_b32_e32 v30, 2, v30
	v_lshlrev_b32_e32 v31, 2, v31
	global_load_dword v32, v193, s[10:11]
	global_load_dword v33, v193, s[10:11] offset:256
	global_load_dword v34, v16, s[4:5]
	global_load_dword v35, v17, s[4:5]
	global_load_dword v36, v16, s[8:9]
	global_load_dword v37, v17, s[8:9]
	s_add_u32 s10, s10, s18
	s_addc_u32 s11, s11, 0
	global_load_dword v38, v193, s[10:11]
	global_load_dword v39, v193, s[10:11] offset:256
	global_load_dword v40, v18, s[4:5]
	global_load_dword v41, v19, s[4:5]
	global_load_dword v42, v18, s[8:9]
	global_load_dword v43, v19, s[8:9]
	s_add_u32 s10, s10, s18
	s_addc_u32 s11, s11, 0
	global_load_dword v44, v193, s[10:11]
	global_load_dword v45, v193, s[10:11] offset:256
	global_load_dword v46, v20, s[4:5]
	global_load_dword v47, v21, s[4:5]
	global_load_dword v48, v20, s[8:9]
	global_load_dword v49, v21, s[8:9]
	s_add_u32 s10, s10, s18
	s_addc_u32 s11, s11, 0
	global_load_dword v50, v193, s[10:11]
	global_load_dword v51, v193, s[10:11] offset:256
	global_load_dword v52, v22, s[4:5]
	global_load_dword v53, v23, s[4:5]
	global_load_dword v54, v22, s[8:9]
	global_load_dword v55, v23, s[8:9]
	s_add_u32 s10, s10, s18
	s_addc_u32 s11, s11, 0
	global_load_dword v56, v193, s[10:11]
	global_load_dword v57, v193, s[10:11] offset:256
	global_load_dword v58, v24, s[4:5]
	global_load_dword v59, v25, s[4:5]
	global_load_dword v60, v24, s[8:9]
	global_load_dword v61, v25, s[8:9]
	s_add_u32 s10, s10, s18
	s_addc_u32 s11, s11, 0
	global_load_dword v62, v193, s[10:11]
	global_load_dword v63, v193, s[10:11] offset:256
	global_load_dword v64, v26, s[4:5]
	global_load_dword v65, v27, s[4:5]
	global_load_dword v66, v26, s[8:9]
	global_load_dword v67, v27, s[8:9]
	s_add_u32 s10, s10, s18
	s_addc_u32 s11, s11, 0
	global_load_dword v68, v193, s[10:11]
	global_load_dword v69, v193, s[10:11] offset:256
	global_load_dword v70, v28, s[4:5]
	global_load_dword v71, v29, s[4:5]
	global_load_dword v72, v28, s[8:9]
	global_load_dword v73, v29, s[8:9]
	s_add_u32 s10, s10, s18
	s_addc_u32 s11, s11, 0
	global_load_dword v74, v193, s[10:11]
	global_load_dword v75, v193, s[10:11] offset:256
	global_load_dword v76, v30, s[4:5]
	global_load_dword v77, v31, s[4:5]
	global_load_dword v78, v30, s[8:9]
	global_load_dword v79, v31, s[8:9]
	s_add_u32 s10, s10, s18
	s_addc_u32 s11, s11, 0
	s_waitcnt vmcnt(0)
	v_mul_f32_e32 v80, v34, v80
	v_mul_f32_e32 v180, 0x3f3504f3, v80
	v_fma_f32 v182, |v180|, s16, v177
	v_fma_f32 v182, |v180|, v182, s19
	v_fma_f32 v182, |v180|, v182, s50
	v_fma_f32 v182, |v180|, v182, s51
	v_fma_f32 v182, |v180|, v182, s64
	v_fma_f32 v182, |v180|, v182, s65
	v_fma_f32 v182, |v180|, v182, |v180|
	v_mul_f32_e32 v184, 0xbfb8aa3b, v182
	v_fma_f32 v185, v182, s98, -v184
	v_rndne_f32_e32 v186, v184
	v_fmac_f32_e32 v185, 0xb2a5705f, v182
	v_sub_f32_e32 v184, v184, v186
	v_add_f32_e32 v184, v184, v185
	v_cvt_i32_f32_e32 v185, v186
	v_exp_f32_e32 v184, v184
	v_cmp_nlt_f32_e32 vcc, s70, v182
	v_ldexp_f32 v184, v184, v185
	s_nop 0
	v_cndmask_b32_e32 v184, 0, v184, vcc
	v_cmp_ngt_f32_e32 vcc, s71, v182
	s_nop 1
	v_cndmask_b32_e32 v184, v178, v184, vcc
	v_sub_f32_e32 v184, 1.0, v184
	v_mul_f32_e32 v183, v180, v180
	v_fmamk_f32 v185, v183, 0xba1345e1, v176
	v_fmaak_f32 v185, v183, v185, 0xbcdac9b8
	v_fmaak_f32 v185, v183, v185, 0x3de703be
	v_fmaak_f32 v185, v183, v185, 0xbec09330
	v_fmaak_f32 v183, v183, v185, 0x3e0375d0
	v_fma_f32 v183, |v180|, v183, |v180|
	v_cmp_nlt_f32_e64 vcc, |v180|, 1.0
	s_nop 1
	v_cndmask_b32_e32 v184, v183, v184, vcc
	v_bfi_b32 v184, s14, v184, v180
	v_add_f32_e32 v184, 1.0, v184
	v_mul_f32_e32 v80, 0.5, v80
	v_mul_f32_e32 v32, v32, v36
	v_mul_f32_e32 v80, v80, v184
	v_mul_f32_e32 v80, v32, v80
	v_mul_f32_e32 v81, v35, v81
	v_mul_f32_e32 v180, 0x3f3504f3, v81
	v_fma_f32 v182, |v180|, s16, v177
	v_fma_f32 v182, |v180|, v182, s19
	v_fma_f32 v182, |v180|, v182, s50
	v_fma_f32 v182, |v180|, v182, s51
	v_fma_f32 v182, |v180|, v182, s64
	v_fma_f32 v182, |v180|, v182, s65
	v_fma_f32 v182, |v180|, v182, |v180|
	v_mul_f32_e32 v184, 0xbfb8aa3b, v182
	v_fma_f32 v185, v182, s98, -v184
	v_rndne_f32_e32 v186, v184
	v_fmac_f32_e32 v185, 0xb2a5705f, v182
	v_sub_f32_e32 v184, v184, v186
	v_add_f32_e32 v184, v184, v185
	v_cvt_i32_f32_e32 v185, v186
	v_exp_f32_e32 v184, v184
	v_cmp_nlt_f32_e32 vcc, s70, v182
	v_ldexp_f32 v184, v184, v185
	s_nop 0
	v_cndmask_b32_e32 v184, 0, v184, vcc
	v_cmp_ngt_f32_e32 vcc, s71, v182
	s_nop 1
	v_cndmask_b32_e32 v184, v178, v184, vcc
	v_sub_f32_e32 v184, 1.0, v184
	v_mul_f32_e32 v183, v180, v180
	v_fmamk_f32 v185, v183, 0xba1345e1, v176
	v_fmaak_f32 v185, v183, v185, 0xbcdac9b8
	v_fmaak_f32 v185, v183, v185, 0x3de703be
	v_fmaak_f32 v185, v183, v185, 0xbec09330
	v_fmaak_f32 v183, v183, v185, 0x3e0375d0
	v_fma_f32 v183, |v180|, v183, |v180|
	v_cmp_nlt_f32_e64 vcc, |v180|, 1.0
	s_nop 1
	v_cndmask_b32_e32 v184, v183, v184, vcc
	v_bfi_b32 v184, s14, v184, v180
	v_add_f32_e32 v184, 1.0, v184
	v_mul_f32_e32 v81, 0.5, v81
	v_mul_f32_e32 v33, v33, v37
	v_mul_f32_e32 v81, v81, v184
	v_mul_f32_e32 v81, v33, v81
	global_store_dword v193, v80, s[12:13]
	global_store_dword v193, v81, s[12:13] offset:256
	s_add_u32 s12, s12, s18
	s_addc_u32 s13, s13, 0
	v_mul_f32_e32 v82, v40, v82
	v_mul_f32_e32 v180, 0x3f3504f3, v82
	v_fma_f32 v182, |v180|, s16, v177
	v_fma_f32 v182, |v180|, v182, s19
	v_fma_f32 v182, |v180|, v182, s50
	v_fma_f32 v182, |v180|, v182, s51
	v_fma_f32 v182, |v180|, v182, s64
	v_fma_f32 v182, |v180|, v182, s65
	v_fma_f32 v182, |v180|, v182, |v180|
	v_mul_f32_e32 v184, 0xbfb8aa3b, v182
	v_fma_f32 v185, v182, s98, -v184
	v_rndne_f32_e32 v186, v184
	v_fmac_f32_e32 v185, 0xb2a5705f, v182
	v_sub_f32_e32 v184, v184, v186
	v_add_f32_e32 v184, v184, v185
	v_cvt_i32_f32_e32 v185, v186
	v_exp_f32_e32 v184, v184
	v_cmp_nlt_f32_e32 vcc, s70, v182
	v_ldexp_f32 v184, v184, v185
	s_nop 0
	v_cndmask_b32_e32 v184, 0, v184, vcc
	v_cmp_ngt_f32_e32 vcc, s71, v182
	s_nop 1
	v_cndmask_b32_e32 v184, v178, v184, vcc
	v_sub_f32_e32 v184, 1.0, v184
	v_mul_f32_e32 v183, v180, v180
	v_fmamk_f32 v185, v183, 0xba1345e1, v176
	v_fmaak_f32 v185, v183, v185, 0xbcdac9b8
	v_fmaak_f32 v185, v183, v185, 0x3de703be
	v_fmaak_f32 v185, v183, v185, 0xbec09330
	v_fmaak_f32 v183, v183, v185, 0x3e0375d0
	v_fma_f32 v183, |v180|, v183, |v180|
	v_cmp_nlt_f32_e64 vcc, |v180|, 1.0
	s_nop 1
	v_cndmask_b32_e32 v184, v183, v184, vcc
	v_bfi_b32 v184, s14, v184, v180
	v_add_f32_e32 v184, 1.0, v184
	v_mul_f32_e32 v82, 0.5, v82
	v_mul_f32_e32 v38, v38, v42
	v_mul_f32_e32 v82, v82, v184
	v_mul_f32_e32 v82, v38, v82
	v_mul_f32_e32 v83, v41, v83
	v_mul_f32_e32 v180, 0x3f3504f3, v83
	v_fma_f32 v182, |v180|, s16, v177
	v_fma_f32 v182, |v180|, v182, s19
	v_fma_f32 v182, |v180|, v182, s50
	v_fma_f32 v182, |v180|, v182, s51
	v_fma_f32 v182, |v180|, v182, s64
	v_fma_f32 v182, |v180|, v182, s65
	v_fma_f32 v182, |v180|, v182, |v180|
	v_mul_f32_e32 v184, 0xbfb8aa3b, v182
	v_fma_f32 v185, v182, s98, -v184
	v_rndne_f32_e32 v186, v184
	v_fmac_f32_e32 v185, 0xb2a5705f, v182
	v_sub_f32_e32 v184, v184, v186
	v_add_f32_e32 v184, v184, v185
	v_cvt_i32_f32_e32 v185, v186
	v_exp_f32_e32 v184, v184
	v_cmp_nlt_f32_e32 vcc, s70, v182
	v_ldexp_f32 v184, v184, v185
	s_nop 0
	v_cndmask_b32_e32 v184, 0, v184, vcc
	v_cmp_ngt_f32_e32 vcc, s71, v182
	s_nop 1
	v_cndmask_b32_e32 v184, v178, v184, vcc
	v_sub_f32_e32 v184, 1.0, v184
	v_mul_f32_e32 v183, v180, v180
	v_fmamk_f32 v185, v183, 0xba1345e1, v176
	v_fmaak_f32 v185, v183, v185, 0xbcdac9b8
	v_fmaak_f32 v185, v183, v185, 0x3de703be
	v_fmaak_f32 v185, v183, v185, 0xbec09330
	v_fmaak_f32 v183, v183, v185, 0x3e0375d0
	v_fma_f32 v183, |v180|, v183, |v180|
	v_cmp_nlt_f32_e64 vcc, |v180|, 1.0
	s_nop 1
	v_cndmask_b32_e32 v184, v183, v184, vcc
	v_bfi_b32 v184, s14, v184, v180
	v_add_f32_e32 v184, 1.0, v184
	v_mul_f32_e32 v83, 0.5, v83
	v_mul_f32_e32 v39, v39, v43
	v_mul_f32_e32 v83, v83, v184
	v_mul_f32_e32 v83, v39, v83
	global_store_dword v193, v82, s[12:13]
	global_store_dword v193, v83, s[12:13] offset:256
	s_add_u32 s12, s12, s18
	s_addc_u32 s13, s13, 0
	v_mul_f32_e32 v84, v46, v84
	v_mul_f32_e32 v180, 0x3f3504f3, v84
	v_fma_f32 v182, |v180|, s16, v177
	v_fma_f32 v182, |v180|, v182, s19
	v_fma_f32 v182, |v180|, v182, s50
	v_fma_f32 v182, |v180|, v182, s51
	v_fma_f32 v182, |v180|, v182, s64
	v_fma_f32 v182, |v180|, v182, s65
	v_fma_f32 v182, |v180|, v182, |v180|
	v_mul_f32_e32 v184, 0xbfb8aa3b, v182
	v_fma_f32 v185, v182, s98, -v184
	v_rndne_f32_e32 v186, v184
	v_fmac_f32_e32 v185, 0xb2a5705f, v182
	v_sub_f32_e32 v184, v184, v186
	v_add_f32_e32 v184, v184, v185
	v_cvt_i32_f32_e32 v185, v186
	v_exp_f32_e32 v184, v184
	v_cmp_nlt_f32_e32 vcc, s70, v182
	v_ldexp_f32 v184, v184, v185
	s_nop 0
	v_cndmask_b32_e32 v184, 0, v184, vcc
	v_cmp_ngt_f32_e32 vcc, s71, v182
	s_nop 1
	v_cndmask_b32_e32 v184, v178, v184, vcc
	v_sub_f32_e32 v184, 1.0, v184
	v_mul_f32_e32 v183, v180, v180
	v_fmamk_f32 v185, v183, 0xba1345e1, v176
	v_fmaak_f32 v185, v183, v185, 0xbcdac9b8
	v_fmaak_f32 v185, v183, v185, 0x3de703be
	v_fmaak_f32 v185, v183, v185, 0xbec09330
	v_fmaak_f32 v183, v183, v185, 0x3e0375d0
	v_fma_f32 v183, |v180|, v183, |v180|
	v_cmp_nlt_f32_e64 vcc, |v180|, 1.0
	s_nop 1
	v_cndmask_b32_e32 v184, v183, v184, vcc
	v_bfi_b32 v184, s14, v184, v180
	v_add_f32_e32 v184, 1.0, v184
	v_mul_f32_e32 v84, 0.5, v84
	v_mul_f32_e32 v44, v44, v48
	v_mul_f32_e32 v84, v84, v184
	v_mul_f32_e32 v84, v44, v84
	v_mul_f32_e32 v85, v47, v85
	v_mul_f32_e32 v180, 0x3f3504f3, v85
	v_fma_f32 v182, |v180|, s16, v177
	v_fma_f32 v182, |v180|, v182, s19
	v_fma_f32 v182, |v180|, v182, s50
	v_fma_f32 v182, |v180|, v182, s51
	v_fma_f32 v182, |v180|, v182, s64
	v_fma_f32 v182, |v180|, v182, s65
	v_fma_f32 v182, |v180|, v182, |v180|
	v_mul_f32_e32 v184, 0xbfb8aa3b, v182
	v_fma_f32 v185, v182, s98, -v184
	v_rndne_f32_e32 v186, v184
	v_fmac_f32_e32 v185, 0xb2a5705f, v182
	v_sub_f32_e32 v184, v184, v186
	v_add_f32_e32 v184, v184, v185
	v_cvt_i32_f32_e32 v185, v186
	v_exp_f32_e32 v184, v184
	v_cmp_nlt_f32_e32 vcc, s70, v182
	v_ldexp_f32 v184, v184, v185
	s_nop 0
	v_cndmask_b32_e32 v184, 0, v184, vcc
	v_cmp_ngt_f32_e32 vcc, s71, v182
	s_nop 1
	v_cndmask_b32_e32 v184, v178, v184, vcc
	v_sub_f32_e32 v184, 1.0, v184
	v_mul_f32_e32 v183, v180, v180
	v_fmamk_f32 v185, v183, 0xba1345e1, v176
	v_fmaak_f32 v185, v183, v185, 0xbcdac9b8
	v_fmaak_f32 v185, v183, v185, 0x3de703be
	v_fmaak_f32 v185, v183, v185, 0xbec09330
	v_fmaak_f32 v183, v183, v185, 0x3e0375d0
	v_fma_f32 v183, |v180|, v183, |v180|
	v_cmp_nlt_f32_e64 vcc, |v180|, 1.0
	s_nop 1
	v_cndmask_b32_e32 v184, v183, v184, vcc
	v_bfi_b32 v184, s14, v184, v180
	v_add_f32_e32 v184, 1.0, v184
	v_mul_f32_e32 v85, 0.5, v85
	v_mul_f32_e32 v45, v45, v49
	v_mul_f32_e32 v85, v85, v184
	v_mul_f32_e32 v85, v45, v85
	global_store_dword v193, v84, s[12:13]
	global_store_dword v193, v85, s[12:13] offset:256
	s_add_u32 s12, s12, s18
	s_addc_u32 s13, s13, 0
	v_mul_f32_e32 v86, v52, v86
	v_mul_f32_e32 v180, 0x3f3504f3, v86
	v_fma_f32 v182, |v180|, s16, v177
	v_fma_f32 v182, |v180|, v182, s19
	v_fma_f32 v182, |v180|, v182, s50
	v_fma_f32 v182, |v180|, v182, s51
	v_fma_f32 v182, |v180|, v182, s64
	v_fma_f32 v182, |v180|, v182, s65
	v_fma_f32 v182, |v180|, v182, |v180|
	v_mul_f32_e32 v184, 0xbfb8aa3b, v182
	v_fma_f32 v185, v182, s98, -v184
	v_rndne_f32_e32 v186, v184
	v_fmac_f32_e32 v185, 0xb2a5705f, v182
	v_sub_f32_e32 v184, v184, v186
	v_add_f32_e32 v184, v184, v185
	v_cvt_i32_f32_e32 v185, v186
	v_exp_f32_e32 v184, v184
	v_cmp_nlt_f32_e32 vcc, s70, v182
	v_ldexp_f32 v184, v184, v185
	s_nop 0
	v_cndmask_b32_e32 v184, 0, v184, vcc
	v_cmp_ngt_f32_e32 vcc, s71, v182
	s_nop 1
	v_cndmask_b32_e32 v184, v178, v184, vcc
	v_sub_f32_e32 v184, 1.0, v184
	v_mul_f32_e32 v183, v180, v180
	v_fmamk_f32 v185, v183, 0xba1345e1, v176
	v_fmaak_f32 v185, v183, v185, 0xbcdac9b8
	v_fmaak_f32 v185, v183, v185, 0x3de703be
	v_fmaak_f32 v185, v183, v185, 0xbec09330
	v_fmaak_f32 v183, v183, v185, 0x3e0375d0
	v_fma_f32 v183, |v180|, v183, |v180|
	v_cmp_nlt_f32_e64 vcc, |v180|, 1.0
	s_nop 1
	v_cndmask_b32_e32 v184, v183, v184, vcc
	v_bfi_b32 v184, s14, v184, v180
	v_add_f32_e32 v184, 1.0, v184
	v_mul_f32_e32 v86, 0.5, v86
	v_mul_f32_e32 v50, v50, v54
	v_mul_f32_e32 v86, v86, v184
	v_mul_f32_e32 v86, v50, v86
	v_mul_f32_e32 v87, v53, v87
	v_mul_f32_e32 v180, 0x3f3504f3, v87
	v_fma_f32 v182, |v180|, s16, v177
	v_fma_f32 v182, |v180|, v182, s19
	v_fma_f32 v182, |v180|, v182, s50
	v_fma_f32 v182, |v180|, v182, s51
	v_fma_f32 v182, |v180|, v182, s64
	v_fma_f32 v182, |v180|, v182, s65
	v_fma_f32 v182, |v180|, v182, |v180|
	v_mul_f32_e32 v184, 0xbfb8aa3b, v182
	v_fma_f32 v185, v182, s98, -v184
	v_rndne_f32_e32 v186, v184
	v_fmac_f32_e32 v185, 0xb2a5705f, v182
	v_sub_f32_e32 v184, v184, v186
	v_add_f32_e32 v184, v184, v185
	v_cvt_i32_f32_e32 v185, v186
	v_exp_f32_e32 v184, v184
	v_cmp_nlt_f32_e32 vcc, s70, v182
	v_ldexp_f32 v184, v184, v185
	s_nop 0
	v_cndmask_b32_e32 v184, 0, v184, vcc
	v_cmp_ngt_f32_e32 vcc, s71, v182
	s_nop 1
	v_cndmask_b32_e32 v184, v178, v184, vcc
	v_sub_f32_e32 v184, 1.0, v184
	v_mul_f32_e32 v183, v180, v180
	v_fmamk_f32 v185, v183, 0xba1345e1, v176
	v_fmaak_f32 v185, v183, v185, 0xbcdac9b8
	v_fmaak_f32 v185, v183, v185, 0x3de703be
	v_fmaak_f32 v185, v183, v185, 0xbec09330
	v_fmaak_f32 v183, v183, v185, 0x3e0375d0
	v_fma_f32 v183, |v180|, v183, |v180|
	v_cmp_nlt_f32_e64 vcc, |v180|, 1.0
	s_nop 1
	v_cndmask_b32_e32 v184, v183, v184, vcc
	v_bfi_b32 v184, s14, v184, v180
	v_add_f32_e32 v184, 1.0, v184
	v_mul_f32_e32 v87, 0.5, v87
	v_mul_f32_e32 v51, v51, v55
	v_mul_f32_e32 v87, v87, v184
	v_mul_f32_e32 v87, v51, v87
	global_store_dword v193, v86, s[12:13]
	global_store_dword v193, v87, s[12:13] offset:256
	s_add_u32 s12, s12, s18
	s_addc_u32 s13, s13, 0
	v_mul_f32_e32 v88, v58, v88
	v_mul_f32_e32 v180, 0x3f3504f3, v88
	v_fma_f32 v182, |v180|, s16, v177
	v_fma_f32 v182, |v180|, v182, s19
	v_fma_f32 v182, |v180|, v182, s50
	v_fma_f32 v182, |v180|, v182, s51
	v_fma_f32 v182, |v180|, v182, s64
	v_fma_f32 v182, |v180|, v182, s65
	v_fma_f32 v182, |v180|, v182, |v180|
	v_mul_f32_e32 v184, 0xbfb8aa3b, v182
	v_fma_f32 v185, v182, s98, -v184
	v_rndne_f32_e32 v186, v184
	v_fmac_f32_e32 v185, 0xb2a5705f, v182
	v_sub_f32_e32 v184, v184, v186
	v_add_f32_e32 v184, v184, v185
	v_cvt_i32_f32_e32 v185, v186
	v_exp_f32_e32 v184, v184
	v_cmp_nlt_f32_e32 vcc, s70, v182
	v_ldexp_f32 v184, v184, v185
	s_nop 0
	v_cndmask_b32_e32 v184, 0, v184, vcc
	v_cmp_ngt_f32_e32 vcc, s71, v182
	s_nop 1
	v_cndmask_b32_e32 v184, v178, v184, vcc
	v_sub_f32_e32 v184, 1.0, v184
	v_mul_f32_e32 v183, v180, v180
	v_fmamk_f32 v185, v183, 0xba1345e1, v176
	v_fmaak_f32 v185, v183, v185, 0xbcdac9b8
	v_fmaak_f32 v185, v183, v185, 0x3de703be
	v_fmaak_f32 v185, v183, v185, 0xbec09330
	v_fmaak_f32 v183, v183, v185, 0x3e0375d0
	v_fma_f32 v183, |v180|, v183, |v180|
	v_cmp_nlt_f32_e64 vcc, |v180|, 1.0
	s_nop 1
	v_cndmask_b32_e32 v184, v183, v184, vcc
	v_bfi_b32 v184, s14, v184, v180
	v_add_f32_e32 v184, 1.0, v184
	v_mul_f32_e32 v88, 0.5, v88
	v_mul_f32_e32 v56, v56, v60
	v_mul_f32_e32 v88, v88, v184
	v_mul_f32_e32 v88, v56, v88
	v_mul_f32_e32 v89, v59, v89
	v_mul_f32_e32 v180, 0x3f3504f3, v89
	v_fma_f32 v182, |v180|, s16, v177
	v_fma_f32 v182, |v180|, v182, s19
	v_fma_f32 v182, |v180|, v182, s50
	v_fma_f32 v182, |v180|, v182, s51
	v_fma_f32 v182, |v180|, v182, s64
	v_fma_f32 v182, |v180|, v182, s65
	v_fma_f32 v182, |v180|, v182, |v180|
	v_mul_f32_e32 v184, 0xbfb8aa3b, v182
	v_fma_f32 v185, v182, s98, -v184
	v_rndne_f32_e32 v186, v184
	v_fmac_f32_e32 v185, 0xb2a5705f, v182
	v_sub_f32_e32 v184, v184, v186
	v_add_f32_e32 v184, v184, v185
	v_cvt_i32_f32_e32 v185, v186
	v_exp_f32_e32 v184, v184
	v_cmp_nlt_f32_e32 vcc, s70, v182
	v_ldexp_f32 v184, v184, v185
	s_nop 0
	v_cndmask_b32_e32 v184, 0, v184, vcc
	v_cmp_ngt_f32_e32 vcc, s71, v182
	s_nop 1
	v_cndmask_b32_e32 v184, v178, v184, vcc
	v_sub_f32_e32 v184, 1.0, v184
	v_mul_f32_e32 v183, v180, v180
	v_fmamk_f32 v185, v183, 0xba1345e1, v176
	v_fmaak_f32 v185, v183, v185, 0xbcdac9b8
	v_fmaak_f32 v185, v183, v185, 0x3de703be
	v_fmaak_f32 v185, v183, v185, 0xbec09330
	v_fmaak_f32 v183, v183, v185, 0x3e0375d0
	v_fma_f32 v183, |v180|, v183, |v180|
	v_cmp_nlt_f32_e64 vcc, |v180|, 1.0
	s_nop 1
	v_cndmask_b32_e32 v184, v183, v184, vcc
	v_bfi_b32 v184, s14, v184, v180
	v_add_f32_e32 v184, 1.0, v184
	v_mul_f32_e32 v89, 0.5, v89
	v_mul_f32_e32 v57, v57, v61
	v_mul_f32_e32 v89, v89, v184
	v_mul_f32_e32 v89, v57, v89
	global_store_dword v193, v88, s[12:13]
	global_store_dword v193, v89, s[12:13] offset:256
	s_add_u32 s12, s12, s18
	s_addc_u32 s13, s13, 0
	v_mul_f32_e32 v90, v64, v90
	v_mul_f32_e32 v180, 0x3f3504f3, v90
	v_fma_f32 v182, |v180|, s16, v177
	v_fma_f32 v182, |v180|, v182, s19
	v_fma_f32 v182, |v180|, v182, s50
	v_fma_f32 v182, |v180|, v182, s51
	v_fma_f32 v182, |v180|, v182, s64
	v_fma_f32 v182, |v180|, v182, s65
	v_fma_f32 v182, |v180|, v182, |v180|
	v_mul_f32_e32 v184, 0xbfb8aa3b, v182
	v_fma_f32 v185, v182, s98, -v184
	v_rndne_f32_e32 v186, v184
	v_fmac_f32_e32 v185, 0xb2a5705f, v182
	v_sub_f32_e32 v184, v184, v186
	v_add_f32_e32 v184, v184, v185
	v_cvt_i32_f32_e32 v185, v186
	v_exp_f32_e32 v184, v184
	v_cmp_nlt_f32_e32 vcc, s70, v182
	v_ldexp_f32 v184, v184, v185
	s_nop 0
	v_cndmask_b32_e32 v184, 0, v184, vcc
	v_cmp_ngt_f32_e32 vcc, s71, v182
	s_nop 1
	v_cndmask_b32_e32 v184, v178, v184, vcc
	v_sub_f32_e32 v184, 1.0, v184
	v_mul_f32_e32 v183, v180, v180
	v_fmamk_f32 v185, v183, 0xba1345e1, v176
	v_fmaak_f32 v185, v183, v185, 0xbcdac9b8
	v_fmaak_f32 v185, v183, v185, 0x3de703be
	v_fmaak_f32 v185, v183, v185, 0xbec09330
	v_fmaak_f32 v183, v183, v185, 0x3e0375d0
	v_fma_f32 v183, |v180|, v183, |v180|
	v_cmp_nlt_f32_e64 vcc, |v180|, 1.0
	s_nop 1
	v_cndmask_b32_e32 v184, v183, v184, vcc
	v_bfi_b32 v184, s14, v184, v180
	v_add_f32_e32 v184, 1.0, v184
	v_mul_f32_e32 v90, 0.5, v90
	v_mul_f32_e32 v62, v62, v66
	v_mul_f32_e32 v90, v90, v184
	v_mul_f32_e32 v90, v62, v90
	v_mul_f32_e32 v91, v65, v91
	v_mul_f32_e32 v180, 0x3f3504f3, v91
	v_fma_f32 v182, |v180|, s16, v177
	v_fma_f32 v182, |v180|, v182, s19
	v_fma_f32 v182, |v180|, v182, s50
	v_fma_f32 v182, |v180|, v182, s51
	v_fma_f32 v182, |v180|, v182, s64
	v_fma_f32 v182, |v180|, v182, s65
	v_fma_f32 v182, |v180|, v182, |v180|
	v_mul_f32_e32 v184, 0xbfb8aa3b, v182
	v_fma_f32 v185, v182, s98, -v184
	v_rndne_f32_e32 v186, v184
	v_fmac_f32_e32 v185, 0xb2a5705f, v182
	v_sub_f32_e32 v184, v184, v186
	v_add_f32_e32 v184, v184, v185
	v_cvt_i32_f32_e32 v185, v186
	v_exp_f32_e32 v184, v184
	v_cmp_nlt_f32_e32 vcc, s70, v182
	v_ldexp_f32 v184, v184, v185
	s_nop 0
	v_cndmask_b32_e32 v184, 0, v184, vcc
	v_cmp_ngt_f32_e32 vcc, s71, v182
	s_nop 1
	v_cndmask_b32_e32 v184, v178, v184, vcc
	v_sub_f32_e32 v184, 1.0, v184
	v_mul_f32_e32 v183, v180, v180
	v_fmamk_f32 v185, v183, 0xba1345e1, v176
	v_fmaak_f32 v185, v183, v185, 0xbcdac9b8
	v_fmaak_f32 v185, v183, v185, 0x3de703be
	v_fmaak_f32 v185, v183, v185, 0xbec09330
	v_fmaak_f32 v183, v183, v185, 0x3e0375d0
	v_fma_f32 v183, |v180|, v183, |v180|
	v_cmp_nlt_f32_e64 vcc, |v180|, 1.0
	s_nop 1
	v_cndmask_b32_e32 v184, v183, v184, vcc
	v_bfi_b32 v184, s14, v184, v180
	v_add_f32_e32 v184, 1.0, v184
	v_mul_f32_e32 v91, 0.5, v91
	v_mul_f32_e32 v63, v63, v67
	v_mul_f32_e32 v91, v91, v184
	v_mul_f32_e32 v91, v63, v91
	global_store_dword v193, v90, s[12:13]
	global_store_dword v193, v91, s[12:13] offset:256
	s_add_u32 s12, s12, s18
	s_addc_u32 s13, s13, 0
	v_mul_f32_e32 v92, v70, v92
	v_mul_f32_e32 v180, 0x3f3504f3, v92
	v_fma_f32 v182, |v180|, s16, v177
	v_fma_f32 v182, |v180|, v182, s19
	v_fma_f32 v182, |v180|, v182, s50
	v_fma_f32 v182, |v180|, v182, s51
	v_fma_f32 v182, |v180|, v182, s64
	v_fma_f32 v182, |v180|, v182, s65
	v_fma_f32 v182, |v180|, v182, |v180|
	v_mul_f32_e32 v184, 0xbfb8aa3b, v182
	v_fma_f32 v185, v182, s98, -v184
	v_rndne_f32_e32 v186, v184
	v_fmac_f32_e32 v185, 0xb2a5705f, v182
	v_sub_f32_e32 v184, v184, v186
	v_add_f32_e32 v184, v184, v185
	v_cvt_i32_f32_e32 v185, v186
	v_exp_f32_e32 v184, v184
	v_cmp_nlt_f32_e32 vcc, s70, v182
	v_ldexp_f32 v184, v184, v185
	s_nop 0
	v_cndmask_b32_e32 v184, 0, v184, vcc
	v_cmp_ngt_f32_e32 vcc, s71, v182
	s_nop 1
	v_cndmask_b32_e32 v184, v178, v184, vcc
	v_sub_f32_e32 v184, 1.0, v184
	v_mul_f32_e32 v183, v180, v180
	v_fmamk_f32 v185, v183, 0xba1345e1, v176
	v_fmaak_f32 v185, v183, v185, 0xbcdac9b8
	v_fmaak_f32 v185, v183, v185, 0x3de703be
	v_fmaak_f32 v185, v183, v185, 0xbec09330
	v_fmaak_f32 v183, v183, v185, 0x3e0375d0
	v_fma_f32 v183, |v180|, v183, |v180|
	v_cmp_nlt_f32_e64 vcc, |v180|, 1.0
	s_nop 1
	v_cndmask_b32_e32 v184, v183, v184, vcc
	v_bfi_b32 v184, s14, v184, v180
	v_add_f32_e32 v184, 1.0, v184
	v_mul_f32_e32 v92, 0.5, v92
	v_mul_f32_e32 v68, v68, v72
	v_mul_f32_e32 v92, v92, v184
	v_mul_f32_e32 v92, v68, v92
	v_mul_f32_e32 v93, v71, v93
	v_mul_f32_e32 v180, 0x3f3504f3, v93
	v_fma_f32 v182, |v180|, s16, v177
	v_fma_f32 v182, |v180|, v182, s19
	v_fma_f32 v182, |v180|, v182, s50
	v_fma_f32 v182, |v180|, v182, s51
	v_fma_f32 v182, |v180|, v182, s64
	v_fma_f32 v182, |v180|, v182, s65
	v_fma_f32 v182, |v180|, v182, |v180|
	v_mul_f32_e32 v184, 0xbfb8aa3b, v182
	v_fma_f32 v185, v182, s98, -v184
	v_rndne_f32_e32 v186, v184
	v_fmac_f32_e32 v185, 0xb2a5705f, v182
	v_sub_f32_e32 v184, v184, v186
	v_add_f32_e32 v184, v184, v185
	v_cvt_i32_f32_e32 v185, v186
	v_exp_f32_e32 v184, v184
	v_cmp_nlt_f32_e32 vcc, s70, v182
	v_ldexp_f32 v184, v184, v185
	s_nop 0
	v_cndmask_b32_e32 v184, 0, v184, vcc
	v_cmp_ngt_f32_e32 vcc, s71, v182
	s_nop 1
	v_cndmask_b32_e32 v184, v178, v184, vcc
	v_sub_f32_e32 v184, 1.0, v184
	v_mul_f32_e32 v183, v180, v180
	v_fmamk_f32 v185, v183, 0xba1345e1, v176
	v_fmaak_f32 v185, v183, v185, 0xbcdac9b8
	v_fmaak_f32 v185, v183, v185, 0x3de703be
	v_fmaak_f32 v185, v183, v185, 0xbec09330
	v_fmaak_f32 v183, v183, v185, 0x3e0375d0
	v_fma_f32 v183, |v180|, v183, |v180|
	v_cmp_nlt_f32_e64 vcc, |v180|, 1.0
	s_nop 1
	v_cndmask_b32_e32 v184, v183, v184, vcc
	v_bfi_b32 v184, s14, v184, v180
	v_add_f32_e32 v184, 1.0, v184
	v_mul_f32_e32 v93, 0.5, v93
	v_mul_f32_e32 v69, v69, v73
	v_mul_f32_e32 v93, v93, v184
	v_mul_f32_e32 v93, v69, v93
	global_store_dword v193, v92, s[12:13]
	global_store_dword v193, v93, s[12:13] offset:256
	s_add_u32 s12, s12, s18
	s_addc_u32 s13, s13, 0
	v_mul_f32_e32 v94, v76, v94
	v_mul_f32_e32 v180, 0x3f3504f3, v94
	v_fma_f32 v182, |v180|, s16, v177
	v_fma_f32 v182, |v180|, v182, s19
	v_fma_f32 v182, |v180|, v182, s50
	v_fma_f32 v182, |v180|, v182, s51
	v_fma_f32 v182, |v180|, v182, s64
	v_fma_f32 v182, |v180|, v182, s65
	v_fma_f32 v182, |v180|, v182, |v180|
	v_mul_f32_e32 v184, 0xbfb8aa3b, v182
	v_fma_f32 v185, v182, s98, -v184
	v_rndne_f32_e32 v186, v184
	v_fmac_f32_e32 v185, 0xb2a5705f, v182
	v_sub_f32_e32 v184, v184, v186
	v_add_f32_e32 v184, v184, v185
	v_cvt_i32_f32_e32 v185, v186
	v_exp_f32_e32 v184, v184
	v_cmp_nlt_f32_e32 vcc, s70, v182
	v_ldexp_f32 v184, v184, v185
	s_nop 0
	v_cndmask_b32_e32 v184, 0, v184, vcc
	v_cmp_ngt_f32_e32 vcc, s71, v182
	s_nop 1
	v_cndmask_b32_e32 v184, v178, v184, vcc
	v_sub_f32_e32 v184, 1.0, v184
	v_mul_f32_e32 v183, v180, v180
	v_fmamk_f32 v185, v183, 0xba1345e1, v176
	v_fmaak_f32 v185, v183, v185, 0xbcdac9b8
	v_fmaak_f32 v185, v183, v185, 0x3de703be
	v_fmaak_f32 v185, v183, v185, 0xbec09330
	v_fmaak_f32 v183, v183, v185, 0x3e0375d0
	v_fma_f32 v183, |v180|, v183, |v180|
	v_cmp_nlt_f32_e64 vcc, |v180|, 1.0
	s_nop 1
	v_cndmask_b32_e32 v184, v183, v184, vcc
	v_bfi_b32 v184, s14, v184, v180
	v_add_f32_e32 v184, 1.0, v184
	v_mul_f32_e32 v94, 0.5, v94
	v_mul_f32_e32 v74, v74, v78
	v_mul_f32_e32 v94, v94, v184
	v_mul_f32_e32 v94, v74, v94
	v_mul_f32_e32 v95, v77, v95
	v_mul_f32_e32 v180, 0x3f3504f3, v95
	v_fma_f32 v182, |v180|, s16, v177
	v_fma_f32 v182, |v180|, v182, s19
	v_fma_f32 v182, |v180|, v182, s50
	v_fma_f32 v182, |v180|, v182, s51
	v_fma_f32 v182, |v180|, v182, s64
	v_fma_f32 v182, |v180|, v182, s65
	v_fma_f32 v182, |v180|, v182, |v180|
	v_mul_f32_e32 v184, 0xbfb8aa3b, v182
	v_fma_f32 v185, v182, s98, -v184
	v_rndne_f32_e32 v186, v184
	v_fmac_f32_e32 v185, 0xb2a5705f, v182
	v_sub_f32_e32 v184, v184, v186
	v_add_f32_e32 v184, v184, v185
	v_cvt_i32_f32_e32 v185, v186
	v_exp_f32_e32 v184, v184
	v_cmp_nlt_f32_e32 vcc, s70, v182
	v_ldexp_f32 v184, v184, v185
	s_nop 0
	v_cndmask_b32_e32 v184, 0, v184, vcc
	v_cmp_ngt_f32_e32 vcc, s71, v182
	s_nop 1
	v_cndmask_b32_e32 v184, v178, v184, vcc
	v_sub_f32_e32 v184, 1.0, v184
	v_mul_f32_e32 v183, v180, v180
	v_fmamk_f32 v185, v183, 0xba1345e1, v176
	v_fmaak_f32 v185, v183, v185, 0xbcdac9b8
	v_fmaak_f32 v185, v183, v185, 0x3de703be
	v_fmaak_f32 v185, v183, v185, 0xbec09330
	v_fmaak_f32 v183, v183, v185, 0x3e0375d0
	v_fma_f32 v183, |v180|, v183, |v180|
	v_cmp_nlt_f32_e64 vcc, |v180|, 1.0
	s_nop 1
	v_cndmask_b32_e32 v184, v183, v184, vcc
	v_bfi_b32 v184, s14, v184, v180
	v_add_f32_e32 v184, 1.0, v184
	v_mul_f32_e32 v95, 0.5, v95
	v_mul_f32_e32 v75, v75, v79
	v_mul_f32_e32 v95, v95, v184
	v_mul_f32_e32 v95, v75, v95
	global_store_dword v193, v94, s[12:13]
	global_store_dword v193, v95, s[12:13] offset:256
	s_add_u32 s12, s12, s18
	s_addc_u32 s13, s13, 0
	s_lshl_b32 s17, s92, 6
	s_add_u32 s69, s69, s17
	s_cmpk_lt_u32 s69, 0x8000
	s_cbranch_scc1 .Lgu0_chunk
	s_branch .LBB0_578

.Lgv0_chunk:
	s_movk_i32 s100, 0xc0
	s_lshl_b32 s16, s92, 14
	s_add_u32 s12, s26, 0xd800000
	s_addc_u32 s13, s27, 0
	s_lshl_b32 s15, s101, 9
	s_add_u32 s12, s12, s15
	s_addc_u32 s13, s13, 0
	s_lshl_b32 s18, s92, 11
	global_load_dword v64, v196, s[12:13]
	global_load_dword v65, v196, s[12:13] offset:256
	s_add_u32 s12, s12, s18
	s_addc_u32 s13, s13, 0
	global_load_dword v66, v196, s[12:13]
	global_load_dword v67, v196, s[12:13] offset:256
	s_add_u32 s12, s12, s18
	s_addc_u32 s13, s13, 0
	global_load_dword v68, v196, s[12:13]
	global_load_dword v69, v196, s[12:13] offset:256
	s_add_u32 s12, s12, s18
	s_addc_u32 s13, s13, 0
	global_load_dword v70, v196, s[12:13]
	global_load_dword v71, v196, s[12:13] offset:256
	s_add_u32 s12, s12, s18
	s_addc_u32 s13, s13, 0
	global_load_dword v72, v196, s[12:13]
	global_load_dword v73, v196, s[12:13] offset:256
	s_add_u32 s12, s12, s18
	s_addc_u32 s13, s13, 0
	global_load_dword v74, v196, s[12:13]
	global_load_dword v75, v196, s[12:13] offset:256
	s_add_u32 s12, s12, s18
	s_addc_u32 s13, s13, 0
	global_load_dword v76, v196, s[12:13]
	global_load_dword v77, v196, s[12:13] offset:256
	s_add_u32 s12, s12, s18
	s_addc_u32 s13, s13, 0
	global_load_dword v78, v196, s[12:13]
	global_load_dword v79, v196, s[12:13] offset:256
	s_add_u32 s12, s12, s18
	s_addc_u32 s13, s13, 0
	global_load_dword v80, v196, s[12:13]
	global_load_dword v81, v196, s[12:13] offset:256
	s_add_u32 s12, s12, s18
	s_addc_u32 s13, s13, 0
	global_load_dword v82, v196, s[12:13]
	global_load_dword v83, v196, s[12:13] offset:256
	s_add_u32 s12, s12, s18
	s_addc_u32 s13, s13, 0
	global_load_dword v84, v196, s[12:13]
	global_load_dword v85, v196, s[12:13] offset:256
	s_add_u32 s12, s12, s18
	s_addc_u32 s13, s13, 0
	global_load_dword v86, v196, s[12:13]
	global_load_dword v87, v196, s[12:13] offset:256
	s_add_u32 s12, s12, s18
	s_addc_u32 s13, s13, 0
	global_load_dword v88, v196, s[12:13]
	global_load_dword v89, v196, s[12:13] offset:256
	s_add_u32 s12, s12, s18
	s_addc_u32 s13, s13, 0
	global_load_dword v90, v196, s[12:13]
	global_load_dword v91, v196, s[12:13] offset:256
	s_add_u32 s12, s12, s18
	s_addc_u32 s13, s13, 0
	global_load_dword v92, v196, s[12:13]
	global_load_dword v93, v196, s[12:13] offset:256
	s_add_u32 s12, s12, s18
	s_addc_u32 s13, s13, 0
	global_load_dword v94, v196, s[12:13]
	global_load_dword v95, v196, s[12:13] offset:256
	s_add_u32 s12, s12, s18
	s_addc_u32 s13, s13, 0
	s_waitcnt vmcnt(0)
	ds_write2st64_b32 v206, v64, v65 offset0:0 offset1:1
	ds_write2st64_b32 v206, v66, v67 offset0:2 offset1:3
	ds_write2st64_b32 v206, v68, v69 offset0:4 offset1:5
	ds_write2st64_b32 v206, v70, v71 offset0:6 offset1:7
	ds_write2st64_b32 v206, v72, v73 offset0:8 offset1:9
	ds_write2st64_b32 v206, v74, v75 offset0:10 offset1:11
	ds_write2st64_b32 v206, v76, v77 offset0:12 offset1:13
	ds_write2st64_b32 v206, v78, v79 offset0:14 offset1:15
	ds_write2st64_b32 v206, v80, v81 offset0:16 offset1:17
	ds_write2st64_b32 v206, v82, v83 offset0:18 offset1:19
	ds_write2st64_b32 v206, v84, v85 offset0:20 offset1:21
	ds_write2st64_b32 v206, v86, v87 offset0:22 offset1:23
	ds_write2st64_b32 v206, v88, v89 offset0:24 offset1:25
	ds_write2st64_b32 v206, v90, v91 offset0:26 offset1:27
	ds_write2st64_b32 v206, v92, v93 offset0:28 offset1:29
	ds_write2st64_b32 v206, v94, v95 offset0:30 offset1:31
	s_add_u32 s12, s26, 0xf800000
	s_addc_u32 s13, s27, 0
	s_lshl_b32 s15, s101, 9
	s_add_u32 s12, s12, s15
	s_addc_u32 s13, s13, 0
	s_lshl_b32 s18, s92, 11
	global_load_dword v64, v196, s[12:13]
	global_load_dword v65, v196, s[12:13] offset:256
	s_add_u32 s12, s12, s18
	s_addc_u32 s13, s13, 0
	global_load_dword v66, v196, s[12:13]
	global_load_dword v67, v196, s[12:13] offset:256
	s_add_u32 s12, s12, s18
	s_addc_u32 s13, s13, 0
	global_load_dword v68, v196, s[12:13]
	global_load_dword v69, v196, s[12:13] offset:256
	s_add_u32 s12, s12, s18
	s_addc_u32 s13, s13, 0
	global_load_dword v70, v196, s[12:13]
	global_load_dword v71, v196, s[12:13] offset:256
	s_add_u32 s12, s12, s18
	s_addc_u32 s13, s13, 0
	global_load_dword v72, v196, s[12:13]
	global_load_dword v73, v196, s[12:13] offset:256
	s_add_u32 s12, s12, s18
	s_addc_u32 s13, s13, 0
	global_load_dword v74, v196, s[12:13]
	global_load_dword v75, v196, s[12:13] offset:256
	s_add_u32 s12, s12, s18
	s_addc_u32 s13, s13, 0
	global_load_dword v76, v196, s[12:13]
	global_load_dword v77, v196, s[12:13] offset:256
	s_add_u32 s12, s12, s18
	s_addc_u32 s13, s13, 0
	global_load_dword v78, v196, s[12:13]
	global_load_dword v79, v196, s[12:13] offset:256
	s_add_u32 s12, s12, s18
	s_addc_u32 s13, s13, 0
	global_load_dword v80, v196, s[12:13]
	global_load_dword v81, v196, s[12:13] offset:256
	s_add_u32 s12, s12, s18
	s_addc_u32 s13, s13, 0
	global_load_dword v82, v196, s[12:13]
	global_load_dword v83, v196, s[12:13] offset:256
	s_add_u32 s12, s12, s18
	s_addc_u32 s13, s13, 0
	global_load_dword v84, v196, s[12:13]
	global_load_dword v85, v196, s[12:13] offset:256
	s_add_u32 s12, s12, s18
	s_addc_u32 s13, s13, 0
	global_load_dword v86, v196, s[12:13]
	global_load_dword v87, v196, s[12:13] offset:256
	s_add_u32 s12, s12, s18
	s_addc_u32 s13, s13, 0
	global_load_dword v88, v196, s[12:13]
	global_load_dword v89, v196, s[12:13] offset:256
	s_add_u32 s12, s12, s18
	s_addc_u32 s13, s13, 0
	global_load_dword v90, v196, s[12:13]
	global_load_dword v91, v196, s[12:13] offset:256
	s_add_u32 s12, s12, s18
	s_addc_u32 s13, s13, 0
	global_load_dword v92, v196, s[12:13]
	global_load_dword v93, v196, s[12:13] offset:256
	s_add_u32 s12, s12, s18
	s_addc_u32 s13, s13, 0
	global_load_dword v94, v196, s[12:13]
	global_load_dword v95, v196, s[12:13] offset:256
	s_add_u32 s12, s12, s18
	s_addc_u32 s13, s13, 0
	s_waitcnt vmcnt(0)
	ds_write2st64_b32 v208, v64, v65 offset0:0 offset1:1
	ds_write2st64_b32 v208, v66, v67 offset0:2 offset1:3
	ds_write2st64_b32 v208, v68, v69 offset0:4 offset1:5
	ds_write2st64_b32 v208, v70, v71 offset0:6 offset1:7
	ds_write2st64_b32 v208, v72, v73 offset0:8 offset1:9
	ds_write2st64_b32 v208, v74, v75 offset0:10 offset1:11
	ds_write2st64_b32 v208, v76, v77 offset0:12 offset1:13
	ds_write2st64_b32 v208, v78, v79 offset0:14 offset1:15
	ds_write2st64_b32 v208, v80, v81 offset0:16 offset1:17
	ds_write2st64_b32 v208, v82, v83 offset0:18 offset1:19
	ds_write2st64_b32 v208, v84, v85 offset0:20 offset1:21
	ds_write2st64_b32 v208, v86, v87 offset0:22 offset1:23
	ds_write2st64_b32 v208, v88, v89 offset0:24 offset1:25
	ds_write2st64_b32 v208, v90, v91 offset0:26 offset1:27
	ds_write2st64_b32 v208, v92, v93 offset0:28 offset1:29
	ds_write2st64_b32 v208, v94, v95 offset0:30 offset1:31
	s_waitcnt lgkmcnt(0)
	v_mov_b32_e32 v209, 0x12000
	ds_read_b32 v212, v209
	s_waitcnt lgkmcnt(0)
	v_readfirstlane_b32 s13, v212
	s_nop 3
	s_lshl_b32 s13, s13, 2
	s_mov_b32 s14, 0
	s_mov_b32 s18, 0
	s_and_b32 s19, s18, 15
	s_lshr_b32 s98, s18, 4
	s_lshl_b32 s99, s19, 9
	s_mul_i32 s15, s19, s16
	s_lshl_b32 s18, s98, 7
	s_add_u32 s15, s15, s18
	s_lshl_b32 s18, s101, 12
	s_add_u32 s15, s15, s18
	s_add_u32 s8, s24, s15
	s_addc_u32 s9, s25, 0
	s_mul_i32 s15, s98, 0x300000
	s_add_u32 s4, s26, 0x3800000
	s_addc_u32 s5, s27, 0
	s_add_u32 s4, s4, s15
	s_addc_u32 s5, s5, 0
	v_add_u32_e32 v201, s99, v197
	v_add_u32_e32 v203, s99, v198
	ds_read2_b32 v[160:161], v201 offset0:0 offset1:8
	ds_read2_b32 v[162:163], v201 offset0:16 offset1:24
	s_waitcnt lgkmcnt(0)
	v_mad_u32_u24 v160, v160, s100, v199
	v_mad_u32_u24 v161, v161, s100, v199
	v_mad_u32_u24 v162, v162, s100, v199
	v_mad_u32_u24 v163, v163, s100, v199
	global_load_dwordx4 v[64:67], v160, s[4:5]
	global_load_dwordx2 v[68:69], v160, s[4:5] offset:16
	global_load_dwordx4 v[70:73], v161, s[4:5]
	global_load_dwordx2 v[74:75], v161, s[4:5] offset:16
	global_load_dwordx4 v[76:79], v162, s[4:5]
	global_load_dwordx2 v[80:81], v162, s[4:5] offset:16
	global_load_dwordx4 v[82:85], v163, s[4:5]
	global_load_dwordx2 v[86:87], v163, s[4:5] offset:16
	ds_read2_b32 v[168:169], v201 offset0:32 offset1:40
	ds_read2_b32 v[170:171], v201 offset0:48 offset1:56
	s_waitcnt lgkmcnt(0)
	v_mad_u32_u24 v168, v168, s100, v199
	v_mad_u32_u24 v169, v169, s100, v199
	v_mad_u32_u24 v170, v170, s100, v199
	v_mad_u32_u24 v171, v171, s100, v199
	global_load_dwordx4 v[88:91], v168, s[4:5]
	global_load_dwordx2 v[92:93], v168, s[4:5] offset:16
	global_load_dwordx4 v[94:97], v169, s[4:5]
	global_load_dwordx2 v[98:99], v169, s[4:5] offset:16
	global_load_dwordx4 v[100:103], v170, s[4:5]
	global_load_dwordx2 v[104:105], v170, s[4:5] offset:16
	global_load_dwordx4 v[106:109], v171, s[4:5]
	global_load_dwordx2 v[110:111], v171, s[4:5] offset:16
	ds_read2_b32 v[160:161], v201 offset0:64 offset1:72
	ds_read2_b32 v[162:163], v201 offset0:80 offset1:88
	s_waitcnt lgkmcnt(0)
	v_mad_u32_u24 v160, v160, s100, v199
	v_mad_u32_u24 v161, v161, s100, v199
	v_mad_u32_u24 v162, v162, s100, v199
	v_mad_u32_u24 v163, v163, s100, v199
	global_load_dwordx4 v[112:115], v160, s[4:5]
	global_load_dwordx2 v[116:117], v160, s[4:5] offset:16
	global_load_dwordx4 v[118:121], v161, s[4:5]
	global_load_dwordx2 v[122:123], v161, s[4:5] offset:16
	global_load_dwordx4 v[124:127], v162, s[4:5]
	global_load_dwordx2 v[128:129], v162, s[4:5] offset:16
	global_load_dwordx4 v[130:133], v163, s[4:5]
	global_load_dwordx2 v[134:135], v163, s[4:5] offset:16
	ds_read2_b32 v[168:169], v201 offset0:96 offset1:104
	ds_read2_b32 v[170:171], v201 offset0:112 offset1:120
	s_waitcnt lgkmcnt(0)
	v_mad_u32_u24 v168, v168, s100, v199
	v_mad_u32_u24 v169, v169, s100, v199
	v_mad_u32_u24 v170, v170, s100, v199
	v_mad_u32_u24 v171, v171, s100, v199
	global_load_dwordx4 v[136:139], v168, s[4:5]
	global_load_dwordx2 v[140:141], v168, s[4:5] offset:16
	global_load_dwordx4 v[142:145], v169, s[4:5]
	global_load_dwordx2 v[146:147], v169, s[4:5] offset:16
	global_load_dwordx4 v[148:151], v170, s[4:5]
	global_load_dwordx2 v[152:153], v170, s[4:5] offset:16
	global_load_dwordx4 v[154:157], v171, s[4:5]
	global_load_dwordx2 v[158:159], v171, s[4:5] offset:16
	global_load_dword v209, v200, s[8:9]
	ds_read2_b32 v[176:177], v203 offset0:0 offset1:8
	ds_read2_b32 v[178:179], v203 offset0:16 offset1:24
	s_mov_b32 s18, 1
	s_and_b32 s19, s18, 15
	s_lshr_b32 s98, s18, 4
	s_lshl_b32 s99, s19, 9
	s_mul_i32 s15, s19, s16
	s_lshl_b32 s18, s98, 7
	s_add_u32 s15, s15, s18
	s_lshl_b32 s18, s101, 12
	s_add_u32 s15, s15, s18
	s_add_u32 s10, s24, s15
	s_addc_u32 s11, s25, 0
	s_mul_i32 s15, s98, 0x300000
	s_add_u32 s4, s26, 0x3800000
	s_addc_u32 s5, s27, 0
	s_add_u32 s4, s4, s15
	s_addc_u32 s5, s5, 0
	v_add_u32_e32 v202, s99, v197
	v_add_u32_e32 v204, s99, v198
	ds_read2_b32 v[160:161], v202 offset0:0 offset1:8
	ds_read2_b32 v[162:163], v202 offset0:16 offset1:24
	s_waitcnt lgkmcnt(0)

.Lgu1_start:
	s_mov_b64 exec, -1
	v_and_b32_e32 v0, 63, v205
	v_lshrrev_b32_e32 v1, 6, v205
	v_lshlrev_b32_e32 v193, 2, v0
	v_readfirstlane_b32 s34, v1
	v_and_b32_e32 v1, 3, v0
	v_lshlrev_b32_e32 v196, 4, v1
	v_mul_u32_u24_e32 v197, 48, v1
	s_nop 3
	s_lshl_b32 s13, s34, 14
	s_add_i32 s35, s93, s34
	v_and_b32_e32 v1, 3, v0
	v_lshlrev_b32_e32 v195, 4, v1
	v_lshrrev_b32_e32 v1, 2, v0
	v_add_u32_e32 v195, v195, v1
	v_lshl_add_u32 v195, v195, 2, s13
	v_lshrrev_b32_e32 v1, 2, v0
	v_lshl_add_u32 v194, v1, 2, s13
	v_add_u32_e32 v194, 0x2000, v194
	v_lshl_add_u32 v198, v0, 4, s13
	v_add_u32_e32 v200, s13, v193
	v_add_u32_e32 v199, 0x2000, v200
	v_lshrrev_b32_e32 v114, 3, v0
	v_lshlrev_b32_e32 v114, 8, v114
	v_and_b32_e32 v1, 7, v0
	v_lshl_add_u32 v114, v1, 3, v114
	s_lshl_b32 s14, s34, 9
	s_add_u32 s14, s14, 0x10000
	v_lshl_add_u32 v115, v0, 3, s14
	v_and_b32_e32 v1, 3, v0
	v_lshl_add_u32 v116, v1, 4, s14
.Lgu1_chunk:
	s_movk_i32 s18, 0xc0
	s_lshl_b32 s19, s92, 13
	s_mov_b32 s38, 0x11111111
	s_mov_b32 s39, 0x11111111
	s_mov_b32 s10, 0x22222222
	s_mov_b32 s11, 0x22222222
	s_mov_b32 s100, 0x44444444
	s_mov_b32 s101, 0x44444444
	s_mov_b32 s98, 0x88888888
	s_mov_b32 s99, 0x88888888
	s_add_u32 s6, s26, 0xd800000
	s_addc_u32 s7, s27, 0
	s_lshl_b32 s13, s35, 9
	s_add_u32 s6, s6, s13
	s_addc_u32 s7, s7, 0
	s_lshl_b32 s14, s92, 11
	global_load_dword v16, v193, s[6:7]
	global_load_dword v17, v193, s[6:7] offset:256
	s_add_u32 s6, s6, s14
	s_addc_u32 s7, s7, 0
	global_load_dword v18, v193, s[6:7]
	global_load_dword v19, v193, s[6:7] offset:256
	s_add_u32 s6, s6, s14
	s_addc_u32 s7, s7, 0
	global_load_dword v20, v193, s[6:7]
	global_load_dword v21, v193, s[6:7] offset:256
	s_add_u32 s6, s6, s14
	s_addc_u32 s7, s7, 0
	global_load_dword v22, v193, s[6:7]
	global_load_dword v23, v193, s[6:7] offset:256
	s_add_u32 s6, s6, s14
	s_addc_u32 s7, s7, 0
	global_load_dword v24, v193, s[6:7]
	global_load_dword v25, v193, s[6:7] offset:256
	s_add_u32 s6, s6, s14
	s_addc_u32 s7, s7, 0
	global_load_dword v26, v193, s[6:7]
	global_load_dword v27, v193, s[6:7] offset:256
	s_add_u32 s6, s6, s14
	s_addc_u32 s7, s7, 0
	global_load_dword v28, v193, s[6:7]
	global_load_dword v29, v193, s[6:7] offset:256
	s_add_u32 s6, s6, s14
	s_addc_u32 s7, s7, 0
	global_load_dword v30, v193, s[6:7]
	global_load_dword v31, v193, s[6:7] offset:256
	s_add_u32 s6, s6, s14
	s_addc_u32 s7, s7, 0
	global_load_dword v32, v193, s[6:7]
	global_load_dword v33, v193, s[6:7] offset:256
	s_add_u32 s6, s6, s14
	s_addc_u32 s7, s7, 0
	global_load_dword v34, v193, s[6:7]
	global_load_dword v35, v193, s[6:7] offset:256
	s_add_u32 s6, s6, s14
	s_addc_u32 s7, s7, 0
	global_load_dword v36, v193, s[6:7]
	global_load_dword v37, v193, s[6:7] offset:256
	s_add_u32 s6, s6, s14
	s_addc_u32 s7, s7, 0
	global_load_dword v38, v193, s[6:7]
	global_load_dword v39, v193, s[6:7] offset:256
	s_add_u32 s6, s6, s14
	s_addc_u32 s7, s7, 0
	global_load_dword v40, v193, s[6:7]
	global_load_dword v41, v193, s[6:7] offset:256
	s_add_u32 s6, s6, s14
	s_addc_u32 s7, s7, 0
	global_load_dword v42, v193, s[6:7]
	global_load_dword v43, v193, s[6:7] offset:256
	s_add_u32 s6, s6, s14
	s_addc_u32 s7, s7, 0
	global_load_dword v44, v193, s[6:7]
	global_load_dword v45, v193, s[6:7] offset:256
	s_add_u32 s6, s6, s14
	s_addc_u32 s7, s7, 0
	global_load_dword v46, v193, s[6:7]
	global_load_dword v47, v193, s[6:7] offset:256
	s_add_u32 s6, s6, s14
	s_addc_u32 s7, s7, 0
	v_mov_b32_e32 v0, 0
	v_mov_b32_e32 v1, 0
	v_mov_b32_e32 v2, 0
	v_mov_b32_e32 v3, 0
	ds_write_b128 v198, v[0:3] offset:0
	ds_write_b128 v198, v[0:3] offset:1024
	ds_write_b128 v198, v[0:3] offset:2048
	ds_write_b128 v198, v[0:3] offset:3072
	ds_write_b128 v198, v[0:3] offset:4096
	ds_write_b128 v198, v[0:3] offset:5120
	ds_write_b128 v198, v[0:3] offset:6144
	ds_write_b128 v198, v[0:3] offset:7168
	s_waitcnt vmcnt(0)
	ds_write2st64_b32 v199, v16, v17 offset0:0 offset1:1
	ds_write2st64_b32 v199, v18, v19 offset0:2 offset1:3
	ds_write2st64_b32 v199, v20, v21 offset0:4 offset1:5
	ds_write2st64_b32 v199, v22, v23 offset0:6 offset1:7
	ds_write2st64_b32 v199, v24, v25 offset0:8 offset1:9
	ds_write2st64_b32 v199, v26, v27 offset0:10 offset1:11
	ds_write2st64_b32 v199, v28, v29 offset0:12 offset1:13
	ds_write2st64_b32 v199, v30, v31 offset0:14 offset1:15
	ds_write2st64_b32 v199, v32, v33 offset0:16 offset1:17
	ds_write2st64_b32 v199, v34, v35 offset0:18 offset1:19
	ds_write2st64_b32 v199, v36, v37 offset0:20 offset1:21
	ds_write2st64_b32 v199, v38, v39 offset0:22 offset1:23
	ds_write2st64_b32 v199, v40, v41 offset0:24 offset1:25
	ds_write2st64_b32 v199, v42, v43 offset0:26 offset1:27
	ds_write2st64_b32 v199, v44, v45 offset0:28 offset1:29
	ds_write2st64_b32 v199, v46, v47 offset0:30 offset1:31
	s_waitcnt lgkmcnt(0)
	s_add_u32 s0, s26, 0x2800000
	s_addc_u32 s1, s27, 0
	s_add_u32 s4, s26, 0x5800000
	s_addc_u32 s5, s27, 0
	s_lshl_b32 s13, s35, 11
	s_add_u32 s4, s4, s13
	s_addc_u32 s5, s5, 0
	s_mov_b32 s12, 0
	s_and_b32 s15, s12, 15
	s_lshr_b32 s16, s12, 4
	s_lshl_b32 s17, s15, 9
	s_mul_i32 s13, s15, s19
	s_lshl_b32 s14, s16, 6
	s_add_u32 s13, s13, s14
	s_add_u32 s6, s4, s13
	s_addc_u32 s7, s5, 0
	s_mul_i32 s13, s16, 0x300000
	s_add_u32 s0, s26, 0x2800000
	s_addc_u32 s1, s27, 0
	s_add_u32 s0, s0, s13
	s_addc_u32 s1, s1, 0
	v_add_u32_e32 v201, s17, v194
	ds_read2_b32 v[184:185], v201 offset0:0 offset1:16
	ds_read2_b32 v[186:187], v201 offset0:32 offset1:48
	ds_read2_b32 v[188:189], v201 offset0:64 offset1:80
	ds_read2_b32 v[190:191], v201 offset0:96 offset1:112
	global_load_dwordx2 v[112:113], v114, s[6:7]
	s_waitcnt lgkmcnt(0)
	v_mad_u32_u24 v184, v184, s18, v197
	v_mad_u32_u24 v185, v185, s18, v197
	global_load_dwordx4 v[16:19], v184, s[0:1]
	global_load_dwordx4 v[20:23], v184, s[0:1] offset:16
	global_load_dwordx4 v[24:27], v184, s[0:1] offset:32
	global_load_dwordx4 v[28:31], v185, s[0:1]
	global_load_dwordx4 v[32:35], v185, s[0:1] offset:16
	global_load_dwordx4 v[36:39], v185, s[0:1] offset:32
	v_mad_u32_u24 v186, v186, s18, v197
	v_mad_u32_u24 v187, v187, s18, v197
	global_load_dwordx4 v[40:43], v186, s[0:1]
	global_load_dwordx4 v[44:47], v186, s[0:1] offset:16
	global_load_dwordx4 v[48:51], v186, s[0:1] offset:32
	global_load_dwordx4 v[52:55], v187, s[0:1]
	global_load_dwordx4 v[56:59], v187, s[0:1] offset:16
	global_load_dwordx4 v[60:63], v187, s[0:1] offset:32
	v_mad_u32_u24 v188, v188, s18, v197
	v_mad_u32_u24 v189, v189, s18, v197
	global_load_dwordx4 v[64:67], v188, s[0:1]
	global_load_dwordx4 v[68:71], v188, s[0:1] offset:16
	global_load_dwordx4 v[72:75], v188, s[0:1] offset:32
	global_load_dwordx4 v[76:79], v189, s[0:1]
	global_load_dwordx4 v[80:83], v189, s[0:1] offset:16
	global_load_dwordx4 v[84:87], v189, s[0:1] offset:32
	v_mad_u32_u24 v190, v190, s18, v197
	v_mad_u32_u24 v191, v191, s18, v197
	global_load_dwordx4 v[88:91], v190, s[0:1]
	global_load_dwordx4 v[92:95], v190, s[0:1] offset:16
	global_load_dwordx4 v[96:99], v190, s[0:1] offset:32
	global_load_dwordx4 v[100:103], v191, s[0:1]
	global_load_dwordx4 v[104:107], v191, s[0:1] offset:16
	global_load_dwordx4 v[108:111], v191, s[0:1] offset:32
	s_mov_b32 s14, 1
	s_and_b32 s15, s14, 15
	s_lshr_b32 s16, s14, 4
	s_lshl_b32 s17, s15, 9
	s_mul_i32 s13, s15, s19
	s_lshl_b32 s14, s16, 6
	s_add_u32 s13, s13, s14
	s_add_u32 s8, s4, s13
	s_addc_u32 s9, s5, 0
	s_mul_i32 s13, s16, 0x300000
	s_add_u32 s0, s26, 0x2800000
	s_addc_u32 s1, s27, 0
	s_add_u32 s0, s0, s13
	s_addc_u32 s1, s1, 0
	v_add_u32_e32 v202, s17, v194
	ds_read2_b32 v[184:185], v202 offset0:0 offset1:16
	ds_read2_b32 v[186:187], v202 offset0:32 offset1:48
	ds_read2_b32 v[188:189], v202 offset0:64 offset1:80
	ds_read2_b32 v[190:191], v202 offset0:96 offset1:112
.Lgu1_loop:
	s_and_b32 s15, s12, 15
	s_lshl_b32 s17, s15, 9
	v_add_u32_e32 v203, s17, v195
	s_waitcnt vmcnt(24)
	ds_write_b64 v115, v[112:113]
	ds_read_b128 v[144:147], v116 offset:0
	ds_read_b128 v[148:151], v116 offset:64
	ds_read_b128 v[152:155], v116 offset:128
	ds_read_b128 v[156:159], v116 offset:192
	ds_read_b128 v[160:163], v116 offset:256
	ds_read_b128 v[164:167], v116 offset:320
	ds_read_b128 v[168:171], v116 offset:384
	ds_read_b128 v[172:175], v116 offset:448
	s_waitcnt lgkmcnt(0)
	s_waitcnt vmcnt(21)
	v_cvt_scalef32_pk32_bf16_fp6 v[0:15], v[16:21], 1.0
	v_cvt_scalef32_pk32_bf16_fp6 v[128:143], v[22:27], 1.0
	v_dot2_f32_bf16 v176, v0, v144, 0
	v_dot2_f32_bf16 v177, v1, v145, 0
	v_dot2_f32_bf16 v178, v2, v148, 0
	v_dot2_f32_bf16 v179, v3, v149, 0
	v_dot2c_f32_bf16_e32 v176, v4, v152
	v_dot2c_f32_bf16_e32 v177, v5, v153
	v_dot2c_f32_bf16_e32 v178, v6, v156
	v_dot2c_f32_bf16_e32 v179, v7, v157
	v_dot2c_f32_bf16_e32 v176, v8, v160
	v_dot2c_f32_bf16_e32 v177, v9, v161
	v_dot2c_f32_bf16_e32 v178, v10, v164
	v_dot2c_f32_bf16_e32 v179, v11, v165
	v_dot2c_f32_bf16_e32 v176, v12, v168
	v_dot2c_f32_bf16_e32 v177, v13, v169
	v_dot2c_f32_bf16_e32 v178, v14, v172
	v_dot2c_f32_bf16_e32 v179, v15, v173
	v_dot2c_f32_bf16_e32 v176, v128, v146
	v_dot2c_f32_bf16_e32 v177, v129, v147
	v_dot2c_f32_bf16_e32 v178, v130, v150
	v_dot2c_f32_bf16_e32 v179, v131, v151
	v_dot2c_f32_bf16_e32 v176, v132, v154
	v_dot2c_f32_bf16_e32 v177, v133, v155
	v_dot2c_f32_bf16_e32 v178, v134, v158
	v_dot2c_f32_bf16_e32 v179, v135, v159
	v_dot2c_f32_bf16_e32 v176, v136, v162
	v_dot2c_f32_bf16_e32 v177, v137, v163
	v_dot2c_f32_bf16_e32 v178, v138, v166
	v_dot2c_f32_bf16_e32 v179, v139, v167
	v_dot2c_f32_bf16_e32 v176, v140, v170
	v_dot2c_f32_bf16_e32 v177, v141, v171
	v_dot2c_f32_bf16_e32 v178, v142, v174
	v_dot2c_f32_bf16_e32 v179, v143, v175
	s_waitcnt vmcnt(18)
	v_cvt_scalef32_pk32_bf16_fp6 v[0:15], v[28:33], 1.0
	v_cvt_scalef32_pk32_bf16_fp6 v[128:143], v[34:39], 1.0
	v_dot2_f32_bf16 v180, v0, v144, 0
	v_dot2_f32_bf16 v181, v1, v145, 0
	v_dot2_f32_bf16 v182, v2, v148, 0
	v_dot2_f32_bf16 v183, v3, v149, 0
	v_dot2c_f32_bf16_e32 v180, v4, v152
	v_dot2c_f32_bf16_e32 v181, v5, v153
	v_dot2c_f32_bf16_e32 v182, v6, v156
	v_dot2c_f32_bf16_e32 v183, v7, v157
	v_add_f32_e32 v192, v176, v177
	v_add_f32_e32 v206, v178, v179
	v_add_f32_e32 v192, v192, v206
	s_nop 1
	v_add_f32_dpp v192, v192, v192 quad_perm:[1,0,3,2] row_mask:0xf bank_mask:0xf
	s_nop 1
	v_add_f32_dpp v192, v192, v192 quad_perm:[2,3,0,1] row_mask:0xf bank_mask:0xf
	v_cndmask_b32_e64 v118, v118, v192, s[38:39]
	v_dot2c_f32_bf16_e32 v180, v8, v160
	v_dot2c_f32_bf16_e32 v181, v9, v161
	v_dot2c_f32_bf16_e32 v182, v10, v164
	v_dot2c_f32_bf16_e32 v183, v11, v165
	v_dot2c_f32_bf16_e32 v180, v12, v168
	v_dot2c_f32_bf16_e32 v181, v13, v169
	v_dot2c_f32_bf16_e32 v182, v14, v172
	v_dot2c_f32_bf16_e32 v183, v15, v173
	v_dot2c_f32_bf16_e32 v180, v128, v146
	v_dot2c_f32_bf16_e32 v181, v129, v147
	v_dot2c_f32_bf16_e32 v182, v130, v150
	v_dot2c_f32_bf16_e32 v183, v131, v151
	v_dot2c_f32_bf16_e32 v180, v132, v154
	v_dot2c_f32_bf16_e32 v181, v133, v155
	v_dot2c_f32_bf16_e32 v182, v134, v158
	v_dot2c_f32_bf16_e32 v183, v135, v159
	v_dot2c_f32_bf16_e32 v180, v136, v162
	v_dot2c_f32_bf16_e32 v181, v137, v163
	v_dot2c_f32_bf16_e32 v182, v138, v166
	v_dot2c_f32_bf16_e32 v183, v139, v167
	v_dot2c_f32_bf16_e32 v180, v140, v170
	v_dot2c_f32_bf16_e32 v181, v141, v171
	v_dot2c_f32_bf16_e32 v182, v142, v174
	v_dot2c_f32_bf16_e32 v183, v143, v175
	global_load_dwordx2 v[112:113], v114, s[8:9]
	s_waitcnt lgkmcnt(0)
	v_mad_u32_u24 v184, v184, s18, v197
	v_mad_u32_u24 v185, v185, s18, v197
	global_load_dwordx4 v[16:19], v184, s[0:1]
	global_load_dwordx4 v[20:23], v184, s[0:1] offset:16
	global_load_dwordx4 v[24:27], v184, s[0:1] offset:32
	global_load_dwordx4 v[28:31], v185, s[0:1]
	global_load_dwordx4 v[32:35], v185, s[0:1] offset:16
	global_load_dwordx4 v[36:39], v185, s[0:1] offset:32
	s_waitcnt vmcnt(22)
	v_cvt_scalef32_pk32_bf16_fp6 v[0:15], v[40:45], 1.0
	v_cvt_scalef32_pk32_bf16_fp6 v[128:143], v[46:51], 1.0
	v_dot2_f32_bf16 v176, v0, v144, 0
	v_dot2_f32_bf16 v177, v1, v145, 0
	v_dot2_f32_bf16 v178, v2, v148, 0
	v_dot2_f32_bf16 v179, v3, v149, 0
	v_dot2c_f32_bf16_e32 v176, v4, v152
	v_dot2c_f32_bf16_e32 v177, v5, v153
	v_dot2c_f32_bf16_e32 v178, v6, v156
	v_dot2c_f32_bf16_e32 v179, v7, v157
	v_add_f32_e32 v192, v180, v181
	v_add_f32_e32 v206, v182, v183
	v_add_f32_e32 v192, v192, v206
	s_nop 1
	v_add_f32_dpp v192, v192, v192 quad_perm:[1,0,3,2] row_mask:0xf bank_mask:0xf
	s_nop 1
	v_add_f32_dpp v192, v192, v192 quad_perm:[2,3,0,1] row_mask:0xf bank_mask:0xf
	v_cndmask_b32_e64 v118, v118, v192, s[10:11]
	v_dot2c_f32_bf16_e32 v176, v8, v160
	v_dot2c_f32_bf16_e32 v177, v9, v161
	v_dot2c_f32_bf16_e32 v178, v10, v164
	v_dot2c_f32_bf16_e32 v179, v11, v165
	v_dot2c_f32_bf16_e32 v176, v12, v168
	v_dot2c_f32_bf16_e32 v177, v13, v169
	v_dot2c_f32_bf16_e32 v178, v14, v172
	v_dot2c_f32_bf16_e32 v179, v15, v173
	v_dot2c_f32_bf16_e32 v176, v128, v146
	v_dot2c_f32_bf16_e32 v177, v129, v147
	v_dot2c_f32_bf16_e32 v178, v130, v150
	v_dot2c_f32_bf16_e32 v179, v131, v151
	v_dot2c_f32_bf16_e32 v176, v132, v154
	v_dot2c_f32_bf16_e32 v177, v133, v155
	v_dot2c_f32_bf16_e32 v178, v134, v158
	v_dot2c_f32_bf16_e32 v179, v135, v159
	v_dot2c_f32_bf16_e32 v176, v136, v162
	v_dot2c_f32_bf16_e32 v177, v137, v163
	v_dot2c_f32_bf16_e32 v178, v138, v166
	v_dot2c_f32_bf16_e32 v179, v139, v167
	v_dot2c_f32_bf16_e32 v176, v140, v170
	v_dot2c_f32_bf16_e32 v177, v141, v171
	v_dot2c_f32_bf16_e32 v178, v142, v174
	v_dot2c_f32_bf16_e32 v179, v143, v175
	s_waitcnt vmcnt(19)
	v_cvt_scalef32_pk32_bf16_fp6 v[0:15], v[52:57], 1.0
	v_cvt_scalef32_pk32_bf16_fp6 v[128:143], v[58:63], 1.0
	v_dot2_f32_bf16 v180, v0, v144, 0
	v_dot2_f32_bf16 v181, v1, v145, 0
	v_dot2_f32_bf16 v182, v2, v148, 0
	v_dot2_f32_bf16 v183, v3, v149, 0
	v_dot2c_f32_bf16_e32 v180, v4, v152
	v_dot2c_f32_bf16_e32 v181, v5, v153
	v_dot2c_f32_bf16_e32 v182, v6, v156
	v_dot2c_f32_bf16_e32 v183, v7, v157
	v_add_f32_e32 v192, v176, v177
	v_add_f32_e32 v206, v178, v179
	v_add_f32_e32 v192, v192, v206
	s_nop 1
	v_add_f32_dpp v192, v192, v192 quad_perm:[1,0,3,2] row_mask:0xf bank_mask:0xf
	s_nop 1
	v_add_f32_dpp v192, v192, v192 quad_perm:[2,3,0,1] row_mask:0xf bank_mask:0xf
	v_cndmask_b32_e64 v118, v118, v192, s[100:101]
	v_dot2c_f32_bf16_e32 v180, v8, v160
	v_dot2c_f32_bf16_e32 v181, v9, v161
	v_dot2c_f32_bf16_e32 v182, v10, v164
	v_dot2c_f32_bf16_e32 v183, v11, v165
	v_dot2c_f32_bf16_e32 v180, v12, v168
	v_dot2c_f32_bf16_e32 v181, v13, v169
	v_dot2c_f32_bf16_e32 v182, v14, v172
	v_dot2c_f32_bf16_e32 v183, v15, v173
	v_dot2c_f32_bf16_e32 v180, v128, v146
	v_dot2c_f32_bf16_e32 v181, v129, v147
	v_dot2c_f32_bf16_e32 v182, v130, v150
	v_dot2c_f32_bf16_e32 v183, v131, v151
	v_dot2c_f32_bf16_e32 v180, v132, v154
	v_dot2c_f32_bf16_e32 v181, v133, v155
	v_dot2c_f32_bf16_e32 v182, v134, v158
	v_dot2c_f32_bf16_e32 v183, v135, v159
	v_dot2c_f32_bf16_e32 v180, v136, v162
	v_dot2c_f32_bf16_e32 v181, v137, v163
	v_dot2c_f32_bf16_e32 v182, v138, v166
	v_dot2c_f32_bf16_e32 v183, v139, v167
	v_dot2c_f32_bf16_e32 v180, v140, v170
	v_dot2c_f32_bf16_e32 v181, v141, v171
	v_dot2c_f32_bf16_e32 v182, v142, v174
	v_dot2c_f32_bf16_e32 v183, v143, v175
	v_mad_u32_u24 v186, v186, s18, v197
	v_mad_u32_u24 v187, v187, s18, v197
	global_load_dwordx4 v[40:43], v186, s[0:1]
	global_load_dwordx4 v[44:47], v186, s[0:1] offset:16
	global_load_dwordx4 v[48:51], v186, s[0:1] offset:32
	global_load_dwordx4 v[52:55], v187, s[0:1]
	global_load_dwordx4 v[56:59], v187, s[0:1] offset:16
	global_load_dwordx4 v[60:63], v187, s[0:1] offset:32
	s_waitcnt vmcnt(22)
	v_cvt_scalef32_pk32_bf16_fp6 v[0:15], v[64:69], 1.0
	v_cvt_scalef32_pk32_bf16_fp6 v[128:143], v[70:75], 1.0
	v_dot2_f32_bf16 v176, v0, v144, 0
	v_dot2_f32_bf16 v177, v1, v145, 0
	v_dot2_f32_bf16 v178, v2, v148, 0
	v_dot2_f32_bf16 v179, v3, v149, 0
	v_dot2c_f32_bf16_e32 v176, v4, v152
	v_dot2c_f32_bf16_e32 v177, v5, v153
	v_dot2c_f32_bf16_e32 v178, v6, v156
	v_dot2c_f32_bf16_e32 v179, v7, v157
	v_add_f32_e32 v192, v180, v181
	v_add_f32_e32 v206, v182, v183
	v_add_f32_e32 v192, v192, v206
	s_nop 1
	v_add_f32_dpp v192, v192, v192 quad_perm:[1,0,3,2] row_mask:0xf bank_mask:0xf
	s_nop 1
	v_add_f32_dpp v192, v192, v192 quad_perm:[2,3,0,1] row_mask:0xf bank_mask:0xf
	v_cndmask_b32_e64 v118, v118, v192, s[98:99]
	ds_add_f32 v203, v118 offset:0
	v_dot2c_f32_bf16_e32 v176, v8, v160
	v_dot2c_f32_bf16_e32 v177, v9, v161
	v_dot2c_f32_bf16_e32 v178, v10, v164
	v_dot2c_f32_bf16_e32 v179, v11, v165
	v_dot2c_f32_bf16_e32 v176, v12, v168
	v_dot2c_f32_bf16_e32 v177, v13, v169
	v_dot2c_f32_bf16_e32 v178, v14, v172
	v_dot2c_f32_bf16_e32 v179, v15, v173
	v_dot2c_f32_bf16_e32 v176, v128, v146
	v_dot2c_f32_bf16_e32 v177, v129, v147
	v_dot2c_f32_bf16_e32 v178, v130, v150
	v_dot2c_f32_bf16_e32 v179, v131, v151
	v_dot2c_f32_bf16_e32 v176, v132, v154
	v_dot2c_f32_bf16_e32 v177, v133, v155
	v_dot2c_f32_bf16_e32 v178, v134, v158
	v_dot2c_f32_bf16_e32 v179, v135, v159
	v_dot2c_f32_bf16_e32 v176, v136, v162
	v_dot2c_f32_bf16_e32 v177, v137, v163
	v_dot2c_f32_bf16_e32 v178, v138, v166
	v_dot2c_f32_bf16_e32 v179, v139, v167
	v_dot2c_f32_bf16_e32 v176, v140, v170
	v_dot2c_f32_bf16_e32 v177, v141, v171
	v_dot2c_f32_bf16_e32 v178, v142, v174
	v_dot2c_f32_bf16_e32 v179, v143, v175
	s_waitcnt vmcnt(19)
	v_cvt_scalef32_pk32_bf16_fp6 v[0:15], v[76:81], 1.0
	v_cvt_scalef32_pk32_bf16_fp6 v[128:143], v[82:87], 1.0
	v_dot2_f32_bf16 v180, v0, v144, 0
	v_dot2_f32_bf16 v181, v1, v145, 0
	v_dot2_f32_bf16 v182, v2, v148, 0
	v_dot2_f32_bf16 v183, v3, v149, 0
	v_dot2c_f32_bf16_e32 v180, v4, v152
	v_dot2c_f32_bf16_e32 v181, v5, v153
	v_dot2c_f32_bf16_e32 v182, v6, v156
	v_dot2c_f32_bf16_e32 v183, v7, v157
	v_add_f32_e32 v192, v176, v177
	v_add_f32_e32 v206, v178, v179
	v_add_f32_e32 v192, v192, v206
	s_nop 1
	v_add_f32_dpp v192, v192, v192 quad_perm:[1,0,3,2] row_mask:0xf bank_mask:0xf
	s_nop 1
	v_add_f32_dpp v192, v192, v192 quad_perm:[2,3,0,1] row_mask:0xf bank_mask:0xf
	v_cndmask_b32_e64 v119, v119, v192, s[38:39]
	v_dot2c_f32_bf16_e32 v180, v8, v160
	v_dot2c_f32_bf16_e32 v181, v9, v161
	v_dot2c_f32_bf16_e32 v182, v10, v164
	v_dot2c_f32_bf16_e32 v183, v11, v165
	v_dot2c_f32_bf16_e32 v180, v12, v168
	v_dot2c_f32_bf16_e32 v181, v13, v169
	v_dot2c_f32_bf16_e32 v182, v14, v172
	v_dot2c_f32_bf16_e32 v183, v15, v173
	v_dot2c_f32_bf16_e32 v180, v128, v146
	v_dot2c_f32_bf16_e32 v181, v129, v147
	v_dot2c_f32_bf16_e32 v182, v130, v150
	v_dot2c_f32_bf16_e32 v183, v131, v151
	v_dot2c_f32_bf16_e32 v180, v132, v154
	v_dot2c_f32_bf16_e32 v181, v133, v155
	v_dot2c_f32_bf16_e32 v182, v134, v158
	v_dot2c_f32_bf16_e32 v183, v135, v159
	v_dot2c_f32_bf16_e32 v180, v136, v162
	v_dot2c_f32_bf16_e32 v181, v137, v163
	v_dot2c_f32_bf16_e32 v182, v138, v166
	v_dot2c_f32_bf16_e32 v183, v139, v167
	v_dot2c_f32_bf16_e32 v180, v140, v170
	v_dot2c_f32_bf16_e32 v181, v141, v171
	v_dot2c_f32_bf16_e32 v182, v142, v174
	v_dot2c_f32_bf16_e32 v183, v143, v175
	v_mad_u32_u24 v188, v188, s18, v197
	v_mad_u32_u24 v189, v189, s18, v197
	global_load_dwordx4 v[64:67], v188, s[0:1]
	global_load_dwordx4 v[68:71], v188, s[0:1] offset:16
	global_load_dwordx4 v[72:75], v188, s[0:1] offset:32
	global_load_dwordx4 v[76:79], v189, s[0:1]
	global_load_dwordx4 v[80:83], v189, s[0:1] offset:16
	global_load_dwordx4 v[84:87], v189, s[0:1] offset:32
	s_waitcnt vmcnt(22)
	v_cvt_scalef32_pk32_bf16_fp6 v[0:15], v[88:93], 1.0
	v_cvt_scalef32_pk32_bf16_fp6 v[128:143], v[94:99], 1.0
	v_dot2_f32_bf16 v176, v0, v144, 0
	v_dot2_f32_bf16 v177, v1, v145, 0
	v_dot2_f32_bf16 v178, v2, v148, 0
	v_dot2_f32_bf16 v179, v3, v149, 0
	v_dot2c_f32_bf16_e32 v176, v4, v152
	v_dot2c_f32_bf16_e32 v177, v5, v153
	v_dot2c_f32_bf16_e32 v178, v6, v156
	v_dot2c_f32_bf16_e32 v179, v7, v157
	v_add_f32_e32 v192, v180, v181
	v_add_f32_e32 v206, v182, v183
	v_add_f32_e32 v192, v192, v206
	s_nop 1
	v_add_f32_dpp v192, v192, v192 quad_perm:[1,0,3,2] row_mask:0xf bank_mask:0xf
	s_nop 1
	v_add_f32_dpp v192, v192, v192 quad_perm:[2,3,0,1] row_mask:0xf bank_mask:0xf
	v_cndmask_b32_e64 v119, v119, v192, s[10:11]
	v_dot2c_f32_bf16_e32 v176, v8, v160
	v_dot2c_f32_bf16_e32 v177, v9, v161
	v_dot2c_f32_bf16_e32 v178, v10, v164
	v_dot2c_f32_bf16_e32 v179, v11, v165
	v_dot2c_f32_bf16_e32 v176, v12, v168
	v_dot2c_f32_bf16_e32 v177, v13, v169
	v_dot2c_f32_bf16_e32 v178, v14, v172
	v_dot2c_f32_bf16_e32 v179, v15, v173
	v_dot2c_f32_bf16_e32 v176, v128, v146
	v_dot2c_f32_bf16_e32 v177, v129, v147
	v_dot2c_f32_bf16_e32 v178, v130, v150
	v_dot2c_f32_bf16_e32 v179, v131, v151
	v_dot2c_f32_bf16_e32 v176, v132, v154
	v_dot2c_f32_bf16_e32 v177, v133, v155
	v_dot2c_f32_bf16_e32 v178, v134, v158
	v_dot2c_f32_bf16_e32 v179, v135, v159
	v_dot2c_f32_bf16_e32 v176, v136, v162
	v_dot2c_f32_bf16_e32 v177, v137, v163
	v_dot2c_f32_bf16_e32 v178, v138, v166
	v_dot2c_f32_bf16_e32 v179, v139, v167
	v_dot2c_f32_bf16_e32 v176, v140, v170
	v_dot2c_f32_bf16_e32 v177, v141, v171
	v_dot2c_f32_bf16_e32 v178, v142, v174
	v_dot2c_f32_bf16_e32 v179, v143, v175
	s_waitcnt vmcnt(19)
	v_cvt_scalef32_pk32_bf16_fp6 v[0:15], v[100:105], 1.0
	v_cvt_scalef32_pk32_bf16_fp6 v[128:143], v[106:111], 1.0
	v_dot2_f32_bf16 v180, v0, v144, 0
	v_dot2_f32_bf16 v181, v1, v145, 0
	v_dot2_f32_bf16 v182, v2, v148, 0
	v_dot2_f32_bf16 v183, v3, v149, 0
	v_dot2c_f32_bf16_e32 v180, v4, v152
	v_dot2c_f32_bf16_e32 v181, v5, v153
	v_dot2c_f32_bf16_e32 v182, v6, v156
	v_dot2c_f32_bf16_e32 v183, v7, v157
	v_add_f32_e32 v192, v176, v177
	v_add_f32_e32 v206, v178, v179
	v_add_f32_e32 v192, v192, v206
	s_nop 1
	v_add_f32_dpp v192, v192, v192 quad_perm:[1,0,3,2] row_mask:0xf bank_mask:0xf
	s_nop 1
	v_add_f32_dpp v192, v192, v192 quad_perm:[2,3,0,1] row_mask:0xf bank_mask:0xf
	v_cndmask_b32_e64 v119, v119, v192, s[100:101]
	v_dot2c_f32_bf16_e32 v180, v8, v160
	v_dot2c_f32_bf16_e32 v181, v9, v161
	v_dot2c_f32_bf16_e32 v182, v10, v164
	v_dot2c_f32_bf16_e32 v183, v11, v165
	v_dot2c_f32_bf16_e32 v180, v12, v168
	v_dot2c_f32_bf16_e32 v181, v13, v169
	v_dot2c_f32_bf16_e32 v182, v14, v172
	v_dot2c_f32_bf16_e32 v183, v15, v173
	v_dot2c_f32_bf16_e32 v180, v128, v146
	v_dot2c_f32_bf16_e32 v181, v129, v147
	v_dot2c_f32_bf16_e32 v182, v130, v150
	v_dot2c_f32_bf16_e32 v183, v131, v151
	v_dot2c_f32_bf16_e32 v180, v132, v154
	v_dot2c_f32_bf16_e32 v181, v133, v155
	v_dot2c_f32_bf16_e32 v182, v134, v158
	v_dot2c_f32_bf16_e32 v183, v135, v159
	v_dot2c_f32_bf16_e32 v180, v136, v162
	v_dot2c_f32_bf16_e32 v181, v137, v163
	v_dot2c_f32_bf16_e32 v182, v138, v166
	v_dot2c_f32_bf16_e32 v183, v139, v167
	v_dot2c_f32_bf16_e32 v180, v140, v170
	v_dot2c_f32_bf16_e32 v181, v141, v171
	v_dot2c_f32_bf16_e32 v182, v142, v174
	v_dot2c_f32_bf16_e32 v183, v143, v175
	v_mad_u32_u24 v190, v190, s18, v197
	v_mad_u32_u24 v191, v191, s18, v197
	global_load_dwordx4 v[88:91], v190, s[0:1]
	global_load_dwordx4 v[92:95], v190, s[0:1] offset:16
	global_load_dwordx4 v[96:99], v190, s[0:1] offset:32
	global_load_dwordx4 v[100:103], v191, s[0:1]
	global_load_dwordx4 v[104:107], v191, s[0:1] offset:16
	global_load_dwordx4 v[108:111], v191, s[0:1] offset:32
	s_add_u32 s12, s12, 1
	s_and_b32 s12, s12, 63
	s_add_u32 s14, s12, 1
	s_and_b32 s14, s14, 63
	s_and_b32 s15, s14, 15
	s_lshr_b32 s16, s14, 4
	s_lshl_b32 s17, s15, 9
	s_mul_i32 s13, s15, s19
	s_lshl_b32 s14, s16, 6
	s_add_u32 s13, s13, s14
	s_add_u32 s6, s4, s13
	s_addc_u32 s7, s5, 0
	s_mul_i32 s13, s16, 0x300000
	s_add_u32 s0, s26, 0x2800000
	s_addc_u32 s1, s27, 0
	s_add_u32 s0, s0, s13
	s_addc_u32 s1, s1, 0
	v_add_u32_e32 v201, s17, v194
	ds_read2_b32 v[184:185], v201 offset0:0 offset1:16
	ds_read2_b32 v[186:187], v201 offset0:32 offset1:48
	ds_read2_b32 v[188:189], v201 offset0:64 offset1:80
	ds_read2_b32 v[190:191], v201 offset0:96 offset1:112
	v_add_f32_e32 v192, v180, v181
	v_add_f32_e32 v206, v182, v183
	v_add_f32_e32 v192, v192, v206
	s_nop 1
	v_add_f32_dpp v192, v192, v192 quad_perm:[1,0,3,2] row_mask:0xf bank_mask:0xf
	s_nop 1
	v_add_f32_dpp v192, v192, v192 quad_perm:[2,3,0,1] row_mask:0xf bank_mask:0xf
	v_cndmask_b32_e64 v119, v119, v192, s[98:99]
	ds_add_f32 v203, v119 offset:256
	s_and_b32 s15, s12, 15
	s_lshl_b32 s17, s15, 9
	v_add_u32_e32 v204, s17, v195
	s_waitcnt vmcnt(24)
	ds_write_b64 v115, v[112:113]
	ds_read_b128 v[144:147], v116 offset:0
	ds_read_b128 v[148:151], v116 offset:64
	ds_read_b128 v[152:155], v116 offset:128
	ds_read_b128 v[156:159], v116 offset:192
	ds_read_b128 v[160:163], v116 offset:256
	ds_read_b128 v[164:167], v116 offset:320
	ds_read_b128 v[168:171], v116 offset:384
	ds_read_b128 v[172:175], v116 offset:448
	s_waitcnt lgkmcnt(0)
	s_waitcnt vmcnt(21)
	v_cvt_scalef32_pk32_bf16_fp6 v[0:15], v[16:21], 1.0
	v_cvt_scalef32_pk32_bf16_fp6 v[128:143], v[22:27], 1.0
	v_dot2_f32_bf16 v176, v0, v144, 0
	v_dot2_f32_bf16 v177, v1, v145, 0
	v_dot2_f32_bf16 v178, v2, v148, 0
	v_dot2_f32_bf16 v179, v3, v149, 0
	v_dot2c_f32_bf16_e32 v176, v4, v152
	v_dot2c_f32_bf16_e32 v177, v5, v153
	v_dot2c_f32_bf16_e32 v178, v6, v156
	v_dot2c_f32_bf16_e32 v179, v7, v157
	v_dot2c_f32_bf16_e32 v176, v8, v160
	v_dot2c_f32_bf16_e32 v177, v9, v161
	v_dot2c_f32_bf16_e32 v178, v10, v164
	v_dot2c_f32_bf16_e32 v179, v11, v165
	v_dot2c_f32_bf16_e32 v176, v12, v168
	v_dot2c_f32_bf16_e32 v177, v13, v169
	v_dot2c_f32_bf16_e32 v178, v14, v172
	v_dot2c_f32_bf16_e32 v179, v15, v173
	v_dot2c_f32_bf16_e32 v176, v128, v146
	v_dot2c_f32_bf16_e32 v177, v129, v147
	v_dot2c_f32_bf16_e32 v178, v130, v150
	v_dot2c_f32_bf16_e32 v179, v131, v151
	v_dot2c_f32_bf16_e32 v176, v132, v154
	v_dot2c_f32_bf16_e32 v177, v133, v155
	v_dot2c_f32_bf16_e32 v178, v134, v158
	v_dot2c_f32_bf16_e32 v179, v135, v159
	v_dot2c_f32_bf16_e32 v176, v136, v162
	v_dot2c_f32_bf16_e32 v177, v137, v163
	v_dot2c_f32_bf16_e32 v178, v138, v166
	v_dot2c_f32_bf16_e32 v179, v139, v167
	v_dot2c_f32_bf16_e32 v176, v140, v170
	v_dot2c_f32_bf16_e32 v177, v141, v171
	v_dot2c_f32_bf16_e32 v178, v142, v174
	v_dot2c_f32_bf16_e32 v179, v143, v175
	s_waitcnt vmcnt(18)
	v_cvt_scalef32_pk32_bf16_fp6 v[0:15], v[28:33], 1.0
	v_cvt_scalef32_pk32_bf16_fp6 v[128:143], v[34:39], 1.0
	v_dot2_f32_bf16 v180, v0, v144, 0
	v_dot2_f32_bf16 v181, v1, v145, 0
	v_dot2_f32_bf16 v182, v2, v148, 0
	v_dot2_f32_bf16 v183, v3, v149, 0
	v_dot2c_f32_bf16_e32 v180, v4, v152
	v_dot2c_f32_bf16_e32 v181, v5, v153
	v_dot2c_f32_bf16_e32 v182, v6, v156
	v_dot2c_f32_bf16_e32 v183, v7, v157
	v_add_f32_e32 v192, v176, v177
	v_add_f32_e32 v206, v178, v179
	v_add_f32_e32 v192, v192, v206
	s_nop 1
	v_add_f32_dpp v192, v192, v192 quad_perm:[1,0,3,2] row_mask:0xf bank_mask:0xf
	s_nop 1
	v_add_f32_dpp v192, v192, v192 quad_perm:[2,3,0,1] row_mask:0xf bank_mask:0xf
	v_cndmask_b32_e64 v118, v118, v192, s[38:39]
	v_dot2c_f32_bf16_e32 v180, v8, v160
	v_dot2c_f32_bf16_e32 v181, v9, v161
	v_dot2c_f32_bf16_e32 v182, v10, v164
	v_dot2c_f32_bf16_e32 v183, v11, v165
	v_dot2c_f32_bf16_e32 v180, v12, v168
	v_dot2c_f32_bf16_e32 v181, v13, v169
	v_dot2c_f32_bf16_e32 v182, v14, v172
	v_dot2c_f32_bf16_e32 v183, v15, v173
	v_dot2c_f32_bf16_e32 v180, v128, v146
	v_dot2c_f32_bf16_e32 v181, v129, v147
	v_dot2c_f32_bf16_e32 v182, v130, v150
	v_dot2c_f32_bf16_e32 v183, v131, v151
	v_dot2c_f32_bf16_e32 v180, v132, v154
	v_dot2c_f32_bf16_e32 v181, v133, v155
	v_dot2c_f32_bf16_e32 v182, v134, v158
	v_dot2c_f32_bf16_e32 v183, v135, v159
	v_dot2c_f32_bf16_e32 v180, v136, v162
	v_dot2c_f32_bf16_e32 v181, v137, v163
	v_dot2c_f32_bf16_e32 v182, v138, v166
	v_dot2c_f32_bf16_e32 v183, v139, v167
	v_dot2c_f32_bf16_e32 v180, v140, v170
	v_dot2c_f32_bf16_e32 v181, v141, v171
	v_dot2c_f32_bf16_e32 v182, v142, v174
	v_dot2c_f32_bf16_e32 v183, v143, v175
	global_load_dwordx2 v[112:113], v114, s[6:7]
	s_waitcnt lgkmcnt(0)
	v_mad_u32_u24 v184, v184, s18, v197
	v_mad_u32_u24 v185, v185, s18, v197
	global_load_dwordx4 v[16:19], v184, s[0:1]
	global_load_dwordx4 v[20:23], v184, s[0:1] offset:16
	global_load_dwordx4 v[24:27], v184, s[0:1] offset:32
	global_load_dwordx4 v[28:31], v185, s[0:1]
	global_load_dwordx4 v[32:35], v185, s[0:1] offset:16
	global_load_dwordx4 v[36:39], v185, s[0:1] offset:32
	s_waitcnt vmcnt(22)
	v_cvt_scalef32_pk32_bf16_fp6 v[0:15], v[40:45], 1.0
	v_cvt_scalef32_pk32_bf16_fp6 v[128:143], v[46:51], 1.0
	v_dot2_f32_bf16 v176, v0, v144, 0
	v_dot2_f32_bf16 v177, v1, v145, 0
	v_dot2_f32_bf16 v178, v2, v148, 0
	v_dot2_f32_bf16 v179, v3, v149, 0
	v_dot2c_f32_bf16_e32 v176, v4, v152
	v_dot2c_f32_bf16_e32 v177, v5, v153
	v_dot2c_f32_bf16_e32 v178, v6, v156
	v_dot2c_f32_bf16_e32 v179, v7, v157
	v_add_f32_e32 v192, v180, v181
	v_add_f32_e32 v206, v182, v183
	v_add_f32_e32 v192, v192, v206
	s_nop 1
	v_add_f32_dpp v192, v192, v192 quad_perm:[1,0,3,2] row_mask:0xf bank_mask:0xf
	s_nop 1
	v_add_f32_dpp v192, v192, v192 quad_perm:[2,3,0,1] row_mask:0xf bank_mask:0xf
	v_cndmask_b32_e64 v118, v118, v192, s[10:11]
	v_dot2c_f32_bf16_e32 v176, v8, v160
	v_dot2c_f32_bf16_e32 v177, v9, v161
	v_dot2c_f32_bf16_e32 v178, v10, v164
	v_dot2c_f32_bf16_e32 v179, v11, v165
	v_dot2c_f32_bf16_e32 v176, v12, v168
	v_dot2c_f32_bf16_e32 v177, v13, v169
	v_dot2c_f32_bf16_e32 v178, v14, v172
	v_dot2c_f32_bf16_e32 v179, v15, v173
	v_dot2c_f32_bf16_e32 v176, v128, v146
	v_dot2c_f32_bf16_e32 v177, v129, v147
	v_dot2c_f32_bf16_e32 v178, v130, v150
	v_dot2c_f32_bf16_e32 v179, v131, v151
	v_dot2c_f32_bf16_e32 v176, v132, v154
	v_dot2c_f32_bf16_e32 v177, v133, v155
	v_dot2c_f32_bf16_e32 v178, v134, v158
	v_dot2c_f32_bf16_e32 v179, v135, v159
	v_dot2c_f32_bf16_e32 v176, v136, v162
	v_dot2c_f32_bf16_e32 v177, v137, v163
	v_dot2c_f32_bf16_e32 v178, v138, v166
	v_dot2c_f32_bf16_e32 v179, v139, v167
	v_dot2c_f32_bf16_e32 v176, v140, v170
	v_dot2c_f32_bf16_e32 v177, v141, v171
	v_dot2c_f32_bf16_e32 v178, v142, v174
	v_dot2c_f32_bf16_e32 v179, v143, v175
	s_waitcnt vmcnt(19)
	v_cvt_scalef32_pk32_bf16_fp6 v[0:15], v[52:57], 1.0
	v_cvt_scalef32_pk32_bf16_fp6 v[128:143], v[58:63], 1.0
	v_dot2_f32_bf16 v180, v0, v144, 0
	v_dot2_f32_bf16 v181, v1, v145, 0
	v_dot2_f32_bf16 v182, v2, v148, 0
	v_dot2_f32_bf16 v183, v3, v149, 0
	v_dot2c_f32_bf16_e32 v180, v4, v152
	v_dot2c_f32_bf16_e32 v181, v5, v153
	v_dot2c_f32_bf16_e32 v182, v6, v156
	v_dot2c_f32_bf16_e32 v183, v7, v157
	v_add_f32_e32 v192, v176, v177
	v_add_f32_e32 v206, v178, v179
	v_add_f32_e32 v192, v192, v206
	s_nop 1
	v_add_f32_dpp v192, v192, v192 quad_perm:[1,0,3,2] row_mask:0xf bank_mask:0xf
	s_nop 1
	v_add_f32_dpp v192, v192, v192 quad_perm:[2,3,0,1] row_mask:0xf bank_mask:0xf
	v_cndmask_b32_e64 v118, v118, v192, s[100:101]
	v_dot2c_f32_bf16_e32 v180, v8, v160
	v_dot2c_f32_bf16_e32 v181, v9, v161
	v_dot2c_f32_bf16_e32 v182, v10, v164
	v_dot2c_f32_bf16_e32 v183, v11, v165
	v_dot2c_f32_bf16_e32 v180, v12, v168
	v_dot2c_f32_bf16_e32 v181, v13, v169
	v_dot2c_f32_bf16_e32 v182, v14, v172
	v_dot2c_f32_bf16_e32 v183, v15, v173
	v_dot2c_f32_bf16_e32 v180, v128, v146
	v_dot2c_f32_bf16_e32 v181, v129, v147
	v_dot2c_f32_bf16_e32 v182, v130, v150
	v_dot2c_f32_bf16_e32 v183, v131, v151
	v_dot2c_f32_bf16_e32 v180, v132, v154
	v_dot2c_f32_bf16_e32 v181, v133, v155
	v_dot2c_f32_bf16_e32 v182, v134, v158
	v_dot2c_f32_bf16_e32 v183, v135, v159
	v_dot2c_f32_bf16_e32 v180, v136, v162
	v_dot2c_f32_bf16_e32 v181, v137, v163
	v_dot2c_f32_bf16_e32 v182, v138, v166
	v_dot2c_f32_bf16_e32 v183, v139, v167
	v_dot2c_f32_bf16_e32 v180, v140, v170
	v_dot2c_f32_bf16_e32 v181, v141, v171
	v_dot2c_f32_bf16_e32 v182, v142, v174
	v_dot2c_f32_bf16_e32 v183, v143, v175
	v_mad_u32_u24 v186, v186, s18, v197
	v_mad_u32_u24 v187, v187, s18, v197
	global_load_dwordx4 v[40:43], v186, s[0:1]
	global_load_dwordx4 v[44:47], v186, s[0:1] offset:16
	global_load_dwordx4 v[48:51], v186, s[0:1] offset:32
	global_load_dwordx4 v[52:55], v187, s[0:1]
	global_load_dwordx4 v[56:59], v187, s[0:1] offset:16
	global_load_dwordx4 v[60:63], v187, s[0:1] offset:32
	s_waitcnt vmcnt(22)
	v_cvt_scalef32_pk32_bf16_fp6 v[0:15], v[64:69], 1.0
	v_cvt_scalef32_pk32_bf16_fp6 v[128:143], v[70:75], 1.0
	v_dot2_f32_bf16 v176, v0, v144, 0
	v_dot2_f32_bf16 v177, v1, v145, 0
	v_dot2_f32_bf16 v178, v2, v148, 0
	v_dot2_f32_bf16 v179, v3, v149, 0
	v_dot2c_f32_bf16_e32 v176, v4, v152
	v_dot2c_f32_bf16_e32 v177, v5, v153
	v_dot2c_f32_bf16_e32 v178, v6, v156
	v_dot2c_f32_bf16_e32 v179, v7, v157
	v_add_f32_e32 v192, v180, v181
	v_add_f32_e32 v206, v182, v183
	v_add_f32_e32 v192, v192, v206
	s_nop 1
	v_add_f32_dpp v192, v192, v192 quad_perm:[1,0,3,2] row_mask:0xf bank_mask:0xf
	s_nop 1
	v_add_f32_dpp v192, v192, v192 quad_perm:[2,3,0,1] row_mask:0xf bank_mask:0xf
	v_cndmask_b32_e64 v118, v118, v192, s[98:99]
	ds_add_f32 v204, v118 offset:0
	v_dot2c_f32_bf16_e32 v176, v8, v160
	v_dot2c_f32_bf16_e32 v177, v9, v161
	v_dot2c_f32_bf16_e32 v178, v10, v164
	v_dot2c_f32_bf16_e32 v179, v11, v165
	v_dot2c_f32_bf16_e32 v176, v12, v168
	v_dot2c_f32_bf16_e32 v177, v13, v169
	v_dot2c_f32_bf16_e32 v178, v14, v172
	v_dot2c_f32_bf16_e32 v179, v15, v173
	v_dot2c_f32_bf16_e32 v176, v128, v146
	v_dot2c_f32_bf16_e32 v177, v129, v147
	v_dot2c_f32_bf16_e32 v178, v130, v150
	v_dot2c_f32_bf16_e32 v179, v131, v151
	v_dot2c_f32_bf16_e32 v176, v132, v154
	v_dot2c_f32_bf16_e32 v177, v133, v155
	v_dot2c_f32_bf16_e32 v178, v134, v158
	v_dot2c_f32_bf16_e32 v179, v135, v159
	v_dot2c_f32_bf16_e32 v176, v136, v162
	v_dot2c_f32_bf16_e32 v177, v137, v163
	v_dot2c_f32_bf16_e32 v178, v138, v166
	v_dot2c_f32_bf16_e32 v179, v139, v167
	v_dot2c_f32_bf16_e32 v176, v140, v170
	v_dot2c_f32_bf16_e32 v177, v141, v171
	v_dot2c_f32_bf16_e32 v178, v142, v174
	v_dot2c_f32_bf16_e32 v179, v143, v175
	s_waitcnt vmcnt(19)
	v_cvt_scalef32_pk32_bf16_fp6 v[0:15], v[76:81], 1.0
	v_cvt_scalef32_pk32_bf16_fp6 v[128:143], v[82:87], 1.0
	v_dot2_f32_bf16 v180, v0, v144, 0
	v_dot2_f32_bf16 v181, v1, v145, 0
	v_dot2_f32_bf16 v182, v2, v148, 0
	v_dot2_f32_bf16 v183, v3, v149, 0
	v_dot2c_f32_bf16_e32 v180, v4, v152
	v_dot2c_f32_bf16_e32 v181, v5, v153
	v_dot2c_f32_bf16_e32 v182, v6, v156
	v_dot2c_f32_bf16_e32 v183, v7, v157
	v_add_f32_e32 v192, v176, v177
	v_add_f32_e32 v206, v178, v179
	v_add_f32_e32 v192, v192, v206
	s_nop 1
	v_add_f32_dpp v192, v192, v192 quad_perm:[1,0,3,2] row_mask:0xf bank_mask:0xf
	s_nop 1
	v_add_f32_dpp v192, v192, v192 quad_perm:[2,3,0,1] row_mask:0xf bank_mask:0xf
	v_cndmask_b32_e64 v119, v119, v192, s[38:39]
	v_dot2c_f32_bf16_e32 v180, v8, v160
	v_dot2c_f32_bf16_e32 v181, v9, v161
	v_dot2c_f32_bf16_e32 v182, v10, v164
	v_dot2c_f32_bf16_e32 v183, v11, v165
	v_dot2c_f32_bf16_e32 v180, v12, v168
	v_dot2c_f32_bf16_e32 v181, v13, v169
	v_dot2c_f32_bf16_e32 v182, v14, v172
	v_dot2c_f32_bf16_e32 v183, v15, v173
	v_dot2c_f32_bf16_e32 v180, v128, v146
	v_dot2c_f32_bf16_e32 v181, v129, v147
	v_dot2c_f32_bf16_e32 v182, v130, v150
	v_dot2c_f32_bf16_e32 v183, v131, v151
	v_dot2c_f32_bf16_e32 v180, v132, v154
	v_dot2c_f32_bf16_e32 v181, v133, v155
	v_dot2c_f32_bf16_e32 v182, v134, v158
	v_dot2c_f32_bf16_e32 v183, v135, v159
	v_dot2c_f32_bf16_e32 v180, v136, v162
	v_dot2c_f32_bf16_e32 v181, v137, v163
	v_dot2c_f32_bf16_e32 v182, v138, v166
	v_dot2c_f32_bf16_e32 v183, v139, v167
	v_dot2c_f32_bf16_e32 v180, v140, v170
	v_dot2c_f32_bf16_e32 v181, v141, v171
	v_dot2c_f32_bf16_e32 v182, v142, v174
	v_dot2c_f32_bf16_e32 v183, v143, v175
	v_mad_u32_u24 v188, v188, s18, v197
	v_mad_u32_u24 v189, v189, s18, v197
	global_load_dwordx4 v[64:67], v188, s[0:1]
	global_load_dwordx4 v[68:71], v188, s[0:1] offset:16
	global_load_dwordx4 v[72:75], v188, s[0:1] offset:32
	global_load_dwordx4 v[76:79], v189, s[0:1]
	global_load_dwordx4 v[80:83], v189, s[0:1] offset:16
	global_load_dwordx4 v[84:87], v189, s[0:1] offset:32
	s_waitcnt vmcnt(22)
	v_cvt_scalef32_pk32_bf16_fp6 v[0:15], v[88:93], 1.0
	v_cvt_scalef32_pk32_bf16_fp6 v[128:143], v[94:99], 1.0
	v_dot2_f32_bf16 v176, v0, v144, 0
	v_dot2_f32_bf16 v177, v1, v145, 0
	v_dot2_f32_bf16 v178, v2, v148, 0
	v_dot2_f32_bf16 v179, v3, v149, 0
	v_dot2c_f32_bf16_e32 v176, v4, v152
	v_dot2c_f32_bf16_e32 v177, v5, v153
	v_dot2c_f32_bf16_e32 v178, v6, v156
	v_dot2c_f32_bf16_e32 v179, v7, v157
	v_add_f32_e32 v192, v180, v181
	v_add_f32_e32 v206, v182, v183
	v_add_f32_e32 v192, v192, v206
	s_nop 1
	v_add_f32_dpp v192, v192, v192 quad_perm:[1,0,3,2] row_mask:0xf bank_mask:0xf
	s_nop 1
	v_add_f32_dpp v192, v192, v192 quad_perm:[2,3,0,1] row_mask:0xf bank_mask:0xf
	v_cndmask_b32_e64 v119, v119, v192, s[10:11]
	v_dot2c_f32_bf16_e32 v176, v8, v160
	v_dot2c_f32_bf16_e32 v177, v9, v161
	v_dot2c_f32_bf16_e32 v178, v10, v164
	v_dot2c_f32_bf16_e32 v179, v11, v165
	v_dot2c_f32_bf16_e32 v176, v12, v168
	v_dot2c_f32_bf16_e32 v177, v13, v169
	v_dot2c_f32_bf16_e32 v178, v14, v172
	v_dot2c_f32_bf16_e32 v179, v15, v173
	v_dot2c_f32_bf16_e32 v176, v128, v146
	v_dot2c_f32_bf16_e32 v177, v129, v147
	v_dot2c_f32_bf16_e32 v178, v130, v150
	v_dot2c_f32_bf16_e32 v179, v131, v151
	v_dot2c_f32_bf16_e32 v176, v132, v154
	v_dot2c_f32_bf16_e32 v177, v133, v155
	v_dot2c_f32_bf16_e32 v178, v134, v158
	v_dot2c_f32_bf16_e32 v179, v135, v159
	v_dot2c_f32_bf16_e32 v176, v136, v162
	v_dot2c_f32_bf16_e32 v177, v137, v163
	v_dot2c_f32_bf16_e32 v178, v138, v166
	v_dot2c_f32_bf16_e32 v179, v139, v167
	v_dot2c_f32_bf16_e32 v176, v140, v170
	v_dot2c_f32_bf16_e32 v177, v141, v171
	v_dot2c_f32_bf16_e32 v178, v142, v174
	v_dot2c_f32_bf16_e32 v179, v143, v175
	s_waitcnt vmcnt(19)
	v_cvt_scalef32_pk32_bf16_fp6 v[0:15], v[100:105], 1.0
	v_cvt_scalef32_pk32_bf16_fp6 v[128:143], v[106:111], 1.0
	v_dot2_f32_bf16 v180, v0, v144, 0
	v_dot2_f32_bf16 v181, v1, v145, 0
	v_dot2_f32_bf16 v182, v2, v148, 0
	v_dot2_f32_bf16 v183, v3, v149, 0
	v_dot2c_f32_bf16_e32 v180, v4, v152
	v_dot2c_f32_bf16_e32 v181, v5, v153
	v_dot2c_f32_bf16_e32 v182, v6, v156
	v_dot2c_f32_bf16_e32 v183, v7, v157
	v_add_f32_e32 v192, v176, v177
	v_add_f32_e32 v206, v178, v179
	v_add_f32_e32 v192, v192, v206
	s_nop 1
	v_add_f32_dpp v192, v192, v192 quad_perm:[1,0,3,2] row_mask:0xf bank_mask:0xf
	s_nop 1
	v_add_f32_dpp v192, v192, v192 quad_perm:[2,3,0,1] row_mask:0xf bank_mask:0xf
	v_cndmask_b32_e64 v119, v119, v192, s[100:101]
	v_dot2c_f32_bf16_e32 v180, v8, v160
	v_dot2c_f32_bf16_e32 v181, v9, v161
	v_dot2c_f32_bf16_e32 v182, v10, v164
	v_dot2c_f32_bf16_e32 v183, v11, v165
	v_dot2c_f32_bf16_e32 v180, v12, v168
	v_dot2c_f32_bf16_e32 v181, v13, v169
	v_dot2c_f32_bf16_e32 v182, v14, v172
	v_dot2c_f32_bf16_e32 v183, v15, v173
	v_dot2c_f32_bf16_e32 v180, v128, v146
	v_dot2c_f32_bf16_e32 v181, v129, v147
	v_dot2c_f32_bf16_e32 v182, v130, v150
	v_dot2c_f32_bf16_e32 v183, v131, v151
	v_dot2c_f32_bf16_e32 v180, v132, v154
	v_dot2c_f32_bf16_e32 v181, v133, v155
	v_dot2c_f32_bf16_e32 v182, v134, v158
	v_dot2c_f32_bf16_e32 v183, v135, v159
	v_dot2c_f32_bf16_e32 v180, v136, v162
	v_dot2c_f32_bf16_e32 v181, v137, v163
	v_dot2c_f32_bf16_e32 v182, v138, v166
	v_dot2c_f32_bf16_e32 v183, v139, v167
	v_dot2c_f32_bf16_e32 v180, v140, v170
	v_dot2c_f32_bf16_e32 v181, v141, v171
	v_dot2c_f32_bf16_e32 v182, v142, v174
	v_dot2c_f32_bf16_e32 v183, v143, v175
	v_mad_u32_u24 v190, v190, s18, v197
	v_mad_u32_u24 v191, v191, s18, v197
	global_load_dwordx4 v[88:91], v190, s[0:1]
	global_load_dwordx4 v[92:95], v190, s[0:1] offset:16
	global_load_dwordx4 v[96:99], v190, s[0:1] offset:32
	global_load_dwordx4 v[100:103], v191, s[0:1]
	global_load_dwordx4 v[104:107], v191, s[0:1] offset:16
	global_load_dwordx4 v[108:111], v191, s[0:1] offset:32
	s_add_u32 s12, s12, 1
	s_and_b32 s12, s12, 63
	s_add_u32 s14, s12, 1
	s_and_b32 s14, s14, 63
	s_and_b32 s15, s14, 15
	s_lshr_b32 s16, s14, 4
	s_lshl_b32 s17, s15, 9
	s_mul_i32 s13, s15, s19
	s_lshl_b32 s14, s16, 6
	s_add_u32 s13, s13, s14
	s_add_u32 s8, s4, s13
	s_addc_u32 s9, s5, 0
	s_mul_i32 s13, s16, 0x300000
	s_add_u32 s0, s26, 0x2800000
	s_addc_u32 s1, s27, 0
	s_add_u32 s0, s0, s13
	s_addc_u32 s1, s1, 0
	v_add_u32_e32 v202, s17, v194
	ds_read2_b32 v[184:185], v202 offset0:0 offset1:16
	ds_read2_b32 v[186:187], v202 offset0:32 offset1:48
	ds_read2_b32 v[188:189], v202 offset0:64 offset1:80
	ds_read2_b32 v[190:191], v202 offset0:96 offset1:112
	v_add_f32_e32 v192, v180, v181
	v_add_f32_e32 v206, v182, v183
	v_add_f32_e32 v192, v192, v206
	s_nop 1
	v_add_f32_dpp v192, v192, v192 quad_perm:[1,0,3,2] row_mask:0xf bank_mask:0xf
	s_nop 1
	v_add_f32_dpp v192, v192, v192 quad_perm:[2,3,0,1] row_mask:0xf bank_mask:0xf
	v_cndmask_b32_e64 v119, v119, v192, s[98:99]
	ds_add_f32 v204, v119 offset:256
	s_cmp_lg_u32 s12, 0
	s_cbranch_scc1 .Lgu1_loop
	s_waitcnt vmcnt(0) lgkmcnt(0)
	s_add_u32 s0, s26, 0x1420000
	s_addc_u32 s1, s27, 0
	s_add_u32 s4, s26, 0x1430000
	s_addc_u32 s5, s27, 0
	s_lshl_b32 s13, s35, 9
	s_add_u32 s6, s26, 0xe800000
	s_addc_u32 s7, s27, 0
	s_add_u32 s6, s6, s13
	s_addc_u32 s7, s7, 0
	s_add_u32 s8, s26, 0xf800000
	s_addc_u32 s9, s27, 0
	s_add_u32 s8, s8, s13
	s_addc_u32 s9, s9, 0
	s_lshl_b32 s14, s92, 11
	s_mov_b32 s12, 0x378e98ab
	s_mov_b32 s15, 0x3b7cd369
	s_mov_b32 s16, 0xbcc618b2
	s_mov_b32 s17, 0x3dda74e4
	s_mov_b32 s18, 0x3f228afd
	s_mov_b32 s19, 0x3e03c728
	s_mov_b32 s98, 0xbfb8aa3b
	s_mov_b32 s38, 0x42ce8ed0
	s_mov_b32 s39, 0xc2b17218
	s_mov_b32 s10, 0x7fffffff
	v_mov_b32_e32 v176, 0x3ba10414
	v_mov_b32_e32 v177, 0xb9c68948
	v_mov_b32_e32 v178, 0x7f800000
	ds_read2st64_b32 v[16:17], v199 offset0:0 offset1:1
	ds_read2st64_b32 v[80:81], v200 offset0:0 offset1:1
	ds_read2st64_b32 v[18:19], v199 offset0:2 offset1:3
	ds_read2st64_b32 v[82:83], v200 offset0:2 offset1:3
	ds_read2st64_b32 v[20:21], v199 offset0:4 offset1:5
	ds_read2st64_b32 v[84:85], v200 offset0:4 offset1:5
	ds_read2st64_b32 v[22:23], v199 offset0:6 offset1:7
	ds_read2st64_b32 v[86:87], v200 offset0:6 offset1:7
	ds_read2st64_b32 v[24:25], v199 offset0:8 offset1:9
	ds_read2st64_b32 v[88:89], v200 offset0:8 offset1:9
	ds_read2st64_b32 v[26:27], v199 offset0:10 offset1:11
	ds_read2st64_b32 v[90:91], v200 offset0:10 offset1:11
	ds_read2st64_b32 v[28:29], v199 offset0:12 offset1:13
	ds_read2st64_b32 v[92:93], v200 offset0:12 offset1:13
	ds_read2st64_b32 v[30:31], v199 offset0:14 offset1:15
	ds_read2st64_b32 v[94:95], v200 offset0:14 offset1:15
	s_waitcnt lgkmcnt(0)
	v_lshlrev_b32_e32 v16, 2, v16
	v_lshlrev_b32_e32 v17, 2, v17
	v_lshlrev_b32_e32 v18, 2, v18
	v_lshlrev_b32_e32 v19, 2, v19
	v_lshlrev_b32_e32 v20, 2, v20
	v_lshlrev_b32_e32 v21, 2, v21
	v_lshlrev_b32_e32 v22, 2, v22
	v_lshlrev_b32_e32 v23, 2, v23
	v_lshlrev_b32_e32 v24, 2, v24
	v_lshlrev_b32_e32 v25, 2, v25
	v_lshlrev_b32_e32 v26, 2, v26
	v_lshlrev_b32_e32 v27, 2, v27
	v_lshlrev_b32_e32 v28, 2, v28
	v_lshlrev_b32_e32 v29, 2, v29
	v_lshlrev_b32_e32 v30, 2, v30
	v_lshlrev_b32_e32 v31, 2, v31
	global_load_dword v32, v193, s[6:7]
	global_load_dword v33, v193, s[6:7] offset:256
	global_load_dword v34, v16, s[0:1]
	global_load_dword v35, v17, s[0:1]
	global_load_dword v36, v16, s[4:5]
	global_load_dword v37, v17, s[4:5]
	s_add_u32 s6, s6, s14
	s_addc_u32 s7, s7, 0
	global_load_dword v38, v193, s[6:7]
	global_load_dword v39, v193, s[6:7] offset:256
	global_load_dword v40, v18, s[0:1]
	global_load_dword v41, v19, s[0:1]
	global_load_dword v42, v18, s[4:5]
	global_load_dword v43, v19, s[4:5]
	s_add_u32 s6, s6, s14
	s_addc_u32 s7, s7, 0
	global_load_dword v44, v193, s[6:7]
	global_load_dword v45, v193, s[6:7] offset:256
	global_load_dword v46, v20, s[0:1]
	global_load_dword v47, v21, s[0:1]
	global_load_dword v48, v20, s[4:5]
	global_load_dword v49, v21, s[4:5]
	s_add_u32 s6, s6, s14
	s_addc_u32 s7, s7, 0
	global_load_dword v50, v193, s[6:7]
	global_load_dword v51, v193, s[6:7] offset:256
	global_load_dword v52, v22, s[0:1]
	global_load_dword v53, v23, s[0:1]
	global_load_dword v54, v22, s[4:5]
	global_load_dword v55, v23, s[4:5]
	s_add_u32 s6, s6, s14
	s_addc_u32 s7, s7, 0
	global_load_dword v56, v193, s[6:7]
	global_load_dword v57, v193, s[6:7] offset:256
	global_load_dword v58, v24, s[0:1]
	global_load_dword v59, v25, s[0:1]
	global_load_dword v60, v24, s[4:5]
	global_load_dword v61, v25, s[4:5]
	s_add_u32 s6, s6, s14
	s_addc_u32 s7, s7, 0
	global_load_dword v62, v193, s[6:7]
	global_load_dword v63, v193, s[6:7] offset:256
	global_load_dword v64, v26, s[0:1]
	global_load_dword v65, v27, s[0:1]
	global_load_dword v66, v26, s[4:5]
	global_load_dword v67, v27, s[4:5]
	s_add_u32 s6, s6, s14
	s_addc_u32 s7, s7, 0
	global_load_dword v68, v193, s[6:7]
	global_load_dword v69, v193, s[6:7] offset:256
	global_load_dword v70, v28, s[0:1]
	global_load_dword v71, v29, s[0:1]
	global_load_dword v72, v28, s[4:5]
	global_load_dword v73, v29, s[4:5]
	s_add_u32 s6, s6, s14
	s_addc_u32 s7, s7, 0
	global_load_dword v74, v193, s[6:7]
	global_load_dword v75, v193, s[6:7] offset:256
	global_load_dword v76, v30, s[0:1]
	global_load_dword v77, v31, s[0:1]
	global_load_dword v78, v30, s[4:5]
	global_load_dword v79, v31, s[4:5]
	s_add_u32 s6, s6, s14
	s_addc_u32 s7, s7, 0
	s_waitcnt vmcnt(0)
	v_mul_f32_e32 v80, v34, v80
	v_mul_f32_e32 v180, 0x3f3504f3, v80
	v_fma_f32 v182, |v180|, s12, v177
	v_fma_f32 v182, |v180|, v182, s15
	v_fma_f32 v182, |v180|, v182, s16
	v_fma_f32 v182, |v180|, v182, s17
	v_fma_f32 v182, |v180|, v182, s18
	v_fma_f32 v182, |v180|, v182, s19
	v_fma_f32 v182, |v180|, v182, |v180|
	v_mul_f32_e32 v184, 0xbfb8aa3b, v182
	v_fma_f32 v185, v182, s98, -v184
	v_rndne_f32_e32 v186, v184
	v_fmac_f32_e32 v185, 0xb2a5705f, v182
	v_sub_f32_e32 v184, v184, v186
	v_add_f32_e32 v184, v184, v185
	v_cvt_i32_f32_e32 v185, v186
	v_exp_f32_e32 v184, v184
	v_cmp_nlt_f32_e32 vcc, s38, v182
	v_ldexp_f32 v184, v184, v185
	s_nop 0
	v_cndmask_b32_e32 v184, 0, v184, vcc
	v_cmp_ngt_f32_e32 vcc, s39, v182
	s_nop 1
	v_cndmask_b32_e32 v184, v178, v184, vcc
	v_sub_f32_e32 v184, 1.0, v184
	v_mul_f32_e32 v183, v180, v180
	v_fmamk_f32 v185, v183, 0xba1345e1, v176
	v_fmaak_f32 v185, v183, v185, 0xbcdac9b8
	v_fmaak_f32 v185, v183, v185, 0x3de703be
	v_fmaak_f32 v185, v183, v185, 0xbec09330
	v_fmaak_f32 v183, v183, v185, 0x3e0375d0
	v_fma_f32 v183, |v180|, v183, |v180|
	v_cmp_nlt_f32_e64 vcc, |v180|, 1.0
	s_nop 1
	v_cndmask_b32_e32 v184, v183, v184, vcc
	v_bfi_b32 v184, s10, v184, v180
	v_add_f32_e32 v184, 1.0, v184
	v_mul_f32_e32 v80, 0.5, v80
	v_mul_f32_e32 v32, v32, v36
	v_mul_f32_e32 v80, v80, v184
	v_mul_f32_e32 v80, v32, v80
	v_mul_f32_e32 v81, v35, v81
	v_mul_f32_e32 v180, 0x3f3504f3, v81
	v_fma_f32 v182, |v180|, s12, v177
	v_fma_f32 v182, |v180|, v182, s15
	v_fma_f32 v182, |v180|, v182, s16
	v_fma_f32 v182, |v180|, v182, s17
	v_fma_f32 v182, |v180|, v182, s18
	v_fma_f32 v182, |v180|, v182, s19
	v_fma_f32 v182, |v180|, v182, |v180|
	v_mul_f32_e32 v184, 0xbfb8aa3b, v182
	v_fma_f32 v185, v182, s98, -v184
	v_rndne_f32_e32 v186, v184
	v_fmac_f32_e32 v185, 0xb2a5705f, v182
	v_sub_f32_e32 v184, v184, v186
	v_add_f32_e32 v184, v184, v185
	v_cvt_i32_f32_e32 v185, v186
	v_exp_f32_e32 v184, v184
	v_cmp_nlt_f32_e32 vcc, s38, v182
	v_ldexp_f32 v184, v184, v185
	s_nop 0
	v_cndmask_b32_e32 v184, 0, v184, vcc
	v_cmp_ngt_f32_e32 vcc, s39, v182
	s_nop 1
	v_cndmask_b32_e32 v184, v178, v184, vcc
	v_sub_f32_e32 v184, 1.0, v184
	v_mul_f32_e32 v183, v180, v180
	v_fmamk_f32 v185, v183, 0xba1345e1, v176
	v_fmaak_f32 v185, v183, v185, 0xbcdac9b8
	v_fmaak_f32 v185, v183, v185, 0x3de703be
	v_fmaak_f32 v185, v183, v185, 0xbec09330
	v_fmaak_f32 v183, v183, v185, 0x3e0375d0
	v_fma_f32 v183, |v180|, v183, |v180|
	v_cmp_nlt_f32_e64 vcc, |v180|, 1.0
	s_nop 1
	v_cndmask_b32_e32 v184, v183, v184, vcc
	v_bfi_b32 v184, s10, v184, v180
	v_add_f32_e32 v184, 1.0, v184
	v_mul_f32_e32 v81, 0.5, v81
	v_mul_f32_e32 v33, v33, v37
	v_mul_f32_e32 v81, v81, v184
	v_mul_f32_e32 v81, v33, v81
	global_store_dword v193, v80, s[8:9]
	global_store_dword v193, v81, s[8:9] offset:256
	s_add_u32 s8, s8, s14
	s_addc_u32 s9, s9, 0
	v_mul_f32_e32 v82, v40, v82
	v_mul_f32_e32 v180, 0x3f3504f3, v82
	v_fma_f32 v182, |v180|, s12, v177
	v_fma_f32 v182, |v180|, v182, s15
	v_fma_f32 v182, |v180|, v182, s16
	v_fma_f32 v182, |v180|, v182, s17
	v_fma_f32 v182, |v180|, v182, s18
	v_fma_f32 v182, |v180|, v182, s19
	v_fma_f32 v182, |v180|, v182, |v180|
	v_mul_f32_e32 v184, 0xbfb8aa3b, v182
	v_fma_f32 v185, v182, s98, -v184
	v_rndne_f32_e32 v186, v184
	v_fmac_f32_e32 v185, 0xb2a5705f, v182
	v_sub_f32_e32 v184, v184, v186
	v_add_f32_e32 v184, v184, v185
	v_cvt_i32_f32_e32 v185, v186
	v_exp_f32_e32 v184, v184
	v_cmp_nlt_f32_e32 vcc, s38, v182
	v_ldexp_f32 v184, v184, v185
	s_nop 0
	v_cndmask_b32_e32 v184, 0, v184, vcc
	v_cmp_ngt_f32_e32 vcc, s39, v182
	s_nop 1
	v_cndmask_b32_e32 v184, v178, v184, vcc
	v_sub_f32_e32 v184, 1.0, v184
	v_mul_f32_e32 v183, v180, v180
	v_fmamk_f32 v185, v183, 0xba1345e1, v176
	v_fmaak_f32 v185, v183, v185, 0xbcdac9b8
	v_fmaak_f32 v185, v183, v185, 0x3de703be
	v_fmaak_f32 v185, v183, v185, 0xbec09330
	v_fmaak_f32 v183, v183, v185, 0x3e0375d0
	v_fma_f32 v183, |v180|, v183, |v180|
	v_cmp_nlt_f32_e64 vcc, |v180|, 1.0
	s_nop 1
	v_cndmask_b32_e32 v184, v183, v184, vcc
	v_bfi_b32 v184, s10, v184, v180
	v_add_f32_e32 v184, 1.0, v184
	v_mul_f32_e32 v82, 0.5, v82
	v_mul_f32_e32 v38, v38, v42
	v_mul_f32_e32 v82, v82, v184
	v_mul_f32_e32 v82, v38, v82
	v_mul_f32_e32 v83, v41, v83
	v_mul_f32_e32 v180, 0x3f3504f3, v83
	v_fma_f32 v182, |v180|, s12, v177
	v_fma_f32 v182, |v180|, v182, s15
	v_fma_f32 v182, |v180|, v182, s16
	v_fma_f32 v182, |v180|, v182, s17
	v_fma_f32 v182, |v180|, v182, s18
	v_fma_f32 v182, |v180|, v182, s19
	v_fma_f32 v182, |v180|, v182, |v180|
	v_mul_f32_e32 v184, 0xbfb8aa3b, v182
	v_fma_f32 v185, v182, s98, -v184
	v_rndne_f32_e32 v186, v184
	v_fmac_f32_e32 v185, 0xb2a5705f, v182
	v_sub_f32_e32 v184, v184, v186
	v_add_f32_e32 v184, v184, v185
	v_cvt_i32_f32_e32 v185, v186
	v_exp_f32_e32 v184, v184
	v_cmp_nlt_f32_e32 vcc, s38, v182
	v_ldexp_f32 v184, v184, v185
	s_nop 0
	v_cndmask_b32_e32 v184, 0, v184, vcc
	v_cmp_ngt_f32_e32 vcc, s39, v182
	s_nop 1
	v_cndmask_b32_e32 v184, v178, v184, vcc
	v_sub_f32_e32 v184, 1.0, v184
	v_mul_f32_e32 v183, v180, v180
	v_fmamk_f32 v185, v183, 0xba1345e1, v176
	v_fmaak_f32 v185, v183, v185, 0xbcdac9b8
	v_fmaak_f32 v185, v183, v185, 0x3de703be
	v_fmaak_f32 v185, v183, v185, 0xbec09330
	v_fmaak_f32 v183, v183, v185, 0x3e0375d0
	v_fma_f32 v183, |v180|, v183, |v180|
	v_cmp_nlt_f32_e64 vcc, |v180|, 1.0
	s_nop 1
	v_cndmask_b32_e32 v184, v183, v184, vcc
	v_bfi_b32 v184, s10, v184, v180
	v_add_f32_e32 v184, 1.0, v184
	v_mul_f32_e32 v83, 0.5, v83
	v_mul_f32_e32 v39, v39, v43
	v_mul_f32_e32 v83, v83, v184
	v_mul_f32_e32 v83, v39, v83
	global_store_dword v193, v82, s[8:9]
	global_store_dword v193, v83, s[8:9] offset:256
	s_add_u32 s8, s8, s14
	s_addc_u32 s9, s9, 0
	v_mul_f32_e32 v84, v46, v84
	v_mul_f32_e32 v180, 0x3f3504f3, v84
	v_fma_f32 v182, |v180|, s12, v177
	v_fma_f32 v182, |v180|, v182, s15
	v_fma_f32 v182, |v180|, v182, s16
	v_fma_f32 v182, |v180|, v182, s17
	v_fma_f32 v182, |v180|, v182, s18
	v_fma_f32 v182, |v180|, v182, s19
	v_fma_f32 v182, |v180|, v182, |v180|
	v_mul_f32_e32 v184, 0xbfb8aa3b, v182
	v_fma_f32 v185, v182, s98, -v184
	v_rndne_f32_e32 v186, v184
	v_fmac_f32_e32 v185, 0xb2a5705f, v182
	v_sub_f32_e32 v184, v184, v186
	v_add_f32_e32 v184, v184, v185
	v_cvt_i32_f32_e32 v185, v186
	v_exp_f32_e32 v184, v184
	v_cmp_nlt_f32_e32 vcc, s38, v182
	v_ldexp_f32 v184, v184, v185
	s_nop 0
	v_cndmask_b32_e32 v184, 0, v184, vcc
	v_cmp_ngt_f32_e32 vcc, s39, v182
	s_nop 1
	v_cndmask_b32_e32 v184, v178, v184, vcc
	v_sub_f32_e32 v184, 1.0, v184
	v_mul_f32_e32 v183, v180, v180
	v_fmamk_f32 v185, v183, 0xba1345e1, v176
	v_fmaak_f32 v185, v183, v185, 0xbcdac9b8
	v_fmaak_f32 v185, v183, v185, 0x3de703be
	v_fmaak_f32 v185, v183, v185, 0xbec09330
	v_fmaak_f32 v183, v183, v185, 0x3e0375d0
	v_fma_f32 v183, |v180|, v183, |v180|
	v_cmp_nlt_f32_e64 vcc, |v180|, 1.0
	s_nop 1
	v_cndmask_b32_e32 v184, v183, v184, vcc
	v_bfi_b32 v184, s10, v184, v180
	v_add_f32_e32 v184, 1.0, v184
	v_mul_f32_e32 v84, 0.5, v84
	v_mul_f32_e32 v44, v44, v48
	v_mul_f32_e32 v84, v84, v184
	v_mul_f32_e32 v84, v44, v84
	v_mul_f32_e32 v85, v47, v85
	v_mul_f32_e32 v180, 0x3f3504f3, v85
	v_fma_f32 v182, |v180|, s12, v177
	v_fma_f32 v182, |v180|, v182, s15
	v_fma_f32 v182, |v180|, v182, s16
	v_fma_f32 v182, |v180|, v182, s17
	v_fma_f32 v182, |v180|, v182, s18
	v_fma_f32 v182, |v180|, v182, s19
	v_fma_f32 v182, |v180|, v182, |v180|
	v_mul_f32_e32 v184, 0xbfb8aa3b, v182
	v_fma_f32 v185, v182, s98, -v184
	v_rndne_f32_e32 v186, v184
	v_fmac_f32_e32 v185, 0xb2a5705f, v182
	v_sub_f32_e32 v184, v184, v186
	v_add_f32_e32 v184, v184, v185
	v_cvt_i32_f32_e32 v185, v186
	v_exp_f32_e32 v184, v184
	v_cmp_nlt_f32_e32 vcc, s38, v182
	v_ldexp_f32 v184, v184, v185
	s_nop 0
	v_cndmask_b32_e32 v184, 0, v184, vcc
	v_cmp_ngt_f32_e32 vcc, s39, v182
	s_nop 1
	v_cndmask_b32_e32 v184, v178, v184, vcc
	v_sub_f32_e32 v184, 1.0, v184
	v_mul_f32_e32 v183, v180, v180
	v_fmamk_f32 v185, v183, 0xba1345e1, v176
	v_fmaak_f32 v185, v183, v185, 0xbcdac9b8
	v_fmaak_f32 v185, v183, v185, 0x3de703be
	v_fmaak_f32 v185, v183, v185, 0xbec09330
	v_fmaak_f32 v183, v183, v185, 0x3e0375d0
	v_fma_f32 v183, |v180|, v183, |v180|
	v_cmp_nlt_f32_e64 vcc, |v180|, 1.0
	s_nop 1
	v_cndmask_b32_e32 v184, v183, v184, vcc
	v_bfi_b32 v184, s10, v184, v180
	v_add_f32_e32 v184, 1.0, v184
	v_mul_f32_e32 v85, 0.5, v85
	v_mul_f32_e32 v45, v45, v49
	v_mul_f32_e32 v85, v85, v184
	v_mul_f32_e32 v85, v45, v85
	global_store_dword v193, v84, s[8:9]
	global_store_dword v193, v85, s[8:9] offset:256
	s_add_u32 s8, s8, s14
	s_addc_u32 s9, s9, 0
	v_mul_f32_e32 v86, v52, v86
	v_mul_f32_e32 v180, 0x3f3504f3, v86
	v_fma_f32 v182, |v180|, s12, v177
	v_fma_f32 v182, |v180|, v182, s15
	v_fma_f32 v182, |v180|, v182, s16
	v_fma_f32 v182, |v180|, v182, s17
	v_fma_f32 v182, |v180|, v182, s18
	v_fma_f32 v182, |v180|, v182, s19
	v_fma_f32 v182, |v180|, v182, |v180|
	v_mul_f32_e32 v184, 0xbfb8aa3b, v182
	v_fma_f32 v185, v182, s98, -v184
	v_rndne_f32_e32 v186, v184
	v_fmac_f32_e32 v185, 0xb2a5705f, v182
	v_sub_f32_e32 v184, v184, v186
	v_add_f32_e32 v184, v184, v185
	v_cvt_i32_f32_e32 v185, v186
	v_exp_f32_e32 v184, v184
	v_cmp_nlt_f32_e32 vcc, s38, v182
	v_ldexp_f32 v184, v184, v185
	s_nop 0
	v_cndmask_b32_e32 v184, 0, v184, vcc
	v_cmp_ngt_f32_e32 vcc, s39, v182
	s_nop 1
	v_cndmask_b32_e32 v184, v178, v184, vcc
	v_sub_f32_e32 v184, 1.0, v184
	v_mul_f32_e32 v183, v180, v180
	v_fmamk_f32 v185, v183, 0xba1345e1, v176
	v_fmaak_f32 v185, v183, v185, 0xbcdac9b8
	v_fmaak_f32 v185, v183, v185, 0x3de703be
	v_fmaak_f32 v185, v183, v185, 0xbec09330
	v_fmaak_f32 v183, v183, v185, 0x3e0375d0
	v_fma_f32 v183, |v180|, v183, |v180|
	v_cmp_nlt_f32_e64 vcc, |v180|, 1.0
	s_nop 1
	v_cndmask_b32_e32 v184, v183, v184, vcc
	v_bfi_b32 v184, s10, v184, v180
	v_add_f32_e32 v184, 1.0, v184
	v_mul_f32_e32 v86, 0.5, v86
	v_mul_f32_e32 v50, v50, v54
	v_mul_f32_e32 v86, v86, v184
	v_mul_f32_e32 v86, v50, v86
	v_mul_f32_e32 v87, v53, v87
	v_mul_f32_e32 v180, 0x3f3504f3, v87
	v_fma_f32 v182, |v180|, s12, v177
	v_fma_f32 v182, |v180|, v182, s15
	v_fma_f32 v182, |v180|, v182, s16
	v_fma_f32 v182, |v180|, v182, s17
	v_fma_f32 v182, |v180|, v182, s18
	v_fma_f32 v182, |v180|, v182, s19
	v_fma_f32 v182, |v180|, v182, |v180|
	v_mul_f32_e32 v184, 0xbfb8aa3b, v182
	v_fma_f32 v185, v182, s98, -v184
	v_rndne_f32_e32 v186, v184
	v_fmac_f32_e32 v185, 0xb2a5705f, v182
	v_sub_f32_e32 v184, v184, v186
	v_add_f32_e32 v184, v184, v185
	v_cvt_i32_f32_e32 v185, v186
	v_exp_f32_e32 v184, v184
	v_cmp_nlt_f32_e32 vcc, s38, v182
	v_ldexp_f32 v184, v184, v185
	s_nop 0
	v_cndmask_b32_e32 v184, 0, v184, vcc
	v_cmp_ngt_f32_e32 vcc, s39, v182
	s_nop 1
	v_cndmask_b32_e32 v184, v178, v184, vcc
	v_sub_f32_e32 v184, 1.0, v184
	v_mul_f32_e32 v183, v180, v180
	v_fmamk_f32 v185, v183, 0xba1345e1, v176
	v_fmaak_f32 v185, v183, v185, 0xbcdac9b8
	v_fmaak_f32 v185, v183, v185, 0x3de703be
	v_fmaak_f32 v185, v183, v185, 0xbec09330
	v_fmaak_f32 v183, v183, v185, 0x3e0375d0
	v_fma_f32 v183, |v180|, v183, |v180|
	v_cmp_nlt_f32_e64 vcc, |v180|, 1.0
	s_nop 1
	v_cndmask_b32_e32 v184, v183, v184, vcc
	v_bfi_b32 v184, s10, v184, v180
	v_add_f32_e32 v184, 1.0, v184
	v_mul_f32_e32 v87, 0.5, v87
	v_mul_f32_e32 v51, v51, v55
	v_mul_f32_e32 v87, v87, v184
	v_mul_f32_e32 v87, v51, v87
	global_store_dword v193, v86, s[8:9]
	global_store_dword v193, v87, s[8:9] offset:256
	s_add_u32 s8, s8, s14
	s_addc_u32 s9, s9, 0
	v_mul_f32_e32 v88, v58, v88
	v_mul_f32_e32 v180, 0x3f3504f3, v88
	v_fma_f32 v182, |v180|, s12, v177
	v_fma_f32 v182, |v180|, v182, s15
	v_fma_f32 v182, |v180|, v182, s16
	v_fma_f32 v182, |v180|, v182, s17
	v_fma_f32 v182, |v180|, v182, s18
	v_fma_f32 v182, |v180|, v182, s19
	v_fma_f32 v182, |v180|, v182, |v180|
	v_mul_f32_e32 v184, 0xbfb8aa3b, v182
	v_fma_f32 v185, v182, s98, -v184
	v_rndne_f32_e32 v186, v184
	v_fmac_f32_e32 v185, 0xb2a5705f, v182
	v_sub_f32_e32 v184, v184, v186
	v_add_f32_e32 v184, v184, v185
	v_cvt_i32_f32_e32 v185, v186
	v_exp_f32_e32 v184, v184
	v_cmp_nlt_f32_e32 vcc, s38, v182
	v_ldexp_f32 v184, v184, v185
	s_nop 0
	v_cndmask_b32_e32 v184, 0, v184, vcc
	v_cmp_ngt_f32_e32 vcc, s39, v182
	s_nop 1
	v_cndmask_b32_e32 v184, v178, v184, vcc
	v_sub_f32_e32 v184, 1.0, v184
	v_mul_f32_e32 v183, v180, v180
	v_fmamk_f32 v185, v183, 0xba1345e1, v176
	v_fmaak_f32 v185, v183, v185, 0xbcdac9b8
	v_fmaak_f32 v185, v183, v185, 0x3de703be
	v_fmaak_f32 v185, v183, v185, 0xbec09330
	v_fmaak_f32 v183, v183, v185, 0x3e0375d0
	v_fma_f32 v183, |v180|, v183, |v180|
	v_cmp_nlt_f32_e64 vcc, |v180|, 1.0
	s_nop 1
	v_cndmask_b32_e32 v184, v183, v184, vcc
	v_bfi_b32 v184, s10, v184, v180
	v_add_f32_e32 v184, 1.0, v184
	v_mul_f32_e32 v88, 0.5, v88
	v_mul_f32_e32 v56, v56, v60
	v_mul_f32_e32 v88, v88, v184
	v_mul_f32_e32 v88, v56, v88
	v_mul_f32_e32 v89, v59, v89
	v_mul_f32_e32 v180, 0x3f3504f3, v89
	v_fma_f32 v182, |v180|, s12, v177
	v_fma_f32 v182, |v180|, v182, s15
	v_fma_f32 v182, |v180|, v182, s16
	v_fma_f32 v182, |v180|, v182, s17
	v_fma_f32 v182, |v180|, v182, s18
	v_fma_f32 v182, |v180|, v182, s19
	v_fma_f32 v182, |v180|, v182, |v180|
	v_mul_f32_e32 v184, 0xbfb8aa3b, v182
	v_fma_f32 v185, v182, s98, -v184
	v_rndne_f32_e32 v186, v184
	v_fmac_f32_e32 v185, 0xb2a5705f, v182
	v_sub_f32_e32 v184, v184, v186
	v_add_f32_e32 v184, v184, v185
	v_cvt_i32_f32_e32 v185, v186
	v_exp_f32_e32 v184, v184
	v_cmp_nlt_f32_e32 vcc, s38, v182
	v_ldexp_f32 v184, v184, v185
	s_nop 0
	v_cndmask_b32_e32 v184, 0, v184, vcc
	v_cmp_ngt_f32_e32 vcc, s39, v182
	s_nop 1
	v_cndmask_b32_e32 v184, v178, v184, vcc
	v_sub_f32_e32 v184, 1.0, v184
	v_mul_f32_e32 v183, v180, v180
	v_fmamk_f32 v185, v183, 0xba1345e1, v176
	v_fmaak_f32 v185, v183, v185, 0xbcdac9b8
	v_fmaak_f32 v185, v183, v185, 0x3de703be
	v_fmaak_f32 v185, v183, v185, 0xbec09330
	v_fmaak_f32 v183, v183, v185, 0x3e0375d0
	v_fma_f32 v183, |v180|, v183, |v180|
	v_cmp_nlt_f32_e64 vcc, |v180|, 1.0
	s_nop 1
	v_cndmask_b32_e32 v184, v183, v184, vcc
	v_bfi_b32 v184, s10, v184, v180
	v_add_f32_e32 v184, 1.0, v184
	v_mul_f32_e32 v89, 0.5, v89
	v_mul_f32_e32 v57, v57, v61
	v_mul_f32_e32 v89, v89, v184
	v_mul_f32_e32 v89, v57, v89
	global_store_dword v193, v88, s[8:9]
	global_store_dword v193, v89, s[8:9] offset:256
	s_add_u32 s8, s8, s14
	s_addc_u32 s9, s9, 0
	v_mul_f32_e32 v90, v64, v90
	v_mul_f32_e32 v180, 0x3f3504f3, v90
	v_fma_f32 v182, |v180|, s12, v177
	v_fma_f32 v182, |v180|, v182, s15
	v_fma_f32 v182, |v180|, v182, s16
	v_fma_f32 v182, |v180|, v182, s17
	v_fma_f32 v182, |v180|, v182, s18
	v_fma_f32 v182, |v180|, v182, s19
	v_fma_f32 v182, |v180|, v182, |v180|
	v_mul_f32_e32 v184, 0xbfb8aa3b, v182
	v_fma_f32 v185, v182, s98, -v184
	v_rndne_f32_e32 v186, v184
	v_fmac_f32_e32 v185, 0xb2a5705f, v182
	v_sub_f32_e32 v184, v184, v186
	v_add_f32_e32 v184, v184, v185
	v_cvt_i32_f32_e32 v185, v186
	v_exp_f32_e32 v184, v184
	v_cmp_nlt_f32_e32 vcc, s38, v182
	v_ldexp_f32 v184, v184, v185
	s_nop 0
	v_cndmask_b32_e32 v184, 0, v184, vcc
	v_cmp_ngt_f32_e32 vcc, s39, v182
	s_nop 1
	v_cndmask_b32_e32 v184, v178, v184, vcc
	v_sub_f32_e32 v184, 1.0, v184
	v_mul_f32_e32 v183, v180, v180
	v_fmamk_f32 v185, v183, 0xba1345e1, v176
	v_fmaak_f32 v185, v183, v185, 0xbcdac9b8
	v_fmaak_f32 v185, v183, v185, 0x3de703be
	v_fmaak_f32 v185, v183, v185, 0xbec09330
	v_fmaak_f32 v183, v183, v185, 0x3e0375d0
	v_fma_f32 v183, |v180|, v183, |v180|
	v_cmp_nlt_f32_e64 vcc, |v180|, 1.0
	s_nop 1
	v_cndmask_b32_e32 v184, v183, v184, vcc
	v_bfi_b32 v184, s10, v184, v180
	v_add_f32_e32 v184, 1.0, v184
	v_mul_f32_e32 v90, 0.5, v90
	v_mul_f32_e32 v62, v62, v66
	v_mul_f32_e32 v90, v90, v184
	v_mul_f32_e32 v90, v62, v90
	v_mul_f32_e32 v91, v65, v91
	v_mul_f32_e32 v180, 0x3f3504f3, v91
	v_fma_f32 v182, |v180|, s12, v177
	v_fma_f32 v182, |v180|, v182, s15
	v_fma_f32 v182, |v180|, v182, s16
	v_fma_f32 v182, |v180|, v182, s17
	v_fma_f32 v182, |v180|, v182, s18
	v_fma_f32 v182, |v180|, v182, s19
	v_fma_f32 v182, |v180|, v182, |v180|
	v_mul_f32_e32 v184, 0xbfb8aa3b, v182
	v_fma_f32 v185, v182, s98, -v184
	v_rndne_f32_e32 v186, v184
	v_fmac_f32_e32 v185, 0xb2a5705f, v182
	v_sub_f32_e32 v184, v184, v186
	v_add_f32_e32 v184, v184, v185
	v_cvt_i32_f32_e32 v185, v186
	v_exp_f32_e32 v184, v184
	v_cmp_nlt_f32_e32 vcc, s38, v182
	v_ldexp_f32 v184, v184, v185
	s_nop 0
	v_cndmask_b32_e32 v184, 0, v184, vcc
	v_cmp_ngt_f32_e32 vcc, s39, v182
	s_nop 1
	v_cndmask_b32_e32 v184, v178, v184, vcc
	v_sub_f32_e32 v184, 1.0, v184
	v_mul_f32_e32 v183, v180, v180
	v_fmamk_f32 v185, v183, 0xba1345e1, v176
	v_fmaak_f32 v185, v183, v185, 0xbcdac9b8
	v_fmaak_f32 v185, v183, v185, 0x3de703be
	v_fmaak_f32 v185, v183, v185, 0xbec09330
	v_fmaak_f32 v183, v183, v185, 0x3e0375d0
	v_fma_f32 v183, |v180|, v183, |v180|
	v_cmp_nlt_f32_e64 vcc, |v180|, 1.0
	s_nop 1
	v_cndmask_b32_e32 v184, v183, v184, vcc
	v_bfi_b32 v184, s10, v184, v180
	v_add_f32_e32 v184, 1.0, v184
	v_mul_f32_e32 v91, 0.5, v91
	v_mul_f32_e32 v63, v63, v67
	v_mul_f32_e32 v91, v91, v184
	v_mul_f32_e32 v91, v63, v91
	global_store_dword v193, v90, s[8:9]
	global_store_dword v193, v91, s[8:9] offset:256
	s_add_u32 s8, s8, s14
	s_addc_u32 s9, s9, 0
	v_mul_f32_e32 v92, v70, v92
	v_mul_f32_e32 v180, 0x3f3504f3, v92
	v_fma_f32 v182, |v180|, s12, v177
	v_fma_f32 v182, |v180|, v182, s15
	v_fma_f32 v182, |v180|, v182, s16
	v_fma_f32 v182, |v180|, v182, s17
	v_fma_f32 v182, |v180|, v182, s18
	v_fma_f32 v182, |v180|, v182, s19
	v_fma_f32 v182, |v180|, v182, |v180|
	v_mul_f32_e32 v184, 0xbfb8aa3b, v182
	v_fma_f32 v185, v182, s98, -v184
	v_rndne_f32_e32 v186, v184
	v_fmac_f32_e32 v185, 0xb2a5705f, v182
	v_sub_f32_e32 v184, v184, v186
	v_add_f32_e32 v184, v184, v185
	v_cvt_i32_f32_e32 v185, v186
	v_exp_f32_e32 v184, v184
	v_cmp_nlt_f32_e32 vcc, s38, v182
	v_ldexp_f32 v184, v184, v185
	s_nop 0
	v_cndmask_b32_e32 v184, 0, v184, vcc
	v_cmp_ngt_f32_e32 vcc, s39, v182
	s_nop 1
	v_cndmask_b32_e32 v184, v178, v184, vcc
	v_sub_f32_e32 v184, 1.0, v184
	v_mul_f32_e32 v183, v180, v180
	v_fmamk_f32 v185, v183, 0xba1345e1, v176
	v_fmaak_f32 v185, v183, v185, 0xbcdac9b8
	v_fmaak_f32 v185, v183, v185, 0x3de703be
	v_fmaak_f32 v185, v183, v185, 0xbec09330
	v_fmaak_f32 v183, v183, v185, 0x3e0375d0
	v_fma_f32 v183, |v180|, v183, |v180|
	v_cmp_nlt_f32_e64 vcc, |v180|, 1.0
	s_nop 1
	v_cndmask_b32_e32 v184, v183, v184, vcc
	v_bfi_b32 v184, s10, v184, v180
	v_add_f32_e32 v184, 1.0, v184
	v_mul_f32_e32 v92, 0.5, v92
	v_mul_f32_e32 v68, v68, v72
	v_mul_f32_e32 v92, v92, v184
	v_mul_f32_e32 v92, v68, v92
	v_mul_f32_e32 v93, v71, v93
	v_mul_f32_e32 v180, 0x3f3504f3, v93
	v_fma_f32 v182, |v180|, s12, v177
	v_fma_f32 v182, |v180|, v182, s15
	v_fma_f32 v182, |v180|, v182, s16
	v_fma_f32 v182, |v180|, v182, s17
	v_fma_f32 v182, |v180|, v182, s18
	v_fma_f32 v182, |v180|, v182, s19
	v_fma_f32 v182, |v180|, v182, |v180|
	v_mul_f32_e32 v184, 0xbfb8aa3b, v182
	v_fma_f32 v185, v182, s98, -v184
	v_rndne_f32_e32 v186, v184
	v_fmac_f32_e32 v185, 0xb2a5705f, v182
	v_sub_f32_e32 v184, v184, v186
	v_add_f32_e32 v184, v184, v185
	v_cvt_i32_f32_e32 v185, v186
	v_exp_f32_e32 v184, v184
	v_cmp_nlt_f32_e32 vcc, s38, v182
	v_ldexp_f32 v184, v184, v185
	s_nop 0
	v_cndmask_b32_e32 v184, 0, v184, vcc
	v_cmp_ngt_f32_e32 vcc, s39, v182
	s_nop 1
	v_cndmask_b32_e32 v184, v178, v184, vcc
	v_sub_f32_e32 v184, 1.0, v184
	v_mul_f32_e32 v183, v180, v180
	v_fmamk_f32 v185, v183, 0xba1345e1, v176
	v_fmaak_f32 v185, v183, v185, 0xbcdac9b8
	v_fmaak_f32 v185, v183, v185, 0x3de703be
	v_fmaak_f32 v185, v183, v185, 0xbec09330
	v_fmaak_f32 v183, v183, v185, 0x3e0375d0
	v_fma_f32 v183, |v180|, v183, |v180|
	v_cmp_nlt_f32_e64 vcc, |v180|, 1.0
	s_nop 1
	v_cndmask_b32_e32 v184, v183, v184, vcc
	v_bfi_b32 v184, s10, v184, v180
	v_add_f32_e32 v184, 1.0, v184
	v_mul_f32_e32 v93, 0.5, v93
	v_mul_f32_e32 v69, v69, v73
	v_mul_f32_e32 v93, v93, v184
	v_mul_f32_e32 v93, v69, v93
	global_store_dword v193, v92, s[8:9]
	global_store_dword v193, v93, s[8:9] offset:256
	s_add_u32 s8, s8, s14
	s_addc_u32 s9, s9, 0
	v_mul_f32_e32 v94, v76, v94
	v_mul_f32_e32 v180, 0x3f3504f3, v94
	v_fma_f32 v182, |v180|, s12, v177
	v_fma_f32 v182, |v180|, v182, s15
	v_fma_f32 v182, |v180|, v182, s16
	v_fma_f32 v182, |v180|, v182, s17
	v_fma_f32 v182, |v180|, v182, s18
	v_fma_f32 v182, |v180|, v182, s19
	v_fma_f32 v182, |v180|, v182, |v180|
	v_mul_f32_e32 v184, 0xbfb8aa3b, v182
	v_fma_f32 v185, v182, s98, -v184
	v_rndne_f32_e32 v186, v184
	v_fmac_f32_e32 v185, 0xb2a5705f, v182
	v_sub_f32_e32 v184, v184, v186
	v_add_f32_e32 v184, v184, v185
	v_cvt_i32_f32_e32 v185, v186
	v_exp_f32_e32 v184, v184
	v_cmp_nlt_f32_e32 vcc, s38, v182
	v_ldexp_f32 v184, v184, v185
	s_nop 0
	v_cndmask_b32_e32 v184, 0, v184, vcc
	v_cmp_ngt_f32_e32 vcc, s39, v182
	s_nop 1
	v_cndmask_b32_e32 v184, v178, v184, vcc
	v_sub_f32_e32 v184, 1.0, v184
	v_mul_f32_e32 v183, v180, v180
	v_fmamk_f32 v185, v183, 0xba1345e1, v176
	v_fmaak_f32 v185, v183, v185, 0xbcdac9b8
	v_fmaak_f32 v185, v183, v185, 0x3de703be
	v_fmaak_f32 v185, v183, v185, 0xbec09330
	v_fmaak_f32 v183, v183, v185, 0x3e0375d0
	v_fma_f32 v183, |v180|, v183, |v180|
	v_cmp_nlt_f32_e64 vcc, |v180|, 1.0
	s_nop 1
	v_cndmask_b32_e32 v184, v183, v184, vcc
	v_bfi_b32 v184, s10, v184, v180
	v_add_f32_e32 v184, 1.0, v184
	v_mul_f32_e32 v94, 0.5, v94
	v_mul_f32_e32 v74, v74, v78
	v_mul_f32_e32 v94, v94, v184
	v_mul_f32_e32 v94, v74, v94
	v_mul_f32_e32 v95, v77, v95
	v_mul_f32_e32 v180, 0x3f3504f3, v95
	v_fma_f32 v182, |v180|, s12, v177
	v_fma_f32 v182, |v180|, v182, s15
	v_fma_f32 v182, |v180|, v182, s16
	v_fma_f32 v182, |v180|, v182, s17
	v_fma_f32 v182, |v180|, v182, s18
	v_fma_f32 v182, |v180|, v182, s19
	v_fma_f32 v182, |v180|, v182, |v180|
	v_mul_f32_e32 v184, 0xbfb8aa3b, v182
	v_fma_f32 v185, v182, s98, -v184
	v_rndne_f32_e32 v186, v184
	v_fmac_f32_e32 v185, 0xb2a5705f, v182
	v_sub_f32_e32 v184, v184, v186
	v_add_f32_e32 v184, v184, v185
	v_cvt_i32_f32_e32 v185, v186
	v_exp_f32_e32 v184, v184
	v_cmp_nlt_f32_e32 vcc, s38, v182
	v_ldexp_f32 v184, v184, v185
	s_nop 0
	v_cndmask_b32_e32 v184, 0, v184, vcc
	v_cmp_ngt_f32_e32 vcc, s39, v182
	s_nop 1
	v_cndmask_b32_e32 v184, v178, v184, vcc
	v_sub_f32_e32 v184, 1.0, v184
	v_mul_f32_e32 v183, v180, v180
	v_fmamk_f32 v185, v183, 0xba1345e1, v176
	v_fmaak_f32 v185, v183, v185, 0xbcdac9b8
	v_fmaak_f32 v185, v183, v185, 0x3de703be
	v_fmaak_f32 v185, v183, v185, 0xbec09330
	v_fmaak_f32 v183, v183, v185, 0x3e0375d0
	v_fma_f32 v183, |v180|, v183, |v180|
	v_cmp_nlt_f32_e64 vcc, |v180|, 1.0
	s_nop 1
	v_cndmask_b32_e32 v184, v183, v184, vcc
	v_bfi_b32 v184, s10, v184, v180
	v_add_f32_e32 v184, 1.0, v184
	v_mul_f32_e32 v95, 0.5, v95
	v_mul_f32_e32 v75, v75, v79
	v_mul_f32_e32 v95, v95, v184
	v_mul_f32_e32 v95, v75, v95
	global_store_dword v193, v94, s[8:9]
	global_store_dword v193, v95, s[8:9] offset:256
	s_add_u32 s8, s8, s14
	s_addc_u32 s9, s9, 0
	ds_read2st64_b32 v[16:17], v199 offset0:16 offset1:17
	ds_read2st64_b32 v[80:81], v200 offset0:16 offset1:17
	ds_read2st64_b32 v[18:19], v199 offset0:18 offset1:19
	ds_read2st64_b32 v[82:83], v200 offset0:18 offset1:19
	ds_read2st64_b32 v[20:21], v199 offset0:20 offset1:21
	ds_read2st64_b32 v[84:85], v200 offset0:20 offset1:21
	ds_read2st64_b32 v[22:23], v199 offset0:22 offset1:23
	ds_read2st64_b32 v[86:87], v200 offset0:22 offset1:23
	ds_read2st64_b32 v[24:25], v199 offset0:24 offset1:25
	ds_read2st64_b32 v[88:89], v200 offset0:24 offset1:25
	ds_read2st64_b32 v[26:27], v199 offset0:26 offset1:27
	ds_read2st64_b32 v[90:91], v200 offset0:26 offset1:27
	ds_read2st64_b32 v[28:29], v199 offset0:28 offset1:29
	ds_read2st64_b32 v[92:93], v200 offset0:28 offset1:29
	ds_read2st64_b32 v[30:31], v199 offset0:30 offset1:31
	ds_read2st64_b32 v[94:95], v200 offset0:30 offset1:31
	s_waitcnt lgkmcnt(0)
	v_lshlrev_b32_e32 v16, 2, v16
	v_lshlrev_b32_e32 v17, 2, v17
	v_lshlrev_b32_e32 v18, 2, v18
	v_lshlrev_b32_e32 v19, 2, v19
	v_lshlrev_b32_e32 v20, 2, v20
	v_lshlrev_b32_e32 v21, 2, v21
	v_lshlrev_b32_e32 v22, 2, v22
	v_lshlrev_b32_e32 v23, 2, v23
	v_lshlrev_b32_e32 v24, 2, v24
	v_lshlrev_b32_e32 v25, 2, v25
	v_lshlrev_b32_e32 v26, 2, v26
	v_lshlrev_b32_e32 v27, 2, v27
	v_lshlrev_b32_e32 v28, 2, v28
	v_lshlrev_b32_e32 v29, 2, v29
	v_lshlrev_b32_e32 v30, 2, v30
	v_lshlrev_b32_e32 v31, 2, v31
	global_load_dword v32, v193, s[6:7]
	global_load_dword v33, v193, s[6:7] offset:256
	global_load_dword v34, v16, s[0:1]
	global_load_dword v35, v17, s[0:1]
	global_load_dword v36, v16, s[4:5]
	global_load_dword v37, v17, s[4:5]
	s_add_u32 s6, s6, s14
	s_addc_u32 s7, s7, 0
	global_load_dword v38, v193, s[6:7]
	global_load_dword v39, v193, s[6:7] offset:256
	global_load_dword v40, v18, s[0:1]
	global_load_dword v41, v19, s[0:1]
	global_load_dword v42, v18, s[4:5]
	global_load_dword v43, v19, s[4:5]
	s_add_u32 s6, s6, s14
	s_addc_u32 s7, s7, 0
	global_load_dword v44, v193, s[6:7]
	global_load_dword v45, v193, s[6:7] offset:256
	global_load_dword v46, v20, s[0:1]
	global_load_dword v47, v21, s[0:1]
	global_load_dword v48, v20, s[4:5]
	global_load_dword v49, v21, s[4:5]
	s_add_u32 s6, s6, s14
	s_addc_u32 s7, s7, 0
	global_load_dword v50, v193, s[6:7]
	global_load_dword v51, v193, s[6:7] offset:256
	global_load_dword v52, v22, s[0:1]
	global_load_dword v53, v23, s[0:1]
	global_load_dword v54, v22, s[4:5]
	global_load_dword v55, v23, s[4:5]
	s_add_u32 s6, s6, s14
	s_addc_u32 s7, s7, 0
	global_load_dword v56, v193, s[6:7]
	global_load_dword v57, v193, s[6:7] offset:256
	global_load_dword v58, v24, s[0:1]
	global_load_dword v59, v25, s[0:1]
	global_load_dword v60, v24, s[4:5]
	global_load_dword v61, v25, s[4:5]
	s_add_u32 s6, s6, s14
	s_addc_u32 s7, s7, 0
	global_load_dword v62, v193, s[6:7]
	global_load_dword v63, v193, s[6:7] offset:256
	global_load_dword v64, v26, s[0:1]
	global_load_dword v65, v27, s[0:1]
	global_load_dword v66, v26, s[4:5]
	global_load_dword v67, v27, s[4:5]
	s_add_u32 s6, s6, s14
	s_addc_u32 s7, s7, 0
	global_load_dword v68, v193, s[6:7]
	global_load_dword v69, v193, s[6:7] offset:256
	global_load_dword v70, v28, s[0:1]
	global_load_dword v71, v29, s[0:1]
	global_load_dword v72, v28, s[4:5]
	global_load_dword v73, v29, s[4:5]
	s_add_u32 s6, s6, s14
	s_addc_u32 s7, s7, 0
	global_load_dword v74, v193, s[6:7]
	global_load_dword v75, v193, s[6:7] offset:256
	global_load_dword v76, v30, s[0:1]
	global_load_dword v77, v31, s[0:1]
	global_load_dword v78, v30, s[4:5]
	global_load_dword v79, v31, s[4:5]
	s_add_u32 s6, s6, s14
	s_addc_u32 s7, s7, 0
	s_waitcnt vmcnt(0)
	v_mul_f32_e32 v80, v34, v80
	v_mul_f32_e32 v180, 0x3f3504f3, v80
	v_fma_f32 v182, |v180|, s12, v177
	v_fma_f32 v182, |v180|, v182, s15
	v_fma_f32 v182, |v180|, v182, s16
	v_fma_f32 v182, |v180|, v182, s17
	v_fma_f32 v182, |v180|, v182, s18
	v_fma_f32 v182, |v180|, v182, s19
	v_fma_f32 v182, |v180|, v182, |v180|
	v_mul_f32_e32 v184, 0xbfb8aa3b, v182
	v_fma_f32 v185, v182, s98, -v184
	v_rndne_f32_e32 v186, v184
	v_fmac_f32_e32 v185, 0xb2a5705f, v182
	v_sub_f32_e32 v184, v184, v186
	v_add_f32_e32 v184, v184, v185
	v_cvt_i32_f32_e32 v185, v186
	v_exp_f32_e32 v184, v184
	v_cmp_nlt_f32_e32 vcc, s38, v182
	v_ldexp_f32 v184, v184, v185
	s_nop 0
	v_cndmask_b32_e32 v184, 0, v184, vcc
	v_cmp_ngt_f32_e32 vcc, s39, v182
	s_nop 1
	v_cndmask_b32_e32 v184, v178, v184, vcc
	v_sub_f32_e32 v184, 1.0, v184
	v_mul_f32_e32 v183, v180, v180
	v_fmamk_f32 v185, v183, 0xba1345e1, v176
	v_fmaak_f32 v185, v183, v185, 0xbcdac9b8
	v_fmaak_f32 v185, v183, v185, 0x3de703be
	v_fmaak_f32 v185, v183, v185, 0xbec09330
	v_fmaak_f32 v183, v183, v185, 0x3e0375d0
	v_fma_f32 v183, |v180|, v183, |v180|
	v_cmp_nlt_f32_e64 vcc, |v180|, 1.0
	s_nop 1
	v_cndmask_b32_e32 v184, v183, v184, vcc
	v_bfi_b32 v184, s10, v184, v180
	v_add_f32_e32 v184, 1.0, v184
	v_mul_f32_e32 v80, 0.5, v80
	v_mul_f32_e32 v32, v32, v36
	v_mul_f32_e32 v80, v80, v184
	v_mul_f32_e32 v80, v32, v80
	v_mul_f32_e32 v81, v35, v81
	v_mul_f32_e32 v180, 0x3f3504f3, v81
	v_fma_f32 v182, |v180|, s12, v177
	v_fma_f32 v182, |v180|, v182, s15
	v_fma_f32 v182, |v180|, v182, s16
	v_fma_f32 v182, |v180|, v182, s17
	v_fma_f32 v182, |v180|, v182, s18
	v_fma_f32 v182, |v180|, v182, s19
	v_fma_f32 v182, |v180|, v182, |v180|
	v_mul_f32_e32 v184, 0xbfb8aa3b, v182
	v_fma_f32 v185, v182, s98, -v184
	v_rndne_f32_e32 v186, v184
	v_fmac_f32_e32 v185, 0xb2a5705f, v182
	v_sub_f32_e32 v184, v184, v186
	v_add_f32_e32 v184, v184, v185
	v_cvt_i32_f32_e32 v185, v186
	v_exp_f32_e32 v184, v184
	v_cmp_nlt_f32_e32 vcc, s38, v182
	v_ldexp_f32 v184, v184, v185
	s_nop 0
	v_cndmask_b32_e32 v184, 0, v184, vcc
	v_cmp_ngt_f32_e32 vcc, s39, v182
	s_nop 1
	v_cndmask_b32_e32 v184, v178, v184, vcc
	v_sub_f32_e32 v184, 1.0, v184
	v_mul_f32_e32 v183, v180, v180
	v_fmamk_f32 v185, v183, 0xba1345e1, v176
	v_fmaak_f32 v185, v183, v185, 0xbcdac9b8
	v_fmaak_f32 v185, v183, v185, 0x3de703be
	v_fmaak_f32 v185, v183, v185, 0xbec09330
	v_fmaak_f32 v183, v183, v185, 0x3e0375d0
	v_fma_f32 v183, |v180|, v183, |v180|
	v_cmp_nlt_f32_e64 vcc, |v180|, 1.0
	s_nop 1
	v_cndmask_b32_e32 v184, v183, v184, vcc
	v_bfi_b32 v184, s10, v184, v180
	v_add_f32_e32 v184, 1.0, v184
	v_mul_f32_e32 v81, 0.5, v81
	v_mul_f32_e32 v33, v33, v37
	v_mul_f32_e32 v81, v81, v184
	v_mul_f32_e32 v81, v33, v81
	global_store_dword v193, v80, s[8:9]
	global_store_dword v193, v81, s[8:9] offset:256
	s_add_u32 s8, s8, s14
	s_addc_u32 s9, s9, 0
	v_mul_f32_e32 v82, v40, v82
	v_mul_f32_e32 v180, 0x3f3504f3, v82
	v_fma_f32 v182, |v180|, s12, v177
	v_fma_f32 v182, |v180|, v182, s15
	v_fma_f32 v182, |v180|, v182, s16
	v_fma_f32 v182, |v180|, v182, s17
	v_fma_f32 v182, |v180|, v182, s18
	v_fma_f32 v182, |v180|, v182, s19
	v_fma_f32 v182, |v180|, v182, |v180|
	v_mul_f32_e32 v184, 0xbfb8aa3b, v182
	v_fma_f32 v185, v182, s98, -v184
	v_rndne_f32_e32 v186, v184
	v_fmac_f32_e32 v185, 0xb2a5705f, v182
	v_sub_f32_e32 v184, v184, v186
	v_add_f32_e32 v184, v184, v185
	v_cvt_i32_f32_e32 v185, v186
	v_exp_f32_e32 v184, v184
	v_cmp_nlt_f32_e32 vcc, s38, v182
	v_ldexp_f32 v184, v184, v185
	s_nop 0
	v_cndmask_b32_e32 v184, 0, v184, vcc
	v_cmp_ngt_f32_e32 vcc, s39, v182
	s_nop 1
	v_cndmask_b32_e32 v184, v178, v184, vcc
	v_sub_f32_e32 v184, 1.0, v184
	v_mul_f32_e32 v183, v180, v180
	v_fmamk_f32 v185, v183, 0xba1345e1, v176
	v_fmaak_f32 v185, v183, v185, 0xbcdac9b8
	v_fmaak_f32 v185, v183, v185, 0x3de703be
	v_fmaak_f32 v185, v183, v185, 0xbec09330
	v_fmaak_f32 v183, v183, v185, 0x3e0375d0
	v_fma_f32 v183, |v180|, v183, |v180|
	v_cmp_nlt_f32_e64 vcc, |v180|, 1.0
	s_nop 1
	v_cndmask_b32_e32 v184, v183, v184, vcc
	v_bfi_b32 v184, s10, v184, v180
	v_add_f32_e32 v184, 1.0, v184
	v_mul_f32_e32 v82, 0.5, v82
	v_mul_f32_e32 v38, v38, v42
	v_mul_f32_e32 v82, v82, v184
	v_mul_f32_e32 v82, v38, v82
	v_mul_f32_e32 v83, v41, v83
	v_mul_f32_e32 v180, 0x3f3504f3, v83
	v_fma_f32 v182, |v180|, s12, v177
	v_fma_f32 v182, |v180|, v182, s15
	v_fma_f32 v182, |v180|, v182, s16
	v_fma_f32 v182, |v180|, v182, s17
	v_fma_f32 v182, |v180|, v182, s18
	v_fma_f32 v182, |v180|, v182, s19
	v_fma_f32 v182, |v180|, v182, |v180|
	v_mul_f32_e32 v184, 0xbfb8aa3b, v182
	v_fma_f32 v185, v182, s98, -v184
	v_rndne_f32_e32 v186, v184
	v_fmac_f32_e32 v185, 0xb2a5705f, v182
	v_sub_f32_e32 v184, v184, v186
	v_add_f32_e32 v184, v184, v185
	v_cvt_i32_f32_e32 v185, v186
	v_exp_f32_e32 v184, v184
	v_cmp_nlt_f32_e32 vcc, s38, v182
	v_ldexp_f32 v184, v184, v185
	s_nop 0
	v_cndmask_b32_e32 v184, 0, v184, vcc
	v_cmp_ngt_f32_e32 vcc, s39, v182
	s_nop 1
	v_cndmask_b32_e32 v184, v178, v184, vcc
	v_sub_f32_e32 v184, 1.0, v184
	v_mul_f32_e32 v183, v180, v180
	v_fmamk_f32 v185, v183, 0xba1345e1, v176
	v_fmaak_f32 v185, v183, v185, 0xbcdac9b8
	v_fmaak_f32 v185, v183, v185, 0x3de703be
	v_fmaak_f32 v185, v183, v185, 0xbec09330
	v_fmaak_f32 v183, v183, v185, 0x3e0375d0
	v_fma_f32 v183, |v180|, v183, |v180|
	v_cmp_nlt_f32_e64 vcc, |v180|, 1.0
	s_nop 1
	v_cndmask_b32_e32 v184, v183, v184, vcc
	v_bfi_b32 v184, s10, v184, v180
	v_add_f32_e32 v184, 1.0, v184
	v_mul_f32_e32 v83, 0.5, v83
	v_mul_f32_e32 v39, v39, v43
	v_mul_f32_e32 v83, v83, v184
	v_mul_f32_e32 v83, v39, v83
	global_store_dword v193, v82, s[8:9]
	global_store_dword v193, v83, s[8:9] offset:256
	s_add_u32 s8, s8, s14
	s_addc_u32 s9, s9, 0
	v_mul_f32_e32 v84, v46, v84
	v_mul_f32_e32 v180, 0x3f3504f3, v84
	v_fma_f32 v182, |v180|, s12, v177
	v_fma_f32 v182, |v180|, v182, s15
	v_fma_f32 v182, |v180|, v182, s16
	v_fma_f32 v182, |v180|, v182, s17
	v_fma_f32 v182, |v180|, v182, s18
	v_fma_f32 v182, |v180|, v182, s19
	v_fma_f32 v182, |v180|, v182, |v180|
	v_mul_f32_e32 v184, 0xbfb8aa3b, v182
	v_fma_f32 v185, v182, s98, -v184
	v_rndne_f32_e32 v186, v184
	v_fmac_f32_e32 v185, 0xb2a5705f, v182
	v_sub_f32_e32 v184, v184, v186
	v_add_f32_e32 v184, v184, v185
	v_cvt_i32_f32_e32 v185, v186
	v_exp_f32_e32 v184, v184
	v_cmp_nlt_f32_e32 vcc, s38, v182
	v_ldexp_f32 v184, v184, v185
	s_nop 0
	v_cndmask_b32_e32 v184, 0, v184, vcc
	v_cmp_ngt_f32_e32 vcc, s39, v182
	s_nop 1
	v_cndmask_b32_e32 v184, v178, v184, vcc
	v_sub_f32_e32 v184, 1.0, v184
	v_mul_f32_e32 v183, v180, v180
	v_fmamk_f32 v185, v183, 0xba1345e1, v176
	v_fmaak_f32 v185, v183, v185, 0xbcdac9b8
	v_fmaak_f32 v185, v183, v185, 0x3de703be
	v_fmaak_f32 v185, v183, v185, 0xbec09330
	v_fmaak_f32 v183, v183, v185, 0x3e0375d0
	v_fma_f32 v183, |v180|, v183, |v180|
	v_cmp_nlt_f32_e64 vcc, |v180|, 1.0
	s_nop 1
	v_cndmask_b32_e32 v184, v183, v184, vcc
	v_bfi_b32 v184, s10, v184, v180
	v_add_f32_e32 v184, 1.0, v184
	v_mul_f32_e32 v84, 0.5, v84
	v_mul_f32_e32 v44, v44, v48
	v_mul_f32_e32 v84, v84, v184
	v_mul_f32_e32 v84, v44, v84
	v_mul_f32_e32 v85, v47, v85
	v_mul_f32_e32 v180, 0x3f3504f3, v85
	v_fma_f32 v182, |v180|, s12, v177
	v_fma_f32 v182, |v180|, v182, s15
	v_fma_f32 v182, |v180|, v182, s16
	v_fma_f32 v182, |v180|, v182, s17
	v_fma_f32 v182, |v180|, v182, s18
	v_fma_f32 v182, |v180|, v182, s19
	v_fma_f32 v182, |v180|, v182, |v180|
	v_mul_f32_e32 v184, 0xbfb8aa3b, v182
	v_fma_f32 v185, v182, s98, -v184
	v_rndne_f32_e32 v186, v184
	v_fmac_f32_e32 v185, 0xb2a5705f, v182
	v_sub_f32_e32 v184, v184, v186
	v_add_f32_e32 v184, v184, v185
	v_cvt_i32_f32_e32 v185, v186
	v_exp_f32_e32 v184, v184
	v_cmp_nlt_f32_e32 vcc, s38, v182
	v_ldexp_f32 v184, v184, v185
	s_nop 0
	v_cndmask_b32_e32 v184, 0, v184, vcc
	v_cmp_ngt_f32_e32 vcc, s39, v182
	s_nop 1
	v_cndmask_b32_e32 v184, v178, v184, vcc
	v_sub_f32_e32 v184, 1.0, v184
	v_mul_f32_e32 v183, v180, v180
	v_fmamk_f32 v185, v183, 0xba1345e1, v176
	v_fmaak_f32 v185, v183, v185, 0xbcdac9b8
	v_fmaak_f32 v185, v183, v185, 0x3de703be
	v_fmaak_f32 v185, v183, v185, 0xbec09330
	v_fmaak_f32 v183, v183, v185, 0x3e0375d0
	v_fma_f32 v183, |v180|, v183, |v180|
	v_cmp_nlt_f32_e64 vcc, |v180|, 1.0
	s_nop 1
	v_cndmask_b32_e32 v184, v183, v184, vcc
	v_bfi_b32 v184, s10, v184, v180
	v_add_f32_e32 v184, 1.0, v184
	v_mul_f32_e32 v85, 0.5, v85
	v_mul_f32_e32 v45, v45, v49
	v_mul_f32_e32 v85, v85, v184
	v_mul_f32_e32 v85, v45, v85
	global_store_dword v193, v84, s[8:9]
	global_store_dword v193, v85, s[8:9] offset:256
	s_add_u32 s8, s8, s14
	s_addc_u32 s9, s9, 0
	v_mul_f32_e32 v86, v52, v86
	v_mul_f32_e32 v180, 0x3f3504f3, v86
	v_fma_f32 v182, |v180|, s12, v177
	v_fma_f32 v182, |v180|, v182, s15
	v_fma_f32 v182, |v180|, v182, s16
	v_fma_f32 v182, |v180|, v182, s17
	v_fma_f32 v182, |v180|, v182, s18
	v_fma_f32 v182, |v180|, v182, s19
	v_fma_f32 v182, |v180|, v182, |v180|
	v_mul_f32_e32 v184, 0xbfb8aa3b, v182
	v_fma_f32 v185, v182, s98, -v184
	v_rndne_f32_e32 v186, v184
	v_fmac_f32_e32 v185, 0xb2a5705f, v182
	v_sub_f32_e32 v184, v184, v186
	v_add_f32_e32 v184, v184, v185
	v_cvt_i32_f32_e32 v185, v186
	v_exp_f32_e32 v184, v184
	v_cmp_nlt_f32_e32 vcc, s38, v182
	v_ldexp_f32 v184, v184, v185
	s_nop 0
	v_cndmask_b32_e32 v184, 0, v184, vcc
	v_cmp_ngt_f32_e32 vcc, s39, v182
	s_nop 1
	v_cndmask_b32_e32 v184, v178, v184, vcc
	v_sub_f32_e32 v184, 1.0, v184
	v_mul_f32_e32 v183, v180, v180
	v_fmamk_f32 v185, v183, 0xba1345e1, v176
	v_fmaak_f32 v185, v183, v185, 0xbcdac9b8
	v_fmaak_f32 v185, v183, v185, 0x3de703be
	v_fmaak_f32 v185, v183, v185, 0xbec09330
	v_fmaak_f32 v183, v183, v185, 0x3e0375d0
	v_fma_f32 v183, |v180|, v183, |v180|
	v_cmp_nlt_f32_e64 vcc, |v180|, 1.0
	s_nop 1
	v_cndmask_b32_e32 v184, v183, v184, vcc
	v_bfi_b32 v184, s10, v184, v180
	v_add_f32_e32 v184, 1.0, v184
	v_mul_f32_e32 v86, 0.5, v86
	v_mul_f32_e32 v50, v50, v54
	v_mul_f32_e32 v86, v86, v184
	v_mul_f32_e32 v86, v50, v86
	v_mul_f32_e32 v87, v53, v87
	v_mul_f32_e32 v180, 0x3f3504f3, v87
	v_fma_f32 v182, |v180|, s12, v177
	v_fma_f32 v182, |v180|, v182, s15
	v_fma_f32 v182, |v180|, v182, s16
	v_fma_f32 v182, |v180|, v182, s17
	v_fma_f32 v182, |v180|, v182, s18
	v_fma_f32 v182, |v180|, v182, s19
	v_fma_f32 v182, |v180|, v182, |v180|
	v_mul_f32_e32 v184, 0xbfb8aa3b, v182
	v_fma_f32 v185, v182, s98, -v184
	v_rndne_f32_e32 v186, v184
	v_fmac_f32_e32 v185, 0xb2a5705f, v182
	v_sub_f32_e32 v184, v184, v186
	v_add_f32_e32 v184, v184, v185
	v_cvt_i32_f32_e32 v185, v186
	v_exp_f32_e32 v184, v184
	v_cmp_nlt_f32_e32 vcc, s38, v182
	v_ldexp_f32 v184, v184, v185
	s_nop 0
	v_cndmask_b32_e32 v184, 0, v184, vcc
	v_cmp_ngt_f32_e32 vcc, s39, v182
	s_nop 1
	v_cndmask_b32_e32 v184, v178, v184, vcc
	v_sub_f32_e32 v184, 1.0, v184
	v_mul_f32_e32 v183, v180, v180
	v_fmamk_f32 v185, v183, 0xba1345e1, v176
	v_fmaak_f32 v185, v183, v185, 0xbcdac9b8
	v_fmaak_f32 v185, v183, v185, 0x3de703be
	v_fmaak_f32 v185, v183, v185, 0xbec09330
	v_fmaak_f32 v183, v183, v185, 0x3e0375d0
	v_fma_f32 v183, |v180|, v183, |v180|
	v_cmp_nlt_f32_e64 vcc, |v180|, 1.0
	s_nop 1
	v_cndmask_b32_e32 v184, v183, v184, vcc
	v_bfi_b32 v184, s10, v184, v180
	v_add_f32_e32 v184, 1.0, v184
	v_mul_f32_e32 v87, 0.5, v87
	v_mul_f32_e32 v51, v51, v55
	v_mul_f32_e32 v87, v87, v184
	v_mul_f32_e32 v87, v51, v87
	global_store_dword v193, v86, s[8:9]
	global_store_dword v193, v87, s[8:9] offset:256
	s_add_u32 s8, s8, s14
	s_addc_u32 s9, s9, 0
	v_mul_f32_e32 v88, v58, v88
	v_mul_f32_e32 v180, 0x3f3504f3, v88
	v_fma_f32 v182, |v180|, s12, v177
	v_fma_f32 v182, |v180|, v182, s15
	v_fma_f32 v182, |v180|, v182, s16
	v_fma_f32 v182, |v180|, v182, s17
	v_fma_f32 v182, |v180|, v182, s18
	v_fma_f32 v182, |v180|, v182, s19
	v_fma_f32 v182, |v180|, v182, |v180|
	v_mul_f32_e32 v184, 0xbfb8aa3b, v182
	v_fma_f32 v185, v182, s98, -v184
	v_rndne_f32_e32 v186, v184
	v_fmac_f32_e32 v185, 0xb2a5705f, v182
	v_sub_f32_e32 v184, v184, v186
	v_add_f32_e32 v184, v184, v185
	v_cvt_i32_f32_e32 v185, v186
	v_exp_f32_e32 v184, v184
	v_cmp_nlt_f32_e32 vcc, s38, v182
	v_ldexp_f32 v184, v184, v185
	s_nop 0
	v_cndmask_b32_e32 v184, 0, v184, vcc
	v_cmp_ngt_f32_e32 vcc, s39, v182
	s_nop 1
	v_cndmask_b32_e32 v184, v178, v184, vcc
	v_sub_f32_e32 v184, 1.0, v184
	v_mul_f32_e32 v183, v180, v180
	v_fmamk_f32 v185, v183, 0xba1345e1, v176
	v_fmaak_f32 v185, v183, v185, 0xbcdac9b8
	v_fmaak_f32 v185, v183, v185, 0x3de703be
	v_fmaak_f32 v185, v183, v185, 0xbec09330
	v_fmaak_f32 v183, v183, v185, 0x3e0375d0
	v_fma_f32 v183, |v180|, v183, |v180|
	v_cmp_nlt_f32_e64 vcc, |v180|, 1.0
	s_nop 1
	v_cndmask_b32_e32 v184, v183, v184, vcc
	v_bfi_b32 v184, s10, v184, v180
	v_add_f32_e32 v184, 1.0, v184
	v_mul_f32_e32 v88, 0.5, v88
	v_mul_f32_e32 v56, v56, v60
	v_mul_f32_e32 v88, v88, v184
	v_mul_f32_e32 v88, v56, v88
	v_mul_f32_e32 v89, v59, v89
	v_mul_f32_e32 v180, 0x3f3504f3, v89
	v_fma_f32 v182, |v180|, s12, v177
	v_fma_f32 v182, |v180|, v182, s15
	v_fma_f32 v182, |v180|, v182, s16
	v_fma_f32 v182, |v180|, v182, s17
	v_fma_f32 v182, |v180|, v182, s18
	v_fma_f32 v182, |v180|, v182, s19
	v_fma_f32 v182, |v180|, v182, |v180|
	v_mul_f32_e32 v184, 0xbfb8aa3b, v182
	v_fma_f32 v185, v182, s98, -v184
	v_rndne_f32_e32 v186, v184
	v_fmac_f32_e32 v185, 0xb2a5705f, v182
	v_sub_f32_e32 v184, v184, v186
	v_add_f32_e32 v184, v184, v185
	v_cvt_i32_f32_e32 v185, v186
	v_exp_f32_e32 v184, v184
	v_cmp_nlt_f32_e32 vcc, s38, v182
	v_ldexp_f32 v184, v184, v185
	s_nop 0
	v_cndmask_b32_e32 v184, 0, v184, vcc
	v_cmp_ngt_f32_e32 vcc, s39, v182
	s_nop 1
	v_cndmask_b32_e32 v184, v178, v184, vcc
	v_sub_f32_e32 v184, 1.0, v184
	v_mul_f32_e32 v183, v180, v180
	v_fmamk_f32 v185, v183, 0xba1345e1, v176
	v_fmaak_f32 v185, v183, v185, 0xbcdac9b8
	v_fmaak_f32 v185, v183, v185, 0x3de703be
	v_fmaak_f32 v185, v183, v185, 0xbec09330
	v_fmaak_f32 v183, v183, v185, 0x3e0375d0
	v_fma_f32 v183, |v180|, v183, |v180|
	v_cmp_nlt_f32_e64 vcc, |v180|, 1.0
	s_nop 1
	v_cndmask_b32_e32 v184, v183, v184, vcc
	v_bfi_b32 v184, s10, v184, v180
	v_add_f32_e32 v184, 1.0, v184
	v_mul_f32_e32 v89, 0.5, v89
	v_mul_f32_e32 v57, v57, v61
	v_mul_f32_e32 v89, v89, v184
	v_mul_f32_e32 v89, v57, v89
	global_store_dword v193, v88, s[8:9]
	global_store_dword v193, v89, s[8:9] offset:256
	s_add_u32 s8, s8, s14
	s_addc_u32 s9, s9, 0
	v_mul_f32_e32 v90, v64, v90
	v_mul_f32_e32 v180, 0x3f3504f3, v90
	v_fma_f32 v182, |v180|, s12, v177
	v_fma_f32 v182, |v180|, v182, s15
	v_fma_f32 v182, |v180|, v182, s16
	v_fma_f32 v182, |v180|, v182, s17
	v_fma_f32 v182, |v180|, v182, s18
	v_fma_f32 v182, |v180|, v182, s19
	v_fma_f32 v182, |v180|, v182, |v180|
	v_mul_f32_e32 v184, 0xbfb8aa3b, v182
	v_fma_f32 v185, v182, s98, -v184
	v_rndne_f32_e32 v186, v184
	v_fmac_f32_e32 v185, 0xb2a5705f, v182
	v_sub_f32_e32 v184, v184, v186
	v_add_f32_e32 v184, v184, v185
	v_cvt_i32_f32_e32 v185, v186
	v_exp_f32_e32 v184, v184
	v_cmp_nlt_f32_e32 vcc, s38, v182
	v_ldexp_f32 v184, v184, v185
	s_nop 0
	v_cndmask_b32_e32 v184, 0, v184, vcc
	v_cmp_ngt_f32_e32 vcc, s39, v182
	s_nop 1
	v_cndmask_b32_e32 v184, v178, v184, vcc
	v_sub_f32_e32 v184, 1.0, v184
	v_mul_f32_e32 v183, v180, v180
	v_fmamk_f32 v185, v183, 0xba1345e1, v176
	v_fmaak_f32 v185, v183, v185, 0xbcdac9b8
	v_fmaak_f32 v185, v183, v185, 0x3de703be
	v_fmaak_f32 v185, v183, v185, 0xbec09330
	v_fmaak_f32 v183, v183, v185, 0x3e0375d0
	v_fma_f32 v183, |v180|, v183, |v180|
	v_cmp_nlt_f32_e64 vcc, |v180|, 1.0
	s_nop 1
	v_cndmask_b32_e32 v184, v183, v184, vcc
	v_bfi_b32 v184, s10, v184, v180
	v_add_f32_e32 v184, 1.0, v184
	v_mul_f32_e32 v90, 0.5, v90
	v_mul_f32_e32 v62, v62, v66
	v_mul_f32_e32 v90, v90, v184
	v_mul_f32_e32 v90, v62, v90
	v_mul_f32_e32 v91, v65, v91
	v_mul_f32_e32 v180, 0x3f3504f3, v91
	v_fma_f32 v182, |v180|, s12, v177
	v_fma_f32 v182, |v180|, v182, s15
	v_fma_f32 v182, |v180|, v182, s16
	v_fma_f32 v182, |v180|, v182, s17
	v_fma_f32 v182, |v180|, v182, s18
	v_fma_f32 v182, |v180|, v182, s19
	v_fma_f32 v182, |v180|, v182, |v180|
	v_mul_f32_e32 v184, 0xbfb8aa3b, v182
	v_fma_f32 v185, v182, s98, -v184
	v_rndne_f32_e32 v186, v184
	v_fmac_f32_e32 v185, 0xb2a5705f, v182
	v_sub_f32_e32 v184, v184, v186
	v_add_f32_e32 v184, v184, v185
	v_cvt_i32_f32_e32 v185, v186
	v_exp_f32_e32 v184, v184
	v_cmp_nlt_f32_e32 vcc, s38, v182
	v_ldexp_f32 v184, v184, v185
	s_nop 0
	v_cndmask_b32_e32 v184, 0, v184, vcc
	v_cmp_ngt_f32_e32 vcc, s39, v182
	s_nop 1
	v_cndmask_b32_e32 v184, v178, v184, vcc
	v_sub_f32_e32 v184, 1.0, v184
	v_mul_f32_e32 v183, v180, v180
	v_fmamk_f32 v185, v183, 0xba1345e1, v176
	v_fmaak_f32 v185, v183, v185, 0xbcdac9b8
	v_fmaak_f32 v185, v183, v185, 0x3de703be
	v_fmaak_f32 v185, v183, v185, 0xbec09330
	v_fmaak_f32 v183, v183, v185, 0x3e0375d0
	v_fma_f32 v183, |v180|, v183, |v180|
	v_cmp_nlt_f32_e64 vcc, |v180|, 1.0
	s_nop 1
	v_cndmask_b32_e32 v184, v183, v184, vcc
	v_bfi_b32 v184, s10, v184, v180
	v_add_f32_e32 v184, 1.0, v184
	v_mul_f32_e32 v91, 0.5, v91
	v_mul_f32_e32 v63, v63, v67
	v_mul_f32_e32 v91, v91, v184
	v_mul_f32_e32 v91, v63, v91
	global_store_dword v193, v90, s[8:9]
	global_store_dword v193, v91, s[8:9] offset:256
	s_add_u32 s8, s8, s14
	s_addc_u32 s9, s9, 0
	v_mul_f32_e32 v92, v70, v92
	v_mul_f32_e32 v180, 0x3f3504f3, v92
	v_fma_f32 v182, |v180|, s12, v177
	v_fma_f32 v182, |v180|, v182, s15
	v_fma_f32 v182, |v180|, v182, s16
	v_fma_f32 v182, |v180|, v182, s17
	v_fma_f32 v182, |v180|, v182, s18
	v_fma_f32 v182, |v180|, v182, s19
	v_fma_f32 v182, |v180|, v182, |v180|
	v_mul_f32_e32 v184, 0xbfb8aa3b, v182
	v_fma_f32 v185, v182, s98, -v184
	v_rndne_f32_e32 v186, v184
	v_fmac_f32_e32 v185, 0xb2a5705f, v182
	v_sub_f32_e32 v184, v184, v186
	v_add_f32_e32 v184, v184, v185
	v_cvt_i32_f32_e32 v185, v186
	v_exp_f32_e32 v184, v184
	v_cmp_nlt_f32_e32 vcc, s38, v182
	v_ldexp_f32 v184, v184, v185
	s_nop 0
	v_cndmask_b32_e32 v184, 0, v184, vcc
	v_cmp_ngt_f32_e32 vcc, s39, v182
	s_nop 1
	v_cndmask_b32_e32 v184, v178, v184, vcc
	v_sub_f32_e32 v184, 1.0, v184
	v_mul_f32_e32 v183, v180, v180
	v_fmamk_f32 v185, v183, 0xba1345e1, v176
	v_fmaak_f32 v185, v183, v185, 0xbcdac9b8
	v_fmaak_f32 v185, v183, v185, 0x3de703be
	v_fmaak_f32 v185, v183, v185, 0xbec09330
	v_fmaak_f32 v183, v183, v185, 0x3e0375d0
	v_fma_f32 v183, |v180|, v183, |v180|
	v_cmp_nlt_f32_e64 vcc, |v180|, 1.0
	s_nop 1
	v_cndmask_b32_e32 v184, v183, v184, vcc
	v_bfi_b32 v184, s10, v184, v180
	v_add_f32_e32 v184, 1.0, v184
	v_mul_f32_e32 v92, 0.5, v92
	v_mul_f32_e32 v68, v68, v72
	v_mul_f32_e32 v92, v92, v184
	v_mul_f32_e32 v92, v68, v92
	v_mul_f32_e32 v93, v71, v93
	v_mul_f32_e32 v180, 0x3f3504f3, v93
	v_fma_f32 v182, |v180|, s12, v177
	v_fma_f32 v182, |v180|, v182, s15
	v_fma_f32 v182, |v180|, v182, s16
	v_fma_f32 v182, |v180|, v182, s17
	v_fma_f32 v182, |v180|, v182, s18
	v_fma_f32 v182, |v180|, v182, s19
	v_fma_f32 v182, |v180|, v182, |v180|
	v_mul_f32_e32 v184, 0xbfb8aa3b, v182
	v_fma_f32 v185, v182, s98, -v184
	v_rndne_f32_e32 v186, v184
	v_fmac_f32_e32 v185, 0xb2a5705f, v182
	v_sub_f32_e32 v184, v184, v186
	v_add_f32_e32 v184, v184, v185
	v_cvt_i32_f32_e32 v185, v186
	v_exp_f32_e32 v184, v184
	v_cmp_nlt_f32_e32 vcc, s38, v182
	v_ldexp_f32 v184, v184, v185
	s_nop 0
	v_cndmask_b32_e32 v184, 0, v184, vcc
	v_cmp_ngt_f32_e32 vcc, s39, v182
	s_nop 1
	v_cndmask_b32_e32 v184, v178, v184, vcc
	v_sub_f32_e32 v184, 1.0, v184
	v_mul_f32_e32 v183, v180, v180
	v_fmamk_f32 v185, v183, 0xba1345e1, v176
	v_fmaak_f32 v185, v183, v185, 0xbcdac9b8
	v_fmaak_f32 v185, v183, v185, 0x3de703be
	v_fmaak_f32 v185, v183, v185, 0xbec09330
	v_fmaak_f32 v183, v183, v185, 0x3e0375d0
	v_fma_f32 v183, |v180|, v183, |v180|
	v_cmp_nlt_f32_e64 vcc, |v180|, 1.0
	s_nop 1
	v_cndmask_b32_e32 v184, v183, v184, vcc
	v_bfi_b32 v184, s10, v184, v180
	v_add_f32_e32 v184, 1.0, v184
	v_mul_f32_e32 v93, 0.5, v93
	v_mul_f32_e32 v69, v69, v73
	v_mul_f32_e32 v93, v93, v184
	v_mul_f32_e32 v93, v69, v93
	global_store_dword v193, v92, s[8:9]
	global_store_dword v193, v93, s[8:9] offset:256
	s_add_u32 s8, s8, s14
	s_addc_u32 s9, s9, 0
	v_mul_f32_e32 v94, v76, v94
	v_mul_f32_e32 v180, 0x3f3504f3, v94
	v_fma_f32 v182, |v180|, s12, v177
	v_fma_f32 v182, |v180|, v182, s15
	v_fma_f32 v182, |v180|, v182, s16
	v_fma_f32 v182, |v180|, v182, s17
	v_fma_f32 v182, |v180|, v182, s18
	v_fma_f32 v182, |v180|, v182, s19
	v_fma_f32 v182, |v180|, v182, |v180|
	v_mul_f32_e32 v184, 0xbfb8aa3b, v182
	v_fma_f32 v185, v182, s98, -v184
	v_rndne_f32_e32 v186, v184
	v_fmac_f32_e32 v185, 0xb2a5705f, v182
	v_sub_f32_e32 v184, v184, v186
	v_add_f32_e32 v184, v184, v185
	v_cvt_i32_f32_e32 v185, v186
	v_exp_f32_e32 v184, v184
	v_cmp_nlt_f32_e32 vcc, s38, v182
	v_ldexp_f32 v184, v184, v185
	s_nop 0
	v_cndmask_b32_e32 v184, 0, v184, vcc
	v_cmp_ngt_f32_e32 vcc, s39, v182
	s_nop 1
	v_cndmask_b32_e32 v184, v178, v184, vcc
	v_sub_f32_e32 v184, 1.0, v184
	v_mul_f32_e32 v183, v180, v180
	v_fmamk_f32 v185, v183, 0xba1345e1, v176
	v_fmaak_f32 v185, v183, v185, 0xbcdac9b8
	v_fmaak_f32 v185, v183, v185, 0x3de703be
	v_fmaak_f32 v185, v183, v185, 0xbec09330
	v_fmaak_f32 v183, v183, v185, 0x3e0375d0
	v_fma_f32 v183, |v180|, v183, |v180|
	v_cmp_nlt_f32_e64 vcc, |v180|, 1.0
	s_nop 1
	v_cndmask_b32_e32 v184, v183, v184, vcc
	v_bfi_b32 v184, s10, v184, v180
	v_add_f32_e32 v184, 1.0, v184
	v_mul_f32_e32 v94, 0.5, v94
	v_mul_f32_e32 v74, v74, v78
	v_mul_f32_e32 v94, v94, v184
	v_mul_f32_e32 v94, v74, v94
	v_mul_f32_e32 v95, v77, v95
	v_mul_f32_e32 v180, 0x3f3504f3, v95
	v_fma_f32 v182, |v180|, s12, v177
	v_fma_f32 v182, |v180|, v182, s15
	v_fma_f32 v182, |v180|, v182, s16
	v_fma_f32 v182, |v180|, v182, s17
	v_fma_f32 v182, |v180|, v182, s18
	v_fma_f32 v182, |v180|, v182, s19
	v_fma_f32 v182, |v180|, v182, |v180|
	v_mul_f32_e32 v184, 0xbfb8aa3b, v182
	v_fma_f32 v185, v182, s98, -v184
	v_rndne_f32_e32 v186, v184
	v_fmac_f32_e32 v185, 0xb2a5705f, v182
	v_sub_f32_e32 v184, v184, v186
	v_add_f32_e32 v184, v184, v185
	v_cvt_i32_f32_e32 v185, v186
	v_exp_f32_e32 v184, v184
	v_cmp_nlt_f32_e32 vcc, s38, v182
	v_ldexp_f32 v184, v184, v185
	s_nop 0
	v_cndmask_b32_e32 v184, 0, v184, vcc
	v_cmp_ngt_f32_e32 vcc, s39, v182
	s_nop 1
	v_cndmask_b32_e32 v184, v178, v184, vcc
	v_sub_f32_e32 v184, 1.0, v184
	v_mul_f32_e32 v183, v180, v180
	v_fmamk_f32 v185, v183, 0xba1345e1, v176
	v_fmaak_f32 v185, v183, v185, 0xbcdac9b8
	v_fmaak_f32 v185, v183, v185, 0x3de703be
	v_fmaak_f32 v185, v183, v185, 0xbec09330
	v_fmaak_f32 v183, v183, v185, 0x3e0375d0
	v_fma_f32 v183, |v180|, v183, |v180|
	v_cmp_nlt_f32_e64 vcc, |v180|, 1.0
	s_nop 1
	v_cndmask_b32_e32 v184, v183, v184, vcc
	v_bfi_b32 v184, s10, v184, v180
	v_add_f32_e32 v184, 1.0, v184
	v_mul_f32_e32 v95, 0.5, v95
	v_mul_f32_e32 v75, v75, v79
	v_mul_f32_e32 v95, v95, v184
	v_mul_f32_e32 v95, v75, v95
	global_store_dword v193, v94, s[8:9]
	global_store_dword v193, v95, s[8:9] offset:256
	s_add_u32 s8, s8, s14
	s_addc_u32 s9, s9, 0
	s_lshl_b32 s13, s92, 6
	s_add_u32 s35, s35, s13
	s_cmpk_lt_u32 s35, 0x8000
	s_cbranch_scc1 .Lgu1_chunk
	s_branch .LBB0_1045

.Lgv1_chunk:
	s_movk_i32 s100, 0xc0
	s_lshl_b32 s16, s92, 14
	s_add_u32 s12, s26, 0xd800000
	s_addc_u32 s13, s27, 0
	s_lshl_b32 s15, s101, 9
	s_add_u32 s12, s12, s15
	s_addc_u32 s13, s13, 0
	s_lshl_b32 s18, s92, 11
	global_load_dword v64, v196, s[12:13]
	global_load_dword v65, v196, s[12:13] offset:256
	s_add_u32 s12, s12, s18
	s_addc_u32 s13, s13, 0
	global_load_dword v66, v196, s[12:13]
	global_load_dword v67, v196, s[12:13] offset:256
	s_add_u32 s12, s12, s18
	s_addc_u32 s13, s13, 0
	global_load_dword v68, v196, s[12:13]
	global_load_dword v69, v196, s[12:13] offset:256
	s_add_u32 s12, s12, s18
	s_addc_u32 s13, s13, 0
	global_load_dword v70, v196, s[12:13]
	global_load_dword v71, v196, s[12:13] offset:256
	s_add_u32 s12, s12, s18
	s_addc_u32 s13, s13, 0
	global_load_dword v72, v196, s[12:13]
	global_load_dword v73, v196, s[12:13] offset:256
	s_add_u32 s12, s12, s18
	s_addc_u32 s13, s13, 0
	global_load_dword v74, v196, s[12:13]
	global_load_dword v75, v196, s[12:13] offset:256
	s_add_u32 s12, s12, s18
	s_addc_u32 s13, s13, 0
	global_load_dword v76, v196, s[12:13]
	global_load_dword v77, v196, s[12:13] offset:256
	s_add_u32 s12, s12, s18
	s_addc_u32 s13, s13, 0
	global_load_dword v78, v196, s[12:13]
	global_load_dword v79, v196, s[12:13] offset:256
	s_add_u32 s12, s12, s18
	s_addc_u32 s13, s13, 0
	global_load_dword v80, v196, s[12:13]
	global_load_dword v81, v196, s[12:13] offset:256
	s_add_u32 s12, s12, s18
	s_addc_u32 s13, s13, 0
	global_load_dword v82, v196, s[12:13]
	global_load_dword v83, v196, s[12:13] offset:256
	s_add_u32 s12, s12, s18
	s_addc_u32 s13, s13, 0
	global_load_dword v84, v196, s[12:13]
	global_load_dword v85, v196, s[12:13] offset:256
	s_add_u32 s12, s12, s18
	s_addc_u32 s13, s13, 0
	global_load_dword v86, v196, s[12:13]
	global_load_dword v87, v196, s[12:13] offset:256
	s_add_u32 s12, s12, s18
	s_addc_u32 s13, s13, 0
	global_load_dword v88, v196, s[12:13]
	global_load_dword v89, v196, s[12:13] offset:256
	s_add_u32 s12, s12, s18
	s_addc_u32 s13, s13, 0
	global_load_dword v90, v196, s[12:13]
	global_load_dword v91, v196, s[12:13] offset:256
	s_add_u32 s12, s12, s18
	s_addc_u32 s13, s13, 0
	global_load_dword v92, v196, s[12:13]
	global_load_dword v93, v196, s[12:13] offset:256
	s_add_u32 s12, s12, s18
	s_addc_u32 s13, s13, 0
	global_load_dword v94, v196, s[12:13]
	global_load_dword v95, v196, s[12:13] offset:256
	s_add_u32 s12, s12, s18
	s_addc_u32 s13, s13, 0
	s_waitcnt vmcnt(0)
	ds_write2st64_b32 v206, v64, v65 offset0:0 offset1:1
	ds_write2st64_b32 v206, v66, v67 offset0:2 offset1:3
	ds_write2st64_b32 v206, v68, v69 offset0:4 offset1:5
	ds_write2st64_b32 v206, v70, v71 offset0:6 offset1:7
	ds_write2st64_b32 v206, v72, v73 offset0:8 offset1:9
	ds_write2st64_b32 v206, v74, v75 offset0:10 offset1:11
	ds_write2st64_b32 v206, v76, v77 offset0:12 offset1:13
	ds_write2st64_b32 v206, v78, v79 offset0:14 offset1:15
	ds_write2st64_b32 v206, v80, v81 offset0:16 offset1:17
	ds_write2st64_b32 v206, v82, v83 offset0:18 offset1:19
	ds_write2st64_b32 v206, v84, v85 offset0:20 offset1:21
	ds_write2st64_b32 v206, v86, v87 offset0:22 offset1:23
	ds_write2st64_b32 v206, v88, v89 offset0:24 offset1:25
	ds_write2st64_b32 v206, v90, v91 offset0:26 offset1:27
	ds_write2st64_b32 v206, v92, v93 offset0:28 offset1:29
	ds_write2st64_b32 v206, v94, v95 offset0:30 offset1:31
	s_add_u32 s12, s26, 0xf800000
	s_addc_u32 s13, s27, 0
	s_lshl_b32 s15, s101, 9
	s_add_u32 s12, s12, s15
	s_addc_u32 s13, s13, 0
	s_lshl_b32 s18, s92, 11
	global_load_dword v64, v196, s[12:13]
	global_load_dword v65, v196, s[12:13] offset:256
	s_add_u32 s12, s12, s18
	s_addc_u32 s13, s13, 0
	global_load_dword v66, v196, s[12:13]
	global_load_dword v67, v196, s[12:13] offset:256
	s_add_u32 s12, s12, s18
	s_addc_u32 s13, s13, 0
	global_load_dword v68, v196, s[12:13]
	global_load_dword v69, v196, s[12:13] offset:256
	s_add_u32 s12, s12, s18
	s_addc_u32 s13, s13, 0
	global_load_dword v70, v196, s[12:13]
	global_load_dword v71, v196, s[12:13] offset:256
	s_add_u32 s12, s12, s18
	s_addc_u32 s13, s13, 0
	global_load_dword v72, v196, s[12:13]
	global_load_dword v73, v196, s[12:13] offset:256
	s_add_u32 s12, s12, s18
	s_addc_u32 s13, s13, 0
	global_load_dword v74, v196, s[12:13]
	global_load_dword v75, v196, s[12:13] offset:256
	s_add_u32 s12, s12, s18
	s_addc_u32 s13, s13, 0
	global_load_dword v76, v196, s[12:13]
	global_load_dword v77, v196, s[12:13] offset:256
	s_add_u32 s12, s12, s18
	s_addc_u32 s13, s13, 0
	global_load_dword v78, v196, s[12:13]
	global_load_dword v79, v196, s[12:13] offset:256
	s_add_u32 s12, s12, s18
	s_addc_u32 s13, s13, 0
	global_load_dword v80, v196, s[12:13]
	global_load_dword v81, v196, s[12:13] offset:256
	s_add_u32 s12, s12, s18
	s_addc_u32 s13, s13, 0
	global_load_dword v82, v196, s[12:13]
	global_load_dword v83, v196, s[12:13] offset:256
	s_add_u32 s12, s12, s18
	s_addc_u32 s13, s13, 0
	global_load_dword v84, v196, s[12:13]
	global_load_dword v85, v196, s[12:13] offset:256
	s_add_u32 s12, s12, s18
	s_addc_u32 s13, s13, 0
	global_load_dword v86, v196, s[12:13]
	global_load_dword v87, v196, s[12:13] offset:256
	s_add_u32 s12, s12, s18
	s_addc_u32 s13, s13, 0
	global_load_dword v88, v196, s[12:13]
	global_load_dword v89, v196, s[12:13] offset:256
	s_add_u32 s12, s12, s18
	s_addc_u32 s13, s13, 0
	global_load_dword v90, v196, s[12:13]
	global_load_dword v91, v196, s[12:13] offset:256
	s_add_u32 s12, s12, s18
	s_addc_u32 s13, s13, 0
	global_load_dword v92, v196, s[12:13]
	global_load_dword v93, v196, s[12:13] offset:256
	s_add_u32 s12, s12, s18
	s_addc_u32 s13, s13, 0
	global_load_dword v94, v196, s[12:13]
	global_load_dword v95, v196, s[12:13] offset:256
	s_add_u32 s12, s12, s18
	s_addc_u32 s13, s13, 0
	s_waitcnt vmcnt(0)
	ds_write2st64_b32 v208, v64, v65 offset0:0 offset1:1
	ds_write2st64_b32 v208, v66, v67 offset0:2 offset1:3
	ds_write2st64_b32 v208, v68, v69 offset0:4 offset1:5
	ds_write2st64_b32 v208, v70, v71 offset0:6 offset1:7
	ds_write2st64_b32 v208, v72, v73 offset0:8 offset1:9
	ds_write2st64_b32 v208, v74, v75 offset0:10 offset1:11
	ds_write2st64_b32 v208, v76, v77 offset0:12 offset1:13
	ds_write2st64_b32 v208, v78, v79 offset0:14 offset1:15
	ds_write2st64_b32 v208, v80, v81 offset0:16 offset1:17
	ds_write2st64_b32 v208, v82, v83 offset0:18 offset1:19
	ds_write2st64_b32 v208, v84, v85 offset0:20 offset1:21
	ds_write2st64_b32 v208, v86, v87 offset0:22 offset1:23
	ds_write2st64_b32 v208, v88, v89 offset0:24 offset1:25
	ds_write2st64_b32 v208, v90, v91 offset0:26 offset1:27
	ds_write2st64_b32 v208, v92, v93 offset0:28 offset1:29
	ds_write2st64_b32 v208, v94, v95 offset0:30 offset1:31
	s_waitcnt lgkmcnt(0)
	v_mov_b32_e32 v209, 0x12000
	ds_read_b32 v212, v209
	s_waitcnt lgkmcnt(0)
	v_readfirstlane_b32 s13, v212
	s_nop 3
	s_lshl_b32 s13, s13, 2
	s_mov_b32 s14, 0
	s_mov_b32 s18, 0
	s_and_b32 s19, s18, 15
	s_lshr_b32 s98, s18, 4
	s_lshl_b32 s99, s19, 9
	s_mul_i32 s15, s19, s16
	s_lshl_b32 s18, s98, 7
	s_add_u32 s15, s15, s18
	s_lshl_b32 s18, s101, 12
	s_add_u32 s15, s15, s18
	s_add_u32 s8, s24, s15
	s_addc_u32 s9, s25, 0
	s_mul_i32 s15, s98, 0x300000
	s_add_u32 s4, s26, 0x4800000
	s_addc_u32 s5, s27, 0
	s_add_u32 s4, s4, s15
	s_addc_u32 s5, s5, 0
	v_add_u32_e32 v201, s99, v197
	v_add_u32_e32 v203, s99, v198
	ds_read2_b32 v[160:161], v201 offset0:0 offset1:8
	ds_read2_b32 v[162:163], v201 offset0:16 offset1:24
	s_waitcnt lgkmcnt(0)
	v_mad_u32_u24 v160, v160, s100, v199
	v_mad_u32_u24 v161, v161, s100, v199
	v_mad_u32_u24 v162, v162, s100, v199
	v_mad_u32_u24 v163, v163, s100, v199
	global_load_dwordx4 v[64:67], v160, s[4:5]
	global_load_dwordx2 v[68:69], v160, s[4:5] offset:16
	global_load_dwordx4 v[70:73], v161, s[4:5]
	global_load_dwordx2 v[74:75], v161, s[4:5] offset:16
	global_load_dwordx4 v[76:79], v162, s[4:5]
	global_load_dwordx2 v[80:81], v162, s[4:5] offset:16
	global_load_dwordx4 v[82:85], v163, s[4:5]
	global_load_dwordx2 v[86:87], v163, s[4:5] offset:16
	ds_read2_b32 v[168:169], v201 offset0:32 offset1:40
	ds_read2_b32 v[170:171], v201 offset0:48 offset1:56
	s_waitcnt lgkmcnt(0)
	v_mad_u32_u24 v168, v168, s100, v199
	v_mad_u32_u24 v169, v169, s100, v199
	v_mad_u32_u24 v170, v170, s100, v199
	v_mad_u32_u24 v171, v171, s100, v199
	global_load_dwordx4 v[88:91], v168, s[4:5]
	global_load_dwordx2 v[92:93], v168, s[4:5] offset:16
	global_load_dwordx4 v[94:97], v169, s[4:5]
	global_load_dwordx2 v[98:99], v169, s[4:5] offset:16
	global_load_dwordx4 v[100:103], v170, s[4:5]
	global_load_dwordx2 v[104:105], v170, s[4:5] offset:16
	global_load_dwordx4 v[106:109], v171, s[4:5]
	global_load_dwordx2 v[110:111], v171, s[4:5] offset:16
	ds_read2_b32 v[160:161], v201 offset0:64 offset1:72
	ds_read2_b32 v[162:163], v201 offset0:80 offset1:88
	s_waitcnt lgkmcnt(0)
	v_mad_u32_u24 v160, v160, s100, v199
	v_mad_u32_u24 v161, v161, s100, v199
	v_mad_u32_u24 v162, v162, s100, v199
	v_mad_u32_u24 v163, v163, s100, v199
	global_load_dwordx4 v[112:115], v160, s[4:5]
	global_load_dwordx2 v[116:117], v160, s[4:5] offset:16
	global_load_dwordx4 v[118:121], v161, s[4:5]
	global_load_dwordx2 v[122:123], v161, s[4:5] offset:16
	global_load_dwordx4 v[124:127], v162, s[4:5]
	global_load_dwordx2 v[128:129], v162, s[4:5] offset:16
	global_load_dwordx4 v[130:133], v163, s[4:5]
	global_load_dwordx2 v[134:135], v163, s[4:5] offset:16
	ds_read2_b32 v[168:169], v201 offset0:96 offset1:104
	ds_read2_b32 v[170:171], v201 offset0:112 offset1:120
	s_waitcnt lgkmcnt(0)
	v_mad_u32_u24 v168, v168, s100, v199
	v_mad_u32_u24 v169, v169, s100, v199
	v_mad_u32_u24 v170, v170, s100, v199
	v_mad_u32_u24 v171, v171, s100, v199
	global_load_dwordx4 v[136:139], v168, s[4:5]
	global_load_dwordx2 v[140:141], v168, s[4:5] offset:16
	global_load_dwordx4 v[142:145], v169, s[4:5]
	global_load_dwordx2 v[146:147], v169, s[4:5] offset:16
	global_load_dwordx4 v[148:151], v170, s[4:5]
	global_load_dwordx2 v[152:153], v170, s[4:5] offset:16
	global_load_dwordx4 v[154:157], v171, s[4:5]
	global_load_dwordx2 v[158:159], v171, s[4:5] offset:16
	global_load_dword v209, v200, s[8:9]
	ds_read2_b32 v[176:177], v203 offset0:0 offset1:8
	ds_read2_b32 v[178:179], v203 offset0:16 offset1:24
	s_mov_b32 s18, 1
	s_and_b32 s19, s18, 15
	s_lshr_b32 s98, s18, 4
	s_lshl_b32 s99, s19, 9
	s_mul_i32 s15, s19, s16
	s_lshl_b32 s18, s98, 7
	s_add_u32 s15, s15, s18
	s_lshl_b32 s18, s101, 12
	s_add_u32 s15, s15, s18
	s_add_u32 s10, s24, s15
	s_addc_u32 s11, s25, 0
	s_mul_i32 s15, s98, 0x300000
	s_add_u32 s4, s26, 0x4800000
	s_addc_u32 s5, s27, 0
	s_add_u32 s4, s4, s15
	s_addc_u32 s5, s5, 0
	v_add_u32_e32 v202, s99, v197
	v_add_u32_e32 v204, s99, v198
	ds_read2_b32 v[160:161], v202 offset0:0 offset1:8
	ds_read2_b32 v[162:163], v202 offset0:16 offset1:24
	s_waitcnt lgkmcnt(0)
